# removed the back-to-back s_setprio 0 / s_setprio 1 pair in the middle of every 32-MFMA segment (36 pairs, all GEMM loops): two fewer issue slots between MFMAs, priority unchanged
# speedup vs baseline: 1.0015x; 1.0015x over previous
; #define PG8_STAGE(bufoff, gbase, voff) do { _Pragma("unroll") for (int _i = 0; _i < 2; ++_i) \
;         __builtin_amdgcn_global_load_lds((const unsigned*)((const char*)(gbase) + (voff)[_i]), (LAS unsigned*)(lds + (bufoff) + ldsw + _i * 8192), 16, 0, 0); } while (0)
; #define PG8_LDA(dst, b, h) do { _Pragma("unroll") for (int m = 0; m < 4; ++m) _Pragma("unroll") for (int k = 0; k < 2; ++k) dst[m][k] = *(const LAS bf16x8*)(lds + PG8_SA(b, h) + aoff + m * 2048 + k * 1024); } while (0)
; #define PG8_LDB(dst, b, h) do { _Pragma("unroll") for (int n = 0; n < 2; ++n) _Pragma("unroll") for (int k = 0; k < 2; ++k) dst[n][k] = *(const LAS bf16x8*)(lds + PG8_SB(b, h) + boff + n * 2048 + k * 1024); } while (0)
; #define PG8_MMA(ai, bj, At, Bt) do { __builtin_amdgcn_s_setprio(1); _Pragma("unroll") for (int m = 0; m < 4; ++m) _Pragma("unroll") for (int n = 0; n < 2; ++n) _Pragma("unroll") for (int k = 0; k < 2; ++k) \
;         acc[ai][bj][m][n] = __builtin_amdgcn_mfma_f32_16x16x32_bf16(Bt[n][k], At[m][k], acc[ai][bj][m][n], 0, 0, 0); __builtin_amdgcn_s_setprio(0); } while (0)
; #define PG8_WAIT_V(n) asm volatile("s_waitcnt vmcnt(" #n ")" ::: "memory")
; #define PG8_WAIT_L(n) asm volatile("s_waitcnt lgkmcnt(" #n ")" ::: "memory")
; #define PG8_BAR __builtin_amdgcn_s_barrier()
; #define PG8_SCHED __builtin_amdgcn_sched_barrier(0)
; template <class Epi, class Sched>
; __device__ __forceinline__ void gemm_phase(LAS unsigned char* lds, const Gemm g, const Sched& S, const Epi& E) {
;     ...
;         for (int t = 0; t < nt; t += 2) {
;             const bool last = (t == nt - 2);
;             const char* a1 = cA + (size_t)(t + 1) * kstep;
;             const char* a2 = last ? nA : cA + (size_t)(t + 2) * kstep; const char* b2 = last ? nB : cB + (size_t)(t + 2) * kstep;
;             const char* a3 = a2 + kstep; const char* b3 = b2 + kstep;
;             PG8_LDB(B0, 0, 0); PG8_LDB(B1, 0, 1); PG8_SCHED; PG8_LDA(At, 0, 0); PG8_STAGE(PG8_SA(1, 1), a1 + hstepA, voffA);
;             PG8_WAIT_V(8); PG8_WAIT_L(0); PG8_BAR; PG8_MMA(0, 0, At, B0); PG8_MMA(0, 1, At, B1); PG8_BAR; PG8_SCHED;
;             PG8_LDA(At, 0, 1); PG8_STAGE(PG8_SB(0, 0), b2, voffB); PG8_STAGE(PG8_SB(0, 1), b2 + hstepB, voffB); PG8_STAGE(PG8_SA(0, 0), a2, voffA);
;             PG8_WAIT_V(8); PG8_WAIT_L(0); PG8_BAR; PG8_MMA(1, 0, At, B0); PG8_MMA(1, 1, At, B1); PG8_BAR; PG8_SCHED;
.Ledge_p1:
.LBB0_148:
	ds_read_b128 v[154:157], v167
	ds_read_b128 v[158:161], v167 offset:1024
	ds_read_b128 v[170:173], v167 offset:2048
	ds_read_b128 v[174:177], v167 offset:3072
	ds_read_b128 v[178:181], v168
	ds_read_b128 v[182:185], v168 offset:1024
	ds_read_b128 v[186:189], v168 offset:2048
	ds_read_b128 v[190:193], v168 offset:3072
	s_add_u32 s48, vcc_lo, 0xfff80080
	s_addc_u32 s49, vcc_hi, -1
	s_cmp_eq_u32 s93, 28
	s_cselect_b32 s97, s2, s49
	s_cselect_b32 s96, s7, s48
	s_cselect_b32 s71, s9, s75
	s_cselect_b32 s70, s34, s35
	v_lshl_add_u64 v[162:163], vcc, 0, v[144:145]
	s_add_i32 m0, s88, 0xc000
	ds_read_b128 v[194:197], v169
	ds_read_b128 v[198:201], v169 offset:1024
	ds_read_b128 v[202:205], v169 offset:2048
	ds_read_b128 v[206:209], v169 offset:3072
	ds_read_b128 v[210:213], v169 offset:4096
	ds_read_b128 v[214:217], v169 offset:5120
	ds_read_b128 v[218:221], v169 offset:6144
	ds_read_b128 v[222:225], v169 offset:7168
	global_load_lds_dwordx4 v[162:163], off
	v_lshl_add_u64 v[162:163], vcc, 0, v[146:147]
	s_add_i32 m0, s88, 0xe000
	s_nop 0
	global_load_lds_dwordx4 v[162:163], off
	s_waitcnt vmcnt(8)
	s_waitcnt lgkmcnt(0)
	s_barrier
	s_setprio 1
	s_waitcnt lgkmcnt(0)
	v_mfma_f32_16x16x32_bf16 v[124:127], v[154:157], v[194:197], v[124:127]
	v_mfma_f32_16x16x32_bf16 v[120:123], v[170:173], v[194:197], v[120:123]
	v_mfma_f32_16x16x32_bf16 v[108:111], v[154:157], v[202:205], v[108:111]
	v_mfma_f32_16x16x32_bf16 v[104:107], v[170:173], v[202:205], v[104:107]
	v_mfma_f32_16x16x32_bf16 v[92:95], v[154:157], v[210:213], v[92:95]
	v_mfma_f32_16x16x32_bf16 v[88:91], v[170:173], v[210:213], v[88:91]
	v_mfma_f32_16x16x32_bf16 v[76:79], v[154:157], v[218:221], v[76:79]
	v_mfma_f32_16x16x32_bf16 v[72:75], v[170:173], v[218:221], v[72:75]
	v_mfma_f32_16x16x32_bf16 v[124:127], v[158:161], v[198:201], v[124:127]
	v_mfma_f32_16x16x32_bf16 v[120:123], v[174:177], v[198:201], v[120:123]
	v_mfma_f32_16x16x32_bf16 v[108:111], v[158:161], v[206:209], v[108:111]
	v_mfma_f32_16x16x32_bf16 v[104:107], v[174:177], v[206:209], v[104:107]
	v_mfma_f32_16x16x32_bf16 v[92:95], v[158:161], v[214:217], v[92:95]
	v_mfma_f32_16x16x32_bf16 v[88:91], v[174:177], v[214:217], v[88:91]
	v_mfma_f32_16x16x32_bf16 v[76:79], v[158:161], v[222:225], v[76:79]
	v_mfma_f32_16x16x32_bf16 v[72:75], v[174:177], v[222:225], v[72:75]
	v_mfma_f32_16x16x32_bf16 v[116:119], v[178:181], v[194:197], v[116:119]
	v_mfma_f32_16x16x32_bf16 v[112:115], v[186:189], v[194:197], v[112:115]
	v_mfma_f32_16x16x32_bf16 v[100:103], v[178:181], v[202:205], v[100:103]
	v_mfma_f32_16x16x32_bf16 v[96:99], v[186:189], v[202:205], v[96:99]
	v_mfma_f32_16x16x32_bf16 v[84:87], v[178:181], v[210:213], v[84:87]
	v_mfma_f32_16x16x32_bf16 v[80:83], v[186:189], v[210:213], v[80:83]
	v_mfma_f32_16x16x32_bf16 v[68:71], v[178:181], v[218:221], v[68:71]
	v_mfma_f32_16x16x32_bf16 v[64:67], v[186:189], v[218:221], v[64:67]
	v_mfma_f32_16x16x32_bf16 v[116:119], v[182:185], v[198:201], v[116:119]
	v_mfma_f32_16x16x32_bf16 v[112:115], v[190:193], v[198:201], v[112:115]
	v_mfma_f32_16x16x32_bf16 v[100:103], v[182:185], v[206:209], v[100:103]
	v_mfma_f32_16x16x32_bf16 v[96:99], v[190:193], v[206:209], v[96:99]
	v_mfma_f32_16x16x32_bf16 v[84:87], v[182:185], v[214:217], v[84:87]
	v_mfma_f32_16x16x32_bf16 v[80:83], v[190:193], v[214:217], v[80:83]
	v_mfma_f32_16x16x32_bf16 v[68:71], v[182:185], v[222:225], v[68:71]
	v_mfma_f32_16x16x32_bf16 v[64:67], v[190:193], v[222:225], v[64:67]
	s_setprio 0
	s_barrier
	s_add_i32 s48, s62, s33
	v_lshl_add_u64 v[162:163], s[70:71], 0, v[130:131]
	s_mov_b32 m0, s48
	ds_read_b128 v[194:197], v169 offset:16384
	ds_read_b128 v[198:201], v169 offset:17408
	ds_read_b128 v[202:205], v169 offset:18432
	ds_read_b128 v[206:209], v169 offset:19456
	ds_read_b128 v[210:213], v169 offset:20480
	ds_read_b128 v[214:217], v169 offset:21504
	ds_read_b128 v[218:221], v169 offset:22528
	ds_read_b128 v[222:225], v169 offset:23552
	global_load_lds_dwordx4 v[162:163], off
	s_add_i32 m0, s48, 0x2000
	s_add_u32 s48, s70, 0x80000
	v_lshl_add_u64 v[226:227], s[70:71], 0, v[134:135]
	s_addc_u32 s49, s71, 0
	s_add_i32 s95, s63, s33
	global_load_lds_dwordx4 v[226:227], off
	v_lshl_add_u64 v[228:229], s[48:49], 0, v[130:131]
	s_mov_b32 m0, s95
	v_lshl_add_u64 v[230:231], s[96:97], 0, v[132:133]
	global_load_lds_dwordx4 v[228:229], off
	v_lshl_add_u64 v[228:229], s[48:49], 0, v[134:135]
	s_add_i32 m0, s95, 0x2000
	s_nop 0
	global_load_lds_dwordx4 v[228:229], off
	v_lshl_add_u64 v[228:229], s[96:97], 0, v[128:129]
	s_mov_b32 m0, s88
	s_nop 0
	global_load_lds_dwordx4 v[228:229], off
	s_mov_b32 m0, s89
	s_nop 0
	global_load_lds_dwordx4 v[230:231], off
	s_waitcnt vmcnt(8)
	s_waitcnt lgkmcnt(0)
	s_barrier
; #define PG8_STAGE(bufoff, gbase, voff) do { _Pragma("unroll") for (int _i = 0; _i < 2; ++_i) \
;         __builtin_amdgcn_global_load_lds((const unsigned*)((const char*)(gbase) + (voff)[_i]), (LAS unsigned*)(lds + (bufoff) + ldsw + _i * 8192), 16, 0, 0); } while (0)
; #define PG8_LDA(dst, b, h) do { _Pragma("unroll") for (int m = 0; m < 4; ++m) _Pragma("unroll") for (int k = 0; k < 2; ++k) dst[m][k] = *(const LAS bf16x8*)(lds + PG8_SA(b, h) + aoff + m * 2048 + k * 1024); } while (0)
; #define PG8_LDB(dst, b, h) do { _Pragma("unroll") for (int n = 0; n < 2; ++n) _Pragma("unroll") for (int k = 0; k < 2; ++k) dst[n][k] = *(const LAS bf16x8*)(lds + PG8_SB(b, h) + boff + n * 2048 + k * 1024); } while (0)
; #define PG8_MMA(ai, bj, At, Bt) do { __builtin_amdgcn_s_setprio(1); _Pragma("unroll") for (int m = 0; m < 4; ++m) _Pragma("unroll") for (int n = 0; n < 2; ++n) _Pragma("unroll") for (int k = 0; k < 2; ++k) \
;         acc[ai][bj][m][n] = __builtin_amdgcn_mfma_f32_16x16x32_bf16(Bt[n][k], At[m][k], acc[ai][bj][m][n], 0, 0, 0); __builtin_amdgcn_s_setprio(0); } while (0)
; #define PG8_WAIT_V(n) asm volatile("s_waitcnt vmcnt(" #n ")" ::: "memory")
; #define PG8_WAIT_L(n) asm volatile("s_waitcnt lgkmcnt(" #n ")" ::: "memory")
; #define PG8_BAR __builtin_amdgcn_s_barrier()
; #define PG8_SCHED __builtin_amdgcn_sched_barrier(0)
; template <class Epi, class Sched>
; __device__ __forceinline__ void gemm_phase(LAS unsigned char* lds, const Gemm g, const Sched& S, const Epi& E) {
;     ...
;             PG8_WAIT_V(8); PG8_WAIT_L(0); PG8_BAR; PG8_MMA(1, 0, At, B0); PG8_MMA(1, 1, At, B1); PG8_BAR; PG8_SCHED;
;             PG8_LDB(B0, 1, 0); PG8_LDB(B1, 1, 1); PG8_SCHED; PG8_LDA(At, 1, 0); PG8_STAGE(PG8_SA(0, 1), a2 + hstepA, voffA);
;             PG8_WAIT_V(8); PG8_WAIT_L(0); PG8_BAR; PG8_MMA(0, 0, At, B0); PG8_MMA(0, 1, At, B1); PG8_BAR; PG8_SCHED;
	s_setprio 1
	s_waitcnt lgkmcnt(0)
	v_mfma_f32_16x16x32_bf16 v[60:63], v[154:157], v[194:197], v[60:63]
	v_mfma_f32_16x16x32_bf16 v[56:59], v[170:173], v[194:197], v[56:59]
	v_mfma_f32_16x16x32_bf16 v[44:47], v[154:157], v[202:205], v[44:47]
	v_mfma_f32_16x16x32_bf16 v[40:43], v[170:173], v[202:205], v[40:43]
	v_mfma_f32_16x16x32_bf16 v[28:31], v[154:157], v[210:213], v[28:31]
	v_mfma_f32_16x16x32_bf16 v[24:27], v[170:173], v[210:213], v[24:27]
	v_mfma_f32_16x16x32_bf16 v[12:15], v[154:157], v[218:221], v[12:15]
	v_mfma_f32_16x16x32_bf16 v[8:11], v[170:173], v[218:221], v[8:11]
	v_mfma_f32_16x16x32_bf16 v[60:63], v[158:161], v[198:201], v[60:63]
	v_mfma_f32_16x16x32_bf16 v[56:59], v[174:177], v[198:201], v[56:59]
	v_mfma_f32_16x16x32_bf16 v[44:47], v[158:161], v[206:209], v[44:47]
	v_mfma_f32_16x16x32_bf16 v[40:43], v[174:177], v[206:209], v[40:43]
	v_mfma_f32_16x16x32_bf16 v[28:31], v[158:161], v[214:217], v[28:31]
	v_mfma_f32_16x16x32_bf16 v[24:27], v[174:177], v[214:217], v[24:27]
	v_mfma_f32_16x16x32_bf16 v[12:15], v[158:161], v[222:225], v[12:15]
	v_mfma_f32_16x16x32_bf16 v[8:11], v[174:177], v[222:225], v[8:11]
	v_mfma_f32_16x16x32_bf16 v[52:55], v[178:181], v[194:197], v[52:55]
	v_mfma_f32_16x16x32_bf16 v[48:51], v[186:189], v[194:197], v[48:51]
	v_mfma_f32_16x16x32_bf16 v[36:39], v[178:181], v[202:205], v[36:39]
	v_mfma_f32_16x16x32_bf16 v[32:35], v[186:189], v[202:205], v[32:35]
	v_mfma_f32_16x16x32_bf16 v[20:23], v[178:181], v[210:213], v[20:23]
	v_mfma_f32_16x16x32_bf16 v[16:19], v[186:189], v[210:213], v[16:19]
	v_mfma_f32_16x16x32_bf16 v[4:7], v[178:181], v[218:221], v[4:7]
	v_mfma_f32_16x16x32_bf16 v[0:3], v[186:189], v[218:221], v[0:3]
	v_mfma_f32_16x16x32_bf16 v[52:55], v[182:185], v[198:201], v[52:55]
	v_mfma_f32_16x16x32_bf16 v[48:51], v[190:193], v[198:201], v[48:51]
	v_mfma_f32_16x16x32_bf16 v[36:39], v[182:185], v[206:209], v[36:39]
	v_mfma_f32_16x16x32_bf16 v[32:35], v[190:193], v[206:209], v[32:35]
	v_mfma_f32_16x16x32_bf16 v[20:23], v[182:185], v[214:217], v[20:23]
	v_mfma_f32_16x16x32_bf16 v[16:19], v[190:193], v[214:217], v[16:19]
	v_mfma_f32_16x16x32_bf16 v[4:7], v[182:185], v[222:225], v[4:7]
	v_mfma_f32_16x16x32_bf16 v[0:3], v[190:193], v[222:225], v[0:3]
	s_setprio 0
	s_barrier
	s_add_i32 s95, 0, 0x18000
	v_add_u32_e32 v138, s95, v141
	s_add_i32 s78, 0, 0x1c000
	ds_read_b128 v[154:157], v138
	ds_read_b128 v[158:161], v138 offset:1024
	ds_read_b128 v[170:173], v138 offset:2048
	ds_read_b128 v[174:177], v138 offset:3072
	v_add_u32_e32 v138, s78, v141
	ds_read_b128 v[178:181], v138
	ds_read_b128 v[182:185], v138 offset:1024
	ds_read_b128 v[186:189], v138 offset:2048
	ds_read_b128 v[190:193], v138 offset:3072
	s_add_u32 s48, s96, 0x80000
	s_addc_u32 s49, s97, 0
	s_mov_b32 m0, s60
	v_lshl_add_u64 v[232:233], s[48:49], 0, v[128:129]
	ds_read_b128 v[194:197], v169 offset:32768
	ds_read_b128 v[198:201], v169 offset:33792
	ds_read_b128 v[202:205], v169 offset:34816
	ds_read_b128 v[206:209], v169 offset:35840
	ds_read_b128 v[210:213], v169 offset:36864
	ds_read_b128 v[214:217], v169 offset:37888
	ds_read_b128 v[218:221], v169 offset:38912
	ds_read_b128 v[222:225], v169 offset:39936
	global_load_lds_dwordx4 v[232:233], off
	v_lshl_add_u64 v[232:233], s[48:49], 0, v[132:133]
	s_mov_b32 m0, s61
	s_nop 0
	global_load_lds_dwordx4 v[232:233], off
	s_waitcnt vmcnt(8)
	s_waitcnt lgkmcnt(0)
	s_barrier
	s_setprio 1
	s_waitcnt lgkmcnt(0)
	v_mfma_f32_16x16x32_bf16 v[124:127], v[154:157], v[194:197], v[124:127]
	v_mfma_f32_16x16x32_bf16 v[120:123], v[170:173], v[194:197], v[120:123]
	v_mfma_f32_16x16x32_bf16 v[108:111], v[154:157], v[202:205], v[108:111]
	v_mfma_f32_16x16x32_bf16 v[104:107], v[170:173], v[202:205], v[104:107]
	v_mfma_f32_16x16x32_bf16 v[92:95], v[154:157], v[210:213], v[92:95]
	v_mfma_f32_16x16x32_bf16 v[88:91], v[170:173], v[210:213], v[88:91]
	v_mfma_f32_16x16x32_bf16 v[76:79], v[154:157], v[218:221], v[76:79]
	v_mfma_f32_16x16x32_bf16 v[72:75], v[170:173], v[218:221], v[72:75]
	v_mfma_f32_16x16x32_bf16 v[124:127], v[158:161], v[198:201], v[124:127]
	v_mfma_f32_16x16x32_bf16 v[120:123], v[174:177], v[198:201], v[120:123]
	v_mfma_f32_16x16x32_bf16 v[108:111], v[158:161], v[206:209], v[108:111]
	v_mfma_f32_16x16x32_bf16 v[104:107], v[174:177], v[206:209], v[104:107]
	v_mfma_f32_16x16x32_bf16 v[92:95], v[158:161], v[214:217], v[92:95]
	v_mfma_f32_16x16x32_bf16 v[88:91], v[174:177], v[214:217], v[88:91]
	v_mfma_f32_16x16x32_bf16 v[76:79], v[158:161], v[222:225], v[76:79]
	v_mfma_f32_16x16x32_bf16 v[72:75], v[174:177], v[222:225], v[72:75]
	v_mfma_f32_16x16x32_bf16 v[116:119], v[178:181], v[194:197], v[116:119]
	v_mfma_f32_16x16x32_bf16 v[112:115], v[186:189], v[194:197], v[112:115]
	v_mfma_f32_16x16x32_bf16 v[100:103], v[178:181], v[202:205], v[100:103]
	v_mfma_f32_16x16x32_bf16 v[96:99], v[186:189], v[202:205], v[96:99]
	v_mfma_f32_16x16x32_bf16 v[84:87], v[178:181], v[210:213], v[84:87]
	v_mfma_f32_16x16x32_bf16 v[80:83], v[186:189], v[210:213], v[80:83]
	v_mfma_f32_16x16x32_bf16 v[68:71], v[178:181], v[218:221], v[68:71]
	v_mfma_f32_16x16x32_bf16 v[64:67], v[186:189], v[218:221], v[64:67]
	v_mfma_f32_16x16x32_bf16 v[116:119], v[182:185], v[198:201], v[116:119]
	v_mfma_f32_16x16x32_bf16 v[112:115], v[190:193], v[198:201], v[112:115]
	v_mfma_f32_16x16x32_bf16 v[100:103], v[182:185], v[206:209], v[100:103]
	v_mfma_f32_16x16x32_bf16 v[96:99], v[190:193], v[206:209], v[96:99]
	v_mfma_f32_16x16x32_bf16 v[84:87], v[182:185], v[214:217], v[84:87]
	v_mfma_f32_16x16x32_bf16 v[80:83], v[190:193], v[214:217], v[80:83]
	v_mfma_f32_16x16x32_bf16 v[68:71], v[182:185], v[222:225], v[68:71]
	v_mfma_f32_16x16x32_bf16 v[64:67], v[190:193], v[222:225], v[64:67]
	s_setprio 0
	s_barrier
; #define PG8_STAGE(bufoff, gbase, voff) do { _Pragma("unroll") for (int _i = 0; _i < 2; ++_i) \
;         __builtin_amdgcn_global_load_lds((const unsigned*)((const char*)(gbase) + (voff)[_i]), (LAS unsigned*)(lds + (bufoff) + ldsw + _i * 8192), 16, 0, 0); } while (0)
; #define PG8_LDA(dst, b, h) do { _Pragma("unroll") for (int m = 0; m < 4; ++m) _Pragma("unroll") for (int k = 0; k < 2; ++k) dst[m][k] = *(const LAS bf16x8*)(lds + PG8_SA(b, h) + aoff + m * 2048 + k * 1024); } while (0)
; #define PG8_MMA(ai, bj, At, Bt) do { __builtin_amdgcn_s_setprio(1); _Pragma("unroll") for (int m = 0; m < 4; ++m) _Pragma("unroll") for (int n = 0; n < 2; ++n) _Pragma("unroll") for (int k = 0; k < 2; ++k) \
;         acc[ai][bj][m][n] = __builtin_amdgcn_mfma_f32_16x16x32_bf16(Bt[n][k], At[m][k], acc[ai][bj][m][n], 0, 0, 0); __builtin_amdgcn_s_setprio(0); } while (0)
; #define PG8_WAIT_V(n) asm volatile("s_waitcnt vmcnt(" #n ")" ::: "memory")
; #define PG8_WAIT_L(n) asm volatile("s_waitcnt lgkmcnt(" #n ")" ::: "memory")
; #define PG8_BAR __builtin_amdgcn_s_barrier()
; #define PG8_SCHED __builtin_amdgcn_sched_barrier(0)
; template <class Epi, class Sched>
; __device__ __forceinline__ void gemm_phase(LAS unsigned char* lds, const Gemm g, const Sched& S, const Epi& E) {
;     ...
;             PG8_LDA(At, 1, 1); PG8_STAGE(PG8_SB(1, 0), b3, voffB); PG8_STAGE(PG8_SB(1, 1), b3 + hstepB, voffB); PG8_STAGE(PG8_SA(1, 0), a3, voffA);
;             PG8_WAIT_V(8); PG8_WAIT_L(0); PG8_BAR; PG8_MMA(1, 0, At, B0); PG8_MMA(1, 1, At, B1); PG8_BAR; PG8_SCHED;
;         }
;         if (wr == 0) PG8_BAR;
	s_add_i32 s48, s95, s33
	v_lshl_add_u64 v[162:163], v[162:163], 0, s[84:85]
	s_mov_b32 m0, s48
	ds_read_b128 v[194:197], v169 offset:49152
	ds_read_b128 v[198:201], v169 offset:50176
	ds_read_b128 v[202:205], v169 offset:51200
	ds_read_b128 v[206:209], v169 offset:52224
	ds_read_b128 v[210:213], v169 offset:53248
	ds_read_b128 v[214:217], v169 offset:54272
	ds_read_b128 v[218:221], v169 offset:55296
	ds_read_b128 v[222:225], v169 offset:56320
	global_load_lds_dwordx4 v[162:163], off
	s_add_i32 m0, s48, 0x2000
	s_add_u32 s48, s70, 0x80080
	v_lshl_add_u64 v[162:163], v[226:227], 0, s[84:85]
	s_addc_u32 s49, s71, 0
	s_add_i32 s70, s78, s33
	global_load_lds_dwordx4 v[162:163], off
	v_lshl_add_u64 v[162:163], s[48:49], 0, v[130:131]
	s_mov_b32 m0, s70
	s_nop 0
	global_load_lds_dwordx4 v[162:163], off
	v_lshl_add_u64 v[162:163], s[48:49], 0, v[134:135]
	s_add_i32 m0, s70, 0x2000
	s_nop 0
	global_load_lds_dwordx4 v[162:163], off
	v_lshl_add_u64 v[162:163], v[228:229], 0, s[84:85]
	s_mov_b32 m0, s90
	s_nop 0
	global_load_lds_dwordx4 v[162:163], off
	v_lshl_add_u64 v[162:163], v[230:231], 0, s[84:85]
	s_mov_b32 m0, s91
	s_nop 0
	global_load_lds_dwordx4 v[162:163], off
	s_waitcnt vmcnt(8)
	s_waitcnt lgkmcnt(0)
	s_barrier
	s_setprio 1
	s_waitcnt lgkmcnt(0)
	v_mfma_f32_16x16x32_bf16 v[60:63], v[154:157], v[194:197], v[60:63]
	v_mfma_f32_16x16x32_bf16 v[56:59], v[170:173], v[194:197], v[56:59]
	v_mfma_f32_16x16x32_bf16 v[44:47], v[154:157], v[202:205], v[44:47]
	v_mfma_f32_16x16x32_bf16 v[40:43], v[170:173], v[202:205], v[40:43]
	v_mfma_f32_16x16x32_bf16 v[28:31], v[154:157], v[210:213], v[28:31]
	v_mfma_f32_16x16x32_bf16 v[24:27], v[170:173], v[210:213], v[24:27]
	v_mfma_f32_16x16x32_bf16 v[12:15], v[154:157], v[218:221], v[12:15]
	v_mfma_f32_16x16x32_bf16 v[8:11], v[170:173], v[218:221], v[8:11]
	v_mfma_f32_16x16x32_bf16 v[60:63], v[158:161], v[198:201], v[60:63]
	v_mfma_f32_16x16x32_bf16 v[56:59], v[174:177], v[198:201], v[56:59]
	v_mfma_f32_16x16x32_bf16 v[44:47], v[158:161], v[206:209], v[44:47]
	v_mfma_f32_16x16x32_bf16 v[40:43], v[174:177], v[206:209], v[40:43]
	v_mfma_f32_16x16x32_bf16 v[28:31], v[158:161], v[214:217], v[28:31]
	v_mfma_f32_16x16x32_bf16 v[24:27], v[174:177], v[214:217], v[24:27]
	v_mfma_f32_16x16x32_bf16 v[12:15], v[158:161], v[222:225], v[12:15]
	v_mfma_f32_16x16x32_bf16 v[8:11], v[174:177], v[222:225], v[8:11]
	v_mfma_f32_16x16x32_bf16 v[52:55], v[178:181], v[194:197], v[52:55]
	v_mfma_f32_16x16x32_bf16 v[48:51], v[186:189], v[194:197], v[48:51]
	v_mfma_f32_16x16x32_bf16 v[36:39], v[178:181], v[202:205], v[36:39]
	v_mfma_f32_16x16x32_bf16 v[32:35], v[186:189], v[202:205], v[32:35]
	v_mfma_f32_16x16x32_bf16 v[20:23], v[178:181], v[210:213], v[20:23]
	v_mfma_f32_16x16x32_bf16 v[16:19], v[186:189], v[210:213], v[16:19]
	v_mfma_f32_16x16x32_bf16 v[4:7], v[178:181], v[218:221], v[4:7]
	v_mfma_f32_16x16x32_bf16 v[0:3], v[186:189], v[218:221], v[0:3]
	v_mfma_f32_16x16x32_bf16 v[52:55], v[182:185], v[198:201], v[52:55]
	v_mfma_f32_16x16x32_bf16 v[48:51], v[190:193], v[198:201], v[48:51]
	v_mfma_f32_16x16x32_bf16 v[36:39], v[182:185], v[206:209], v[36:39]
	v_mfma_f32_16x16x32_bf16 v[32:35], v[190:193], v[206:209], v[32:35]
	v_mfma_f32_16x16x32_bf16 v[20:23], v[182:185], v[214:217], v[20:23]
	v_mfma_f32_16x16x32_bf16 v[16:19], v[190:193], v[214:217], v[16:19]
	v_mfma_f32_16x16x32_bf16 v[4:7], v[182:185], v[222:225], v[4:7]
	v_mfma_f32_16x16x32_bf16 v[0:3], v[190:193], v[222:225], v[0:3]
	s_setprio 0
	s_barrier
	s_add_i32 s93, s93, 2
	s_add_u32 vcc_lo, vcc_lo, 0x100
	s_addc_u32 vcc_hi, vcc_hi, 0
	s_add_u32 s35, s35, 0x100
	s_addc_u32 s75, s75, 0
	s_cmp_gt_u32 s93, 29
	s_cbranch_scc0 .LBB0_148
	s_and_b64 vcc, exec, s[86:87]
	s_cbranch_vccz .LBB0_151
	s_barrier

; #define PG8_STAGE(bufoff, gbase, voff) do { _Pragma("unroll") for (int _i = 0; _i < 2; ++_i) \
;         __builtin_amdgcn_global_load_lds((const unsigned*)((const char*)(gbase) + (voff)[_i]), (LAS unsigned*)(lds + (bufoff) + ldsw + _i * 8192), 16, 0, 0); } while (0)
; #define PG8_LDA(dst, b, h) do { _Pragma("unroll") for (int m = 0; m < 4; ++m) _Pragma("unroll") for (int k = 0; k < 2; ++k) dst[m][k] = *(const LAS bf16x8*)(lds + PG8_SA(b, h) + aoff + m * 2048 + k * 1024); } while (0)
; #define PG8_LDB(dst, b, h) do { _Pragma("unroll") for (int n = 0; n < 2; ++n) _Pragma("unroll") for (int k = 0; k < 2; ++k) dst[n][k] = *(const LAS bf16x8*)(lds + PG8_SB(b, h) + boff + n * 2048 + k * 1024); } while (0)
; #define PG8_MMA(ai, bj, At, Bt) do { __builtin_amdgcn_s_setprio(1); _Pragma("unroll") for (int m = 0; m < 4; ++m) _Pragma("unroll") for (int n = 0; n < 2; ++n) _Pragma("unroll") for (int k = 0; k < 2; ++k) \
;         acc[ai][bj][m][n] = __builtin_amdgcn_mfma_f32_16x16x32_bf16(Bt[n][k], At[m][k], acc[ai][bj][m][n], 0, 0, 0); __builtin_amdgcn_s_setprio(0); } while (0)
; #define PG8_WAIT_V(n) asm volatile("s_waitcnt vmcnt(" #n ")" ::: "memory")
; #define PG8_WAIT_L(n) asm volatile("s_waitcnt lgkmcnt(" #n ")" ::: "memory")
; #define PG8_BAR __builtin_amdgcn_s_barrier()
; #define PG8_SCHED __builtin_amdgcn_sched_barrier(0)
; template <class Epi, class Sched>
; __device__ __forceinline__ void gemm_phase(LAS unsigned char* lds, const Gemm g, const Sched& S, const Epi& E) {
;     ...
;             PG8_LDB(B0, 0, 0); PG8_LDB(B1, 0, 1); PG8_SCHED; PG8_LDA(At, 0, 0); PG8_STAGE(PG8_SA(1, 1), a1 + hstepA, voffA);
;             PG8_WAIT_V(8); PG8_WAIT_L(0); PG8_BAR; PG8_MMA(0, 0, At, B0); PG8_MMA(0, 1, At, B1); PG8_BAR; PG8_SCHED;
;             PG8_LDA(At, 0, 1); PG8_STAGE(PG8_SB(0, 0), b2, voffB); PG8_STAGE(PG8_SB(0, 1), b2 + hstepB, voffB); PG8_STAGE(PG8_SA(0, 0), a2, voffA);
;             PG8_WAIT_V(8); PG8_WAIT_L(0); PG8_BAR; PG8_MMA(1, 0, At, B0); PG8_MMA(1, 1, At, B1); PG8_BAR; PG8_SCHED;
.LBB0_336:
	ds_read_b128 v[86:89], v83
	ds_read_b128 v[90:93], v83 offset:1024
	ds_read_b128 v[94:97], v83 offset:2048
	ds_read_b128 v[98:101], v83 offset:3072
	s_add_u32 s48, s70, 0xfffb8080
	s_addc_u32 s49, s71, -1
	s_cmp_eq_u32 vcc_lo, 12
	s_cselect_b32 s83, s73, s49
	s_cselect_b32 s82, s72, s48
	s_cselect_b32 s77, s35, s97
	s_cselect_b32 s76, s61, s67
	s_mov_b32 m0, s92
	v_lshl_add_u64 v[80:81], s[70:71], 0, v[76:77]
	ds_read_b128 v[102:105], v84
	ds_read_b128 v[106:109], v84 offset:1024
	ds_read_b128 v[110:113], v84 offset:2048
	ds_read_b128 v[114:117], v84 offset:3072
	ds_read_b128 v[118:121], v84 offset:4096
	ds_read_b128 v[122:125], v84 offset:5120
	ds_read_b128 v[126:129], v84 offset:6144
	ds_read_b128 v[130:133], v84 offset:7168
	global_load_lds_dwordx4 v[80:81], off
	v_lshl_add_u64 v[80:81], s[70:71], 0, v[78:79]
	s_mov_b32 m0, s93
	s_nop 0
	global_load_lds_dwordx4 v[80:81], off
	s_waitcnt vmcnt(8)
	s_waitcnt lgkmcnt(0)
	s_barrier
	s_setprio 1
	s_waitcnt lgkmcnt(0)
	v_mfma_f32_16x16x32_bf16 v[60:63], v[86:89], v[102:105], v[60:63]
	v_mfma_f32_16x16x32_bf16 v[56:59], v[94:97], v[102:105], v[56:59]
	v_mfma_f32_16x16x32_bf16 v[52:55], v[86:89], v[110:113], v[52:55]
	v_mfma_f32_16x16x32_bf16 v[48:51], v[94:97], v[110:113], v[48:51]
	v_mfma_f32_16x16x32_bf16 v[44:47], v[86:89], v[118:121], v[44:47]
	v_mfma_f32_16x16x32_bf16 v[40:43], v[94:97], v[118:121], v[40:43]
	v_mfma_f32_16x16x32_bf16 v[36:39], v[86:89], v[126:129], v[36:39]
	v_mfma_f32_16x16x32_bf16 v[32:35], v[94:97], v[126:129], v[32:35]
	v_mfma_f32_16x16x32_bf16 v[60:63], v[90:93], v[106:109], v[60:63]
	v_mfma_f32_16x16x32_bf16 v[56:59], v[98:101], v[106:109], v[56:59]
	v_mfma_f32_16x16x32_bf16 v[52:55], v[90:93], v[114:117], v[52:55]
	v_mfma_f32_16x16x32_bf16 v[48:51], v[98:101], v[114:117], v[48:51]
	v_mfma_f32_16x16x32_bf16 v[44:47], v[90:93], v[122:125], v[44:47]
	v_mfma_f32_16x16x32_bf16 v[40:43], v[98:101], v[122:125], v[40:43]
	v_mfma_f32_16x16x32_bf16 v[36:39], v[90:93], v[130:133], v[36:39]
	v_mfma_f32_16x16x32_bf16 v[32:35], v[98:101], v[130:133], v[32:35]
	s_setprio 0
	s_barrier
	s_mov_b32 m0, s94
	v_lshl_add_u64 v[80:81], s[76:77], 0, v[66:67]
	s_add_u32 s48, s76, 0x40000
	ds_read_b128 v[102:105], v84 offset:16384
	ds_read_b128 v[106:109], v84 offset:17408
	ds_read_b128 v[110:113], v84 offset:18432
	ds_read_b128 v[114:117], v84 offset:19456
	ds_read_b128 v[118:121], v84 offset:20480
	ds_read_b128 v[122:125], v84 offset:21504
	ds_read_b128 v[126:129], v84 offset:22528
	ds_read_b128 v[130:133], v84 offset:23552
	global_load_lds_dwordx4 v[80:81], off
	v_lshl_add_u64 v[134:135], s[76:77], 0, v[70:71]
	s_mov_b32 m0, s95
	s_addc_u32 s49, s77, 0
	global_load_lds_dwordx4 v[134:135], off
	v_lshl_add_u64 v[138:139], s[48:49], 0, v[66:67]
	s_mov_b32 m0, s46
	v_lshl_add_u64 v[140:141], s[82:83], 0, v[68:69]
	global_load_lds_dwordx4 v[138:139], off
	v_lshl_add_u64 v[138:139], s[48:49], 0, v[70:71]
	s_mov_b32 m0, s47
	s_nop 0
	global_load_lds_dwordx4 v[138:139], off
	v_lshl_add_u64 v[138:139], s[82:83], 0, v[64:65]
	s_mov_b32 m0, s33
	s_nop 0
	global_load_lds_dwordx4 v[138:139], off
	s_mov_b32 m0, s75
	s_nop 0
	global_load_lds_dwordx4 v[140:141], off
	s_waitcnt vmcnt(8)
	s_waitcnt lgkmcnt(0)
	s_barrier
	s_setprio 1
	s_waitcnt lgkmcnt(0)
	v_mfma_f32_16x16x32_bf16 v[28:31], v[86:89], v[102:105], v[28:31]
	v_mfma_f32_16x16x32_bf16 v[24:27], v[94:97], v[102:105], v[24:27]
	v_mfma_f32_16x16x32_bf16 v[20:23], v[86:89], v[110:113], v[20:23]
	v_mfma_f32_16x16x32_bf16 v[16:19], v[94:97], v[110:113], v[16:19]
	v_mfma_f32_16x16x32_bf16 v[12:15], v[86:89], v[118:121], v[12:15]
	v_mfma_f32_16x16x32_bf16 v[8:11], v[94:97], v[118:121], v[8:11]
	v_mfma_f32_16x16x32_bf16 v[4:7], v[86:89], v[126:129], v[4:7]
	v_mfma_f32_16x16x32_bf16 v[0:3], v[94:97], v[126:129], v[0:3]
	v_mfma_f32_16x16x32_bf16 v[28:31], v[90:93], v[106:109], v[28:31]
	v_mfma_f32_16x16x32_bf16 v[24:27], v[98:101], v[106:109], v[24:27]
	v_mfma_f32_16x16x32_bf16 v[20:23], v[90:93], v[114:117], v[20:23]
	v_mfma_f32_16x16x32_bf16 v[16:19], v[98:101], v[114:117], v[16:19]
	v_mfma_f32_16x16x32_bf16 v[12:15], v[90:93], v[122:125], v[12:15]
	v_mfma_f32_16x16x32_bf16 v[8:11], v[98:101], v[122:125], v[8:11]
	v_mfma_f32_16x16x32_bf16 v[4:7], v[90:93], v[130:133], v[4:7]
	v_mfma_f32_16x16x32_bf16 v[0:3], v[98:101], v[130:133], v[0:3]
	s_setprio 0
	s_barrier
; #define PG8_STAGE(bufoff, gbase, voff) do { _Pragma("unroll") for (int _i = 0; _i < 2; ++_i) \
;         __builtin_amdgcn_global_load_lds((const unsigned*)((const char*)(gbase) + (voff)[_i]), (LAS unsigned*)(lds + (bufoff) + ldsw + _i * 8192), 16, 0, 0); } while (0)
; #define PG8_LDA(dst, b, h) do { _Pragma("unroll") for (int m = 0; m < 4; ++m) _Pragma("unroll") for (int k = 0; k < 2; ++k) dst[m][k] = *(const LAS bf16x8*)(lds + PG8_SA(b, h) + aoff + m * 2048 + k * 1024); } while (0)
; #define PG8_LDB(dst, b, h) do { _Pragma("unroll") for (int n = 0; n < 2; ++n) _Pragma("unroll") for (int k = 0; k < 2; ++k) dst[n][k] = *(const LAS bf16x8*)(lds + PG8_SB(b, h) + boff + n * 2048 + k * 1024); } while (0)
; #define PG8_MMA(ai, bj, At, Bt) do { __builtin_amdgcn_s_setprio(1); _Pragma("unroll") for (int m = 0; m < 4; ++m) _Pragma("unroll") for (int n = 0; n < 2; ++n) _Pragma("unroll") for (int k = 0; k < 2; ++k) \
;         acc[ai][bj][m][n] = __builtin_amdgcn_mfma_f32_16x16x32_bf16(Bt[n][k], At[m][k], acc[ai][bj][m][n], 0, 0, 0); __builtin_amdgcn_s_setprio(0); } while (0)
; #define PG8_WAIT_V(n) asm volatile("s_waitcnt vmcnt(" #n ")" ::: "memory")
; #define PG8_WAIT_L(n) asm volatile("s_waitcnt lgkmcnt(" #n ")" ::: "memory")
; #define PG8_BAR __builtin_amdgcn_s_barrier()
; #define PG8_SCHED __builtin_amdgcn_sched_barrier(0)
; template <class Epi, class Sched>
; __device__ __forceinline__ void gemm_phase(LAS unsigned char* lds, const Gemm g, const Sched& S, const Epi& E) {
;     ...
;             PG8_LDB(B0, 1, 0); PG8_LDB(B1, 1, 1); PG8_SCHED; PG8_LDA(At, 1, 0); PG8_STAGE(PG8_SA(0, 1), a2 + hstepA, voffA);
;             PG8_WAIT_V(8); PG8_WAIT_L(0); PG8_BAR; PG8_MMA(0, 0, At, B0); PG8_MMA(0, 1, At, B1); PG8_BAR; PG8_SCHED;
;             PG8_LDA(At, 1, 1); PG8_STAGE(PG8_SB(1, 0), b3, voffB); PG8_STAGE(PG8_SB(1, 1), b3 + hstepB, voffB); PG8_STAGE(PG8_SA(1, 0), a3, voffA);
;             PG8_WAIT_V(8); PG8_WAIT_L(0); PG8_BAR; PG8_MMA(1, 0, At, B0); PG8_MMA(1, 1, At, B1); PG8_BAR; PG8_SCHED;
;         }
;         if (wr == 0) PG8_BAR;
	s_add_i32 s78, 0, 0x18000
	v_add_u32_e32 v85, s78, v82
	ds_read_b128 v[86:89], v85
	ds_read_b128 v[90:93], v85 offset:1024
	ds_read_b128 v[94:97], v85 offset:2048
	ds_read_b128 v[98:101], v85 offset:3072
	s_add_u32 s48, s82, 0x48000
	s_addc_u32 s49, s83, 0
	s_mov_b32 m0, s84
	v_lshl_add_u64 v[142:143], s[48:49], 0, v[64:65]
	ds_read_b128 v[102:105], v84 offset:32768
	ds_read_b128 v[106:109], v84 offset:33792
	ds_read_b128 v[110:113], v84 offset:34816
	ds_read_b128 v[114:117], v84 offset:35840
	ds_read_b128 v[118:121], v84 offset:36864
	ds_read_b128 v[122:125], v84 offset:37888
	ds_read_b128 v[126:129], v84 offset:38912
	ds_read_b128 v[130:133], v84 offset:39936
	global_load_lds_dwordx4 v[142:143], off
	v_lshl_add_u64 v[142:143], s[48:49], 0, v[68:69]
	s_mov_b32 m0, s85
	s_nop 0
	global_load_lds_dwordx4 v[142:143], off
	s_waitcnt vmcnt(8)
	s_waitcnt lgkmcnt(0)
	s_barrier
	s_setprio 1
	s_waitcnt lgkmcnt(0)
	v_mfma_f32_16x16x32_bf16 v[60:63], v[86:89], v[102:105], v[60:63]
	v_mfma_f32_16x16x32_bf16 v[56:59], v[94:97], v[102:105], v[56:59]
	v_mfma_f32_16x16x32_bf16 v[52:55], v[86:89], v[110:113], v[52:55]
	v_mfma_f32_16x16x32_bf16 v[48:51], v[94:97], v[110:113], v[48:51]
	v_mfma_f32_16x16x32_bf16 v[44:47], v[86:89], v[118:121], v[44:47]
	v_mfma_f32_16x16x32_bf16 v[40:43], v[94:97], v[118:121], v[40:43]
	v_mfma_f32_16x16x32_bf16 v[36:39], v[86:89], v[126:129], v[36:39]
	v_mfma_f32_16x16x32_bf16 v[32:35], v[94:97], v[126:129], v[32:35]
	v_mfma_f32_16x16x32_bf16 v[60:63], v[90:93], v[106:109], v[60:63]
	v_mfma_f32_16x16x32_bf16 v[56:59], v[98:101], v[106:109], v[56:59]
	v_mfma_f32_16x16x32_bf16 v[52:55], v[90:93], v[114:117], v[52:55]
	v_mfma_f32_16x16x32_bf16 v[48:51], v[98:101], v[114:117], v[48:51]
	v_mfma_f32_16x16x32_bf16 v[44:47], v[90:93], v[122:125], v[44:47]
	v_mfma_f32_16x16x32_bf16 v[40:43], v[98:101], v[122:125], v[40:43]
	v_mfma_f32_16x16x32_bf16 v[36:39], v[90:93], v[130:133], v[36:39]
	v_mfma_f32_16x16x32_bf16 v[32:35], v[98:101], v[130:133], v[32:35]
	s_setprio 0
	s_barrier
	s_add_i32 s48, s78, s5
	v_lshl_add_u64 v[80:81], v[80:81], 0, s[24:25]
	s_mov_b32 m0, s48
	ds_read_b128 v[102:105], v84 offset:49152
	ds_read_b128 v[106:109], v84 offset:50176
	ds_read_b128 v[110:113], v84 offset:51200
	ds_read_b128 v[114:117], v84 offset:52224
	ds_read_b128 v[118:121], v84 offset:53248
	ds_read_b128 v[122:125], v84 offset:54272
	ds_read_b128 v[126:129], v84 offset:55296
	ds_read_b128 v[130:133], v84 offset:56320
	global_load_lds_dwordx4 v[80:81], off
	s_add_i32 m0, s48, 0x2000
	s_add_u32 s48, s76, 0x40080
	v_lshl_add_u64 v[80:81], v[134:135], 0, s[24:25]
	s_addc_u32 s49, s77, 0
	global_load_lds_dwordx4 v[80:81], off
	v_lshl_add_u64 v[80:81], s[48:49], 0, v[66:67]
	s_mov_b32 m0, s89
	s_nop 0
	global_load_lds_dwordx4 v[80:81], off
	v_lshl_add_u64 v[80:81], s[48:49], 0, v[70:71]
	s_mov_b32 m0, s90
	s_nop 0
	global_load_lds_dwordx4 v[80:81], off
	v_lshl_add_u64 v[80:81], v[138:139], 0, s[24:25]
	s_mov_b32 m0, s87
	s_nop 0
	global_load_lds_dwordx4 v[80:81], off
	v_lshl_add_u64 v[80:81], v[140:141], 0, s[24:25]
	s_mov_b32 m0, s88
	s_nop 0
	global_load_lds_dwordx4 v[80:81], off
	s_waitcnt vmcnt(8)
	s_waitcnt lgkmcnt(0)
	s_barrier
	s_setprio 1
	s_waitcnt lgkmcnt(0)
	v_mfma_f32_16x16x32_bf16 v[28:31], v[86:89], v[102:105], v[28:31]
	v_mfma_f32_16x16x32_bf16 v[24:27], v[94:97], v[102:105], v[24:27]
	v_mfma_f32_16x16x32_bf16 v[20:23], v[86:89], v[110:113], v[20:23]
	v_mfma_f32_16x16x32_bf16 v[16:19], v[94:97], v[110:113], v[16:19]
	v_mfma_f32_16x16x32_bf16 v[12:15], v[86:89], v[118:121], v[12:15]
	v_mfma_f32_16x16x32_bf16 v[8:11], v[94:97], v[118:121], v[8:11]
	v_mfma_f32_16x16x32_bf16 v[4:7], v[86:89], v[126:129], v[4:7]
	v_mfma_f32_16x16x32_bf16 v[0:3], v[94:97], v[126:129], v[0:3]
	v_mfma_f32_16x16x32_bf16 v[28:31], v[90:93], v[106:109], v[28:31]
	v_mfma_f32_16x16x32_bf16 v[24:27], v[98:101], v[106:109], v[24:27]
	v_mfma_f32_16x16x32_bf16 v[20:23], v[90:93], v[114:117], v[20:23]
	v_mfma_f32_16x16x32_bf16 v[16:19], v[98:101], v[114:117], v[16:19]
	v_mfma_f32_16x16x32_bf16 v[12:15], v[90:93], v[122:125], v[12:15]
	v_mfma_f32_16x16x32_bf16 v[8:11], v[98:101], v[122:125], v[8:11]
	v_mfma_f32_16x16x32_bf16 v[4:7], v[90:93], v[130:133], v[4:7]
	v_mfma_f32_16x16x32_bf16 v[0:3], v[98:101], v[130:133], v[0:3]
	s_setprio 0
	s_barrier
	s_add_i32 vcc_lo, vcc_lo, 2
	s_add_u32 s70, s70, 0x100
	s_addc_u32 s71, s71, 0
	s_add_u32 s67, s67, 0x100
	s_addc_u32 s97, s97, 0
	s_cmp_gt_u32 vcc_lo, 13
	s_cbranch_scc0 .LBB0_336
	s_and_b64 vcc, exec, s[62:63]
	s_cbranch_vccz .LBB0_339
	s_barrier

; #define PG8_STAGE(bufoff, gbase, voff) do { _Pragma("unroll") for (int _i = 0; _i < 2; ++_i) \
;         __builtin_amdgcn_global_load_lds((const unsigned*)((const char*)(gbase) + (voff)[_i]), (LAS unsigned*)(lds + (bufoff) + ldsw + _i * 8192), 16, 0, 0); } while (0)
; #define PG8_LDA(dst, b, h) do { _Pragma("unroll") for (int m = 0; m < 4; ++m) _Pragma("unroll") for (int k = 0; k < 2; ++k) dst[m][k] = *(const LAS bf16x8*)(lds + PG8_SA(b, h) + aoff + m * 2048 + k * 1024); } while (0)
; #define PG8_LDB(dst, b, h) do { _Pragma("unroll") for (int n = 0; n < 2; ++n) _Pragma("unroll") for (int k = 0; k < 2; ++k) dst[n][k] = *(const LAS bf16x8*)(lds + PG8_SB(b, h) + boff + n * 2048 + k * 1024); } while (0)
; #define PG8_MMA(ai, bj, At, Bt) do { __builtin_amdgcn_s_setprio(1); _Pragma("unroll") for (int m = 0; m < 4; ++m) _Pragma("unroll") for (int n = 0; n < 2; ++n) _Pragma("unroll") for (int k = 0; k < 2; ++k) \
;         acc[ai][bj][m][n] = __builtin_amdgcn_mfma_f32_16x16x32_bf16(Bt[n][k], At[m][k], acc[ai][bj][m][n], 0, 0, 0); __builtin_amdgcn_s_setprio(0); } while (0)
; #define PG8_WAIT_V(n) asm volatile("s_waitcnt vmcnt(" #n ")" ::: "memory")
; #define PG8_WAIT_L(n) asm volatile("s_waitcnt lgkmcnt(" #n ")" ::: "memory")
; #define PG8_BAR __builtin_amdgcn_s_barrier()
; #define PG8_SCHED __builtin_amdgcn_sched_barrier(0)
; template <class Epi, class Sched>
; __device__ __forceinline__ void gemm_phase(LAS unsigned char* lds, const Gemm g, const Sched& S, const Epi& E) {
;     ...
;         for (int t = 0; t < nt; t += 2) {
;             const bool last = (t == nt - 2);
;             const char* a1 = cA + (size_t)(t + 1) * kstep;
;             const char* a2 = last ? nA : cA + (size_t)(t + 2) * kstep; const char* b2 = last ? nB : cB + (size_t)(t + 2) * kstep;
;             const char* a3 = a2 + kstep; const char* b3 = b2 + kstep;
;             PG8_LDB(B0, 0, 0); PG8_LDB(B1, 0, 1); PG8_SCHED; PG8_LDA(At, 0, 0); PG8_STAGE(PG8_SA(1, 1), a1 + hstepA, voffA);
;             PG8_WAIT_V(8); PG8_WAIT_L(0); PG8_BAR; PG8_MMA(0, 0, At, B0); PG8_MMA(0, 1, At, B1); PG8_BAR; PG8_SCHED;
;             PG8_LDA(At, 0, 1); PG8_STAGE(PG8_SB(0, 0), b2, voffB); PG8_STAGE(PG8_SB(0, 1), b2 + hstepB, voffB); PG8_STAGE(PG8_SA(0, 0), a2, voffA);
;             PG8_WAIT_V(8); PG8_WAIT_L(0); PG8_BAR; PG8_MMA(1, 0, At, B0); PG8_MMA(1, 1, At, B1); PG8_BAR; PG8_SCHED;
.LBB0_507:
	ds_read_b128 v[148:151], v159
	ds_read_b128 v[164:167], v159 offset:1024
	ds_read_b128 v[168:171], v159 offset:2048
	ds_read_b128 v[172:175], v159 offset:3072
	ds_read_b128 v[176:179], v160
	ds_read_b128 v[180:183], v160 offset:1024
	ds_read_b128 v[184:187], v160 offset:2048
	ds_read_b128 v[188:191], v160 offset:3072
	s_add_i32 s47, s46, 2
	s_add_u32 s48, s66, 0xfffb8080
	s_addc_u32 s49, s67, -1
	s_cmp_eq_u32 s33, s46
	s_cselect_b32 s73, s63, s49
	s_cselect_b32 s72, s62, s48
	s_cselect_b32 s71, s65, s35
	s_cselect_b32 s70, s64, s34
	v_lshl_add_u64 v[154:155], s[66:67], 0, v[144:145]
	s_add_i32 m0, s41, 0xc000
	ds_read_b128 v[192:195], v161
	ds_read_b128 v[196:199], v161 offset:1024
	ds_read_b128 v[200:203], v161 offset:2048
	ds_read_b128 v[204:207], v161 offset:3072
	ds_read_b128 v[208:211], v161 offset:4096
	ds_read_b128 v[212:215], v161 offset:5120
	ds_read_b128 v[216:219], v161 offset:6144
	ds_read_b128 v[220:223], v161 offset:7168
	global_load_lds_dwordx4 v[154:155], off
	v_lshl_add_u64 v[154:155], s[66:67], 0, v[146:147]
	s_add_i32 m0, s41, 0xe000
	s_nop 0
	global_load_lds_dwordx4 v[154:155], off
	s_waitcnt vmcnt(8)
	s_waitcnt lgkmcnt(0)
	s_barrier
	s_setprio 1
	s_waitcnt lgkmcnt(0)
	v_mfma_f32_16x16x32_bf16 v[124:127], v[148:151], v[192:195], v[124:127]
	v_mfma_f32_16x16x32_bf16 v[120:123], v[168:171], v[192:195], v[120:123]
	v_mfma_f32_16x16x32_bf16 v[108:111], v[148:151], v[200:203], v[108:111]
	v_mfma_f32_16x16x32_bf16 v[104:107], v[168:171], v[200:203], v[104:107]
	v_mfma_f32_16x16x32_bf16 v[92:95], v[148:151], v[208:211], v[92:95]
	v_mfma_f32_16x16x32_bf16 v[88:91], v[168:171], v[208:211], v[88:91]
	v_mfma_f32_16x16x32_bf16 v[76:79], v[148:151], v[216:219], v[76:79]
	v_mfma_f32_16x16x32_bf16 v[72:75], v[168:171], v[216:219], v[72:75]
	v_mfma_f32_16x16x32_bf16 v[124:127], v[164:167], v[196:199], v[124:127]
	v_mfma_f32_16x16x32_bf16 v[120:123], v[172:175], v[196:199], v[120:123]
	v_mfma_f32_16x16x32_bf16 v[108:111], v[164:167], v[204:207], v[108:111]
	v_mfma_f32_16x16x32_bf16 v[104:107], v[172:175], v[204:207], v[104:107]
	v_mfma_f32_16x16x32_bf16 v[92:95], v[164:167], v[212:215], v[92:95]
	v_mfma_f32_16x16x32_bf16 v[88:91], v[172:175], v[212:215], v[88:91]
	v_mfma_f32_16x16x32_bf16 v[76:79], v[164:167], v[220:223], v[76:79]
	v_mfma_f32_16x16x32_bf16 v[72:75], v[172:175], v[220:223], v[72:75]
	v_mfma_f32_16x16x32_bf16 v[116:119], v[176:179], v[192:195], v[116:119]
	v_mfma_f32_16x16x32_bf16 v[112:115], v[184:187], v[192:195], v[112:115]
	v_mfma_f32_16x16x32_bf16 v[100:103], v[176:179], v[200:203], v[100:103]
	v_mfma_f32_16x16x32_bf16 v[96:99], v[184:187], v[200:203], v[96:99]
	v_mfma_f32_16x16x32_bf16 v[84:87], v[176:179], v[208:211], v[84:87]
	v_mfma_f32_16x16x32_bf16 v[80:83], v[184:187], v[208:211], v[80:83]
	v_mfma_f32_16x16x32_bf16 v[68:71], v[176:179], v[216:219], v[68:71]
	v_mfma_f32_16x16x32_bf16 v[64:67], v[184:187], v[216:219], v[64:67]
	v_mfma_f32_16x16x32_bf16 v[116:119], v[180:183], v[196:199], v[116:119]
	v_mfma_f32_16x16x32_bf16 v[112:115], v[188:191], v[196:199], v[112:115]
	v_mfma_f32_16x16x32_bf16 v[100:103], v[180:183], v[204:207], v[100:103]
	v_mfma_f32_16x16x32_bf16 v[96:99], v[188:191], v[204:207], v[96:99]
	v_mfma_f32_16x16x32_bf16 v[84:87], v[180:183], v[212:215], v[84:87]
	v_mfma_f32_16x16x32_bf16 v[80:83], v[188:191], v[212:215], v[80:83]
	v_mfma_f32_16x16x32_bf16 v[68:71], v[180:183], v[220:223], v[68:71]
	v_mfma_f32_16x16x32_bf16 v[64:67], v[188:191], v[220:223], v[64:67]
	s_setprio 0
	s_barrier
	s_add_i32 s46, s77, s25
	v_lshl_add_u64 v[154:155], s[70:71], 0, v[130:131]
	s_mov_b32 m0, s46
	ds_read_b128 v[192:195], v161 offset:16384
	ds_read_b128 v[196:199], v161 offset:17408
	ds_read_b128 v[200:203], v161 offset:18432
	ds_read_b128 v[204:207], v161 offset:19456
	ds_read_b128 v[208:211], v161 offset:20480
	ds_read_b128 v[212:215], v161 offset:21504
	ds_read_b128 v[216:219], v161 offset:22528
	ds_read_b128 v[220:223], v161 offset:23552
	global_load_lds_dwordx4 v[154:155], off
	s_add_i32 m0, s46, 0x2000
	s_add_u32 s48, s70, 0x48000
	v_lshl_add_u64 v[224:225], s[70:71], 0, v[134:135]
	s_addc_u32 s49, s71, 0
	s_add_i32 s46, s78, s25
	global_load_lds_dwordx4 v[224:225], off
	v_lshl_add_u64 v[226:227], s[48:49], 0, v[130:131]
	s_mov_b32 m0, s46
	v_lshl_add_u64 v[228:229], s[72:73], 0, v[132:133]
	global_load_lds_dwordx4 v[226:227], off
	v_lshl_add_u64 v[226:227], s[48:49], 0, v[134:135]
	s_add_i32 m0, s46, 0x2000
	s_nop 0
	global_load_lds_dwordx4 v[226:227], off
	v_lshl_add_u64 v[226:227], s[72:73], 0, v[128:129]
	s_mov_b32 m0, s41
	s_nop 0
	global_load_lds_dwordx4 v[226:227], off
	s_mov_b32 m0, s43
	s_nop 0
	global_load_lds_dwordx4 v[228:229], off
	s_waitcnt vmcnt(8)
	s_waitcnt lgkmcnt(0)
	s_barrier
; #define PG8_STAGE(bufoff, gbase, voff) do { _Pragma("unroll") for (int _i = 0; _i < 2; ++_i) \
;         __builtin_amdgcn_global_load_lds((const unsigned*)((const char*)(gbase) + (voff)[_i]), (LAS unsigned*)(lds + (bufoff) + ldsw + _i * 8192), 16, 0, 0); } while (0)
; #define PG8_LDA(dst, b, h) do { _Pragma("unroll") for (int m = 0; m < 4; ++m) _Pragma("unroll") for (int k = 0; k < 2; ++k) dst[m][k] = *(const LAS bf16x8*)(lds + PG8_SA(b, h) + aoff + m * 2048 + k * 1024); } while (0)
; #define PG8_LDB(dst, b, h) do { _Pragma("unroll") for (int n = 0; n < 2; ++n) _Pragma("unroll") for (int k = 0; k < 2; ++k) dst[n][k] = *(const LAS bf16x8*)(lds + PG8_SB(b, h) + boff + n * 2048 + k * 1024); } while (0)
; #define PG8_MMA(ai, bj, At, Bt) do { __builtin_amdgcn_s_setprio(1); _Pragma("unroll") for (int m = 0; m < 4; ++m) _Pragma("unroll") for (int n = 0; n < 2; ++n) _Pragma("unroll") for (int k = 0; k < 2; ++k) \
;         acc[ai][bj][m][n] = __builtin_amdgcn_mfma_f32_16x16x32_bf16(Bt[n][k], At[m][k], acc[ai][bj][m][n], 0, 0, 0); __builtin_amdgcn_s_setprio(0); } while (0)
; #define PG8_WAIT_V(n) asm volatile("s_waitcnt vmcnt(" #n ")" ::: "memory")
; #define PG8_WAIT_L(n) asm volatile("s_waitcnt lgkmcnt(" #n ")" ::: "memory")
; #define PG8_BAR __builtin_amdgcn_s_barrier()
; #define PG8_SCHED __builtin_amdgcn_sched_barrier(0)
; template <class Epi, class Sched>
; __device__ __forceinline__ void gemm_phase(LAS unsigned char* lds, const Gemm g, const Sched& S, const Epi& E) {
;     ...
;             PG8_WAIT_V(8); PG8_WAIT_L(0); PG8_BAR; PG8_MMA(1, 0, At, B0); PG8_MMA(1, 1, At, B1); PG8_BAR; PG8_SCHED;
;             PG8_LDB(B0, 1, 0); PG8_LDB(B1, 1, 1); PG8_SCHED; PG8_LDA(At, 1, 0); PG8_STAGE(PG8_SA(0, 1), a2 + hstepA, voffA);
;             PG8_WAIT_V(8); PG8_WAIT_L(0); PG8_BAR; PG8_MMA(0, 0, At, B0); PG8_MMA(0, 1, At, B1); PG8_BAR; PG8_SCHED;
	s_setprio 1
	s_waitcnt lgkmcnt(0)
	v_mfma_f32_16x16x32_bf16 v[60:63], v[148:151], v[192:195], v[60:63]
	v_mfma_f32_16x16x32_bf16 v[56:59], v[168:171], v[192:195], v[56:59]
	v_mfma_f32_16x16x32_bf16 v[44:47], v[148:151], v[200:203], v[44:47]
	v_mfma_f32_16x16x32_bf16 v[40:43], v[168:171], v[200:203], v[40:43]
	v_mfma_f32_16x16x32_bf16 v[28:31], v[148:151], v[208:211], v[28:31]
	v_mfma_f32_16x16x32_bf16 v[24:27], v[168:171], v[208:211], v[24:27]
	v_mfma_f32_16x16x32_bf16 v[12:15], v[148:151], v[216:219], v[12:15]
	v_mfma_f32_16x16x32_bf16 v[8:11], v[168:171], v[216:219], v[8:11]
	v_mfma_f32_16x16x32_bf16 v[60:63], v[164:167], v[196:199], v[60:63]
	v_mfma_f32_16x16x32_bf16 v[56:59], v[172:175], v[196:199], v[56:59]
	v_mfma_f32_16x16x32_bf16 v[44:47], v[164:167], v[204:207], v[44:47]
	v_mfma_f32_16x16x32_bf16 v[40:43], v[172:175], v[204:207], v[40:43]
	v_mfma_f32_16x16x32_bf16 v[28:31], v[164:167], v[212:215], v[28:31]
	v_mfma_f32_16x16x32_bf16 v[24:27], v[172:175], v[212:215], v[24:27]
	v_mfma_f32_16x16x32_bf16 v[12:15], v[164:167], v[220:223], v[12:15]
	v_mfma_f32_16x16x32_bf16 v[8:11], v[172:175], v[220:223], v[8:11]
	v_mfma_f32_16x16x32_bf16 v[52:55], v[176:179], v[192:195], v[52:55]
	v_mfma_f32_16x16x32_bf16 v[48:51], v[184:187], v[192:195], v[48:51]
	v_mfma_f32_16x16x32_bf16 v[36:39], v[176:179], v[200:203], v[36:39]
	v_mfma_f32_16x16x32_bf16 v[32:35], v[184:187], v[200:203], v[32:35]
	v_mfma_f32_16x16x32_bf16 v[20:23], v[176:179], v[208:211], v[20:23]
	v_mfma_f32_16x16x32_bf16 v[16:19], v[184:187], v[208:211], v[16:19]
	v_mfma_f32_16x16x32_bf16 v[4:7], v[176:179], v[216:219], v[4:7]
	v_mfma_f32_16x16x32_bf16 v[0:3], v[184:187], v[216:219], v[0:3]
	v_mfma_f32_16x16x32_bf16 v[52:55], v[180:183], v[196:199], v[52:55]
	v_mfma_f32_16x16x32_bf16 v[48:51], v[188:191], v[196:199], v[48:51]
	v_mfma_f32_16x16x32_bf16 v[36:39], v[180:183], v[204:207], v[36:39]
	v_mfma_f32_16x16x32_bf16 v[32:35], v[188:191], v[204:207], v[32:35]
	v_mfma_f32_16x16x32_bf16 v[20:23], v[180:183], v[212:215], v[20:23]
	v_mfma_f32_16x16x32_bf16 v[16:19], v[188:191], v[212:215], v[16:19]
	v_mfma_f32_16x16x32_bf16 v[4:7], v[180:183], v[220:223], v[4:7]
	v_mfma_f32_16x16x32_bf16 v[0:3], v[188:191], v[220:223], v[0:3]
	s_setprio 0
	s_barrier
	s_add_i32 s46, 0, 0x18000
	v_add_u32_e32 v138, s46, v141
	s_add_i32 s75, 0, 0x1c000
	ds_read_b128 v[148:151], v138
	ds_read_b128 v[164:167], v138 offset:1024
	ds_read_b128 v[168:171], v138 offset:2048
	ds_read_b128 v[172:175], v138 offset:3072
	v_add_u32_e32 v138, s75, v141
	ds_read_b128 v[176:179], v138
	ds_read_b128 v[180:183], v138 offset:1024
	ds_read_b128 v[184:187], v138 offset:2048
	ds_read_b128 v[188:191], v138 offset:3072
	s_add_u32 s48, s72, 0x48000
	s_addc_u32 s49, s73, 0
	s_mov_b32 m0, s45
	v_lshl_add_u64 v[230:231], s[48:49], 0, v[128:129]
	ds_read_b128 v[192:195], v161 offset:32768
	ds_read_b128 v[196:199], v161 offset:33792
	ds_read_b128 v[200:203], v161 offset:34816
	ds_read_b128 v[204:207], v161 offset:35840
	ds_read_b128 v[208:211], v161 offset:36864
	ds_read_b128 v[212:215], v161 offset:37888
	ds_read_b128 v[216:219], v161 offset:38912
	ds_read_b128 v[220:223], v161 offset:39936
	global_load_lds_dwordx4 v[230:231], off
	v_lshl_add_u64 v[230:231], s[48:49], 0, v[132:133]
	s_mov_b32 m0, s57
	s_nop 0
	global_load_lds_dwordx4 v[230:231], off
	s_waitcnt vmcnt(8)
	s_waitcnt lgkmcnt(0)
	s_barrier
	s_setprio 1
	s_waitcnt lgkmcnt(0)
	v_mfma_f32_16x16x32_bf16 v[124:127], v[148:151], v[192:195], v[124:127]
	v_mfma_f32_16x16x32_bf16 v[120:123], v[168:171], v[192:195], v[120:123]
	v_mfma_f32_16x16x32_bf16 v[108:111], v[148:151], v[200:203], v[108:111]
	v_mfma_f32_16x16x32_bf16 v[104:107], v[168:171], v[200:203], v[104:107]
	v_mfma_f32_16x16x32_bf16 v[92:95], v[148:151], v[208:211], v[92:95]
	v_mfma_f32_16x16x32_bf16 v[88:91], v[168:171], v[208:211], v[88:91]
	v_mfma_f32_16x16x32_bf16 v[76:79], v[148:151], v[216:219], v[76:79]
	v_mfma_f32_16x16x32_bf16 v[72:75], v[168:171], v[216:219], v[72:75]
	v_mfma_f32_16x16x32_bf16 v[124:127], v[164:167], v[196:199], v[124:127]
	v_mfma_f32_16x16x32_bf16 v[120:123], v[172:175], v[196:199], v[120:123]
	v_mfma_f32_16x16x32_bf16 v[108:111], v[164:167], v[204:207], v[108:111]
	v_mfma_f32_16x16x32_bf16 v[104:107], v[172:175], v[204:207], v[104:107]
	v_mfma_f32_16x16x32_bf16 v[92:95], v[164:167], v[212:215], v[92:95]
	v_mfma_f32_16x16x32_bf16 v[88:91], v[172:175], v[212:215], v[88:91]
	v_mfma_f32_16x16x32_bf16 v[76:79], v[164:167], v[220:223], v[76:79]
	v_mfma_f32_16x16x32_bf16 v[72:75], v[172:175], v[220:223], v[72:75]
	v_mfma_f32_16x16x32_bf16 v[116:119], v[176:179], v[192:195], v[116:119]
	v_mfma_f32_16x16x32_bf16 v[112:115], v[184:187], v[192:195], v[112:115]
	v_mfma_f32_16x16x32_bf16 v[100:103], v[176:179], v[200:203], v[100:103]
	v_mfma_f32_16x16x32_bf16 v[96:99], v[184:187], v[200:203], v[96:99]
	v_mfma_f32_16x16x32_bf16 v[84:87], v[176:179], v[208:211], v[84:87]
	v_mfma_f32_16x16x32_bf16 v[80:83], v[184:187], v[208:211], v[80:83]
	v_mfma_f32_16x16x32_bf16 v[68:71], v[176:179], v[216:219], v[68:71]
	v_mfma_f32_16x16x32_bf16 v[64:67], v[184:187], v[216:219], v[64:67]
	v_mfma_f32_16x16x32_bf16 v[116:119], v[180:183], v[196:199], v[116:119]
	v_mfma_f32_16x16x32_bf16 v[112:115], v[188:191], v[196:199], v[112:115]
	v_mfma_f32_16x16x32_bf16 v[100:103], v[180:183], v[204:207], v[100:103]
	v_mfma_f32_16x16x32_bf16 v[96:99], v[188:191], v[204:207], v[96:99]
	v_mfma_f32_16x16x32_bf16 v[84:87], v[180:183], v[212:215], v[84:87]
	v_mfma_f32_16x16x32_bf16 v[80:83], v[188:191], v[212:215], v[80:83]
	v_mfma_f32_16x16x32_bf16 v[68:71], v[180:183], v[220:223], v[68:71]
	v_mfma_f32_16x16x32_bf16 v[64:67], v[188:191], v[220:223], v[64:67]
	s_setprio 0
	s_barrier
; #define PG8_STAGE(bufoff, gbase, voff) do { _Pragma("unroll") for (int _i = 0; _i < 2; ++_i) \
;         __builtin_amdgcn_global_load_lds((const unsigned*)((const char*)(gbase) + (voff)[_i]), (LAS unsigned*)(lds + (bufoff) + ldsw + _i * 8192), 16, 0, 0); } while (0)
; #define PG8_LDA(dst, b, h) do { _Pragma("unroll") for (int m = 0; m < 4; ++m) _Pragma("unroll") for (int k = 0; k < 2; ++k) dst[m][k] = *(const LAS bf16x8*)(lds + PG8_SA(b, h) + aoff + m * 2048 + k * 1024); } while (0)
; #define PG8_MMA(ai, bj, At, Bt) do { __builtin_amdgcn_s_setprio(1); _Pragma("unroll") for (int m = 0; m < 4; ++m) _Pragma("unroll") for (int n = 0; n < 2; ++n) _Pragma("unroll") for (int k = 0; k < 2; ++k) \
;         acc[ai][bj][m][n] = __builtin_amdgcn_mfma_f32_16x16x32_bf16(Bt[n][k], At[m][k], acc[ai][bj][m][n], 0, 0, 0); __builtin_amdgcn_s_setprio(0); } while (0)
; #define PG8_WAIT_V(n) asm volatile("s_waitcnt vmcnt(" #n ")" ::: "memory")
; #define PG8_WAIT_L(n) asm volatile("s_waitcnt lgkmcnt(" #n ")" ::: "memory")
; #define PG8_BAR __builtin_amdgcn_s_barrier()
; #define PG8_SCHED __builtin_amdgcn_sched_barrier(0)
; template <class Epi, class Sched>
; __device__ __forceinline__ void gemm_phase(LAS unsigned char* lds, const Gemm g, const Sched& S, const Epi& E) {
;     ...
;             PG8_LDA(At, 1, 1); PG8_STAGE(PG8_SB(1, 0), b3, voffB); PG8_STAGE(PG8_SB(1, 1), b3 + hstepB, voffB); PG8_STAGE(PG8_SA(1, 0), a3, voffA);
;             PG8_WAIT_V(8); PG8_WAIT_L(0); PG8_BAR; PG8_MMA(1, 0, At, B0); PG8_MMA(1, 1, At, B1); PG8_BAR; PG8_SCHED;
;         }
;         if (wr == 0) PG8_BAR;
	s_add_i32 s46, s46, s25
	v_lshl_add_u64 v[154:155], v[154:155], 0, s[18:19]
	s_mov_b32 m0, s46
	ds_read_b128 v[192:195], v161 offset:49152
	ds_read_b128 v[196:199], v161 offset:50176
	ds_read_b128 v[200:203], v161 offset:51200
	ds_read_b128 v[204:207], v161 offset:52224
	ds_read_b128 v[208:211], v161 offset:53248
	ds_read_b128 v[212:215], v161 offset:54272
	ds_read_b128 v[216:219], v161 offset:55296
	ds_read_b128 v[220:223], v161 offset:56320
	global_load_lds_dwordx4 v[154:155], off
	s_add_i32 m0, s46, 0x2000
	s_add_u32 s48, s70, 0x48080
	v_lshl_add_u64 v[154:155], v[224:225], 0, s[18:19]
	s_addc_u32 s49, s71, 0
	s_add_i32 s46, s75, s25
	global_load_lds_dwordx4 v[154:155], off
	v_lshl_add_u64 v[154:155], s[48:49], 0, v[130:131]
	s_mov_b32 m0, s46
	s_nop 0
	global_load_lds_dwordx4 v[154:155], off
	v_lshl_add_u64 v[154:155], s[48:49], 0, v[134:135]
	s_add_i32 m0, s46, 0x2000
	s_nop 0
	global_load_lds_dwordx4 v[154:155], off
	v_lshl_add_u64 v[154:155], v[226:227], 0, s[18:19]
	s_mov_b32 m0, s59
	s_nop 0
	global_load_lds_dwordx4 v[154:155], off
	v_lshl_add_u64 v[154:155], v[228:229], 0, s[18:19]
	s_mov_b32 m0, s61
	s_nop 0
	global_load_lds_dwordx4 v[154:155], off
	s_waitcnt vmcnt(8)
	s_waitcnt lgkmcnt(0)
	s_barrier
	s_setprio 1
	s_waitcnt lgkmcnt(0)
	v_mfma_f32_16x16x32_bf16 v[60:63], v[148:151], v[192:195], v[60:63]
	v_mfma_f32_16x16x32_bf16 v[56:59], v[168:171], v[192:195], v[56:59]
	v_mfma_f32_16x16x32_bf16 v[44:47], v[148:151], v[200:203], v[44:47]
	v_mfma_f32_16x16x32_bf16 v[40:43], v[168:171], v[200:203], v[40:43]
	v_mfma_f32_16x16x32_bf16 v[28:31], v[148:151], v[208:211], v[28:31]
	v_mfma_f32_16x16x32_bf16 v[24:27], v[168:171], v[208:211], v[24:27]
	v_mfma_f32_16x16x32_bf16 v[12:15], v[148:151], v[216:219], v[12:15]
	v_mfma_f32_16x16x32_bf16 v[8:11], v[168:171], v[216:219], v[8:11]
	v_mfma_f32_16x16x32_bf16 v[60:63], v[164:167], v[196:199], v[60:63]
	v_mfma_f32_16x16x32_bf16 v[56:59], v[172:175], v[196:199], v[56:59]
	v_mfma_f32_16x16x32_bf16 v[44:47], v[164:167], v[204:207], v[44:47]
	v_mfma_f32_16x16x32_bf16 v[40:43], v[172:175], v[204:207], v[40:43]
	v_mfma_f32_16x16x32_bf16 v[28:31], v[164:167], v[212:215], v[28:31]
	v_mfma_f32_16x16x32_bf16 v[24:27], v[172:175], v[212:215], v[24:27]
	v_mfma_f32_16x16x32_bf16 v[12:15], v[164:167], v[220:223], v[12:15]
	v_mfma_f32_16x16x32_bf16 v[8:11], v[172:175], v[220:223], v[8:11]
	v_mfma_f32_16x16x32_bf16 v[52:55], v[176:179], v[192:195], v[52:55]
	v_mfma_f32_16x16x32_bf16 v[48:51], v[184:187], v[192:195], v[48:51]
	v_mfma_f32_16x16x32_bf16 v[36:39], v[176:179], v[200:203], v[36:39]
	v_mfma_f32_16x16x32_bf16 v[32:35], v[184:187], v[200:203], v[32:35]
	v_mfma_f32_16x16x32_bf16 v[20:23], v[176:179], v[208:211], v[20:23]
	v_mfma_f32_16x16x32_bf16 v[16:19], v[184:187], v[208:211], v[16:19]
	v_mfma_f32_16x16x32_bf16 v[4:7], v[176:179], v[216:219], v[4:7]
	v_mfma_f32_16x16x32_bf16 v[0:3], v[184:187], v[216:219], v[0:3]
	v_mfma_f32_16x16x32_bf16 v[52:55], v[180:183], v[196:199], v[52:55]
	v_mfma_f32_16x16x32_bf16 v[48:51], v[188:191], v[196:199], v[48:51]
	v_mfma_f32_16x16x32_bf16 v[36:39], v[180:183], v[204:207], v[36:39]
	v_mfma_f32_16x16x32_bf16 v[32:35], v[188:191], v[204:207], v[32:35]
	v_mfma_f32_16x16x32_bf16 v[20:23], v[180:183], v[212:215], v[20:23]
	v_mfma_f32_16x16x32_bf16 v[16:19], v[188:191], v[212:215], v[16:19]
	v_mfma_f32_16x16x32_bf16 v[4:7], v[180:183], v[220:223], v[4:7]
	v_mfma_f32_16x16x32_bf16 v[0:3], v[188:191], v[220:223], v[0:3]
	s_setprio 0
	s_barrier
	s_add_u32 s66, s66, 0x100
	s_addc_u32 s67, s67, 0
	s_add_u32 s34, s34, 0x100
	s_addc_u32 s35, s35, 0
	s_cmp_ge_i32 s47, s5
	s_mov_b32 s46, s47
	s_cbranch_scc0 .LBB0_507
	s_and_b64 vcc, exec, s[20:21]
	s_cbranch_vccz .LBB0_510
	s_barrier

; #define PG8_STAGE(bufoff, gbase, voff) do { _Pragma("unroll") for (int _i = 0; _i < 2; ++_i) \
;         __builtin_amdgcn_global_load_lds((const unsigned*)((const char*)(gbase) + (voff)[_i]), (LAS unsigned*)(lds + (bufoff) + ldsw + _i * 8192), 16, 0, 0); } while (0)
; #define PG8_LDA(dst, b, h) do { _Pragma("unroll") for (int m = 0; m < 4; ++m) _Pragma("unroll") for (int k = 0; k < 2; ++k) dst[m][k] = *(const LAS bf16x8*)(lds + PG8_SA(b, h) + aoff + m * 2048 + k * 1024); } while (0)
; #define PG8_LDB(dst, b, h) do { _Pragma("unroll") for (int n = 0; n < 2; ++n) _Pragma("unroll") for (int k = 0; k < 2; ++k) dst[n][k] = *(const LAS bf16x8*)(lds + PG8_SB(b, h) + boff + n * 2048 + k * 1024); } while (0)
; #define PG8_MMA(ai, bj, At, Bt) do { __builtin_amdgcn_s_setprio(1); _Pragma("unroll") for (int m = 0; m < 4; ++m) _Pragma("unroll") for (int n = 0; n < 2; ++n) _Pragma("unroll") for (int k = 0; k < 2; ++k) \
;         acc[ai][bj][m][n] = __builtin_amdgcn_mfma_f32_16x16x32_bf16(Bt[n][k], At[m][k], acc[ai][bj][m][n], 0, 0, 0); __builtin_amdgcn_s_setprio(0); } while (0)
; #define PG8_WAIT_V(n) asm volatile("s_waitcnt vmcnt(" #n ")" ::: "memory")
; #define PG8_WAIT_L(n) asm volatile("s_waitcnt lgkmcnt(" #n ")" ::: "memory")
; #define PG8_BAR __builtin_amdgcn_s_barrier()
; #define PG8_SCHED __builtin_amdgcn_sched_barrier(0)
; template <class Epi, class Sched>
; __device__ __forceinline__ void gemm_phase(LAS unsigned char* lds, const Gemm g, const Sched& S, const Epi& E) {
;     ...
;         for (int t = 0; t < nt; t += 2) {
;             const bool last = (t == nt - 2);
;             const char* a1 = cA + (size_t)(t + 1) * kstep;
;             const char* a2 = last ? nA : cA + (size_t)(t + 2) * kstep; const char* b2 = last ? nB : cB + (size_t)(t + 2) * kstep;
;             const char* a3 = a2 + kstep; const char* b3 = b2 + kstep;
;             PG8_LDB(B0, 0, 0); PG8_LDB(B1, 0, 1); PG8_SCHED; PG8_LDA(At, 0, 0); PG8_STAGE(PG8_SA(1, 1), a1 + hstepA, voffA);
;             PG8_WAIT_V(8); PG8_WAIT_L(0); PG8_BAR; PG8_MMA(0, 0, At, B0); PG8_MMA(0, 1, At, B1); PG8_BAR; PG8_SCHED;
;             PG8_LDA(At, 0, 1); PG8_STAGE(PG8_SB(0, 0), b2, voffB); PG8_STAGE(PG8_SB(0, 1), b2 + hstepB, voffB); PG8_STAGE(PG8_SA(0, 0), a2, voffA);
;             PG8_WAIT_V(8); PG8_WAIT_L(0); PG8_BAR; PG8_MMA(1, 0, At, B0); PG8_MMA(1, 1, At, B1); PG8_BAR; PG8_SCHED;
.LBB0_602:
	ds_read_b128 v[112:115], v172
	ds_read_b128 v[116:119], v172 offset:1024
	ds_read_b128 v[156:159], v172 offset:2048
	ds_read_b128 v[160:163], v172 offset:3072
	ds_read_b128 v[164:167], v173
	ds_read_b128 v[176:179], v173 offset:1024
	ds_read_b128 v[180:183], v173 offset:2048
	ds_read_b128 v[184:187], v173 offset:3072
	s_add_u32 s46, s56, 0xfffc0080
	s_addc_u32 s47, s57, -1
	s_cmp_eq_u32 s43, 12
	s_cselect_b32 s61, s4, s47
	s_cselect_b32 s60, s5, s46
	s_cselect_b32 s59, s17, s41
	s_cselect_b32 s58, s34, s35
	v_lshl_add_u64 v[220:221], s[56:57], 0, v[146:147]
	s_add_i32 m0, s64, 0xc000
	ds_read_b128 v[188:191], v174
	ds_read_b128 v[192:195], v174 offset:1024
	ds_read_b128 v[196:199], v174 offset:2048
	ds_read_b128 v[200:203], v174 offset:3072
	ds_read_b128 v[204:207], v174 offset:4096
	ds_read_b128 v[208:211], v174 offset:5120
	ds_read_b128 v[212:215], v174 offset:6144
	ds_read_b128 v[216:219], v174 offset:7168
	global_load_lds_dwordx4 v[220:221], off
	v_lshl_add_u64 v[220:221], s[56:57], 0, v[148:149]
	s_add_i32 m0, s64, 0xe000
	s_nop 0
	global_load_lds_dwordx4 v[220:221], off
	s_waitcnt vmcnt(8)
	s_waitcnt lgkmcnt(0)
	s_barrier
	s_setprio 1
	s_waitcnt lgkmcnt(0)
	v_mfma_f32_16x16x32_bf16 v[132:135], v[112:115], v[188:191], v[132:135]
	v_mfma_f32_16x16x32_bf16 v[128:131], v[156:159], v[188:191], v[128:131]
	v_mfma_f32_16x16x32_bf16 v[124:127], v[112:115], v[196:199], v[124:127]
	v_mfma_f32_16x16x32_bf16 v[120:123], v[156:159], v[196:199], v[120:123]
	v_mfma_f32_16x16x32_bf16 v[108:111], v[112:115], v[204:207], v[108:111]
	v_mfma_f32_16x16x32_bf16 v[104:107], v[156:159], v[204:207], v[104:107]
	v_mfma_f32_16x16x32_bf16 v[100:103], v[112:115], v[212:215], v[100:103]
	v_mfma_f32_16x16x32_bf16 v[96:99], v[156:159], v[212:215], v[96:99]
	v_mfma_f32_16x16x32_bf16 v[132:135], v[116:119], v[192:195], v[132:135]
	v_mfma_f32_16x16x32_bf16 v[128:131], v[160:163], v[192:195], v[128:131]
	v_mfma_f32_16x16x32_bf16 v[124:127], v[116:119], v[200:203], v[124:127]
	v_mfma_f32_16x16x32_bf16 v[120:123], v[160:163], v[200:203], v[120:123]
	v_mfma_f32_16x16x32_bf16 v[108:111], v[116:119], v[208:211], v[108:111]
	v_mfma_f32_16x16x32_bf16 v[104:107], v[160:163], v[208:211], v[104:107]
	v_mfma_f32_16x16x32_bf16 v[100:103], v[116:119], v[216:219], v[100:103]
	v_mfma_f32_16x16x32_bf16 v[96:99], v[160:163], v[216:219], v[96:99]
	v_mfma_f32_16x16x32_bf16 v[60:63], v[164:167], v[188:191], v[60:63]
	v_mfma_f32_16x16x32_bf16 v[56:59], v[180:183], v[188:191], v[56:59]
	v_mfma_f32_16x16x32_bf16 v[52:55], v[164:167], v[196:199], v[52:55]
	v_mfma_f32_16x16x32_bf16 v[48:51], v[180:183], v[196:199], v[48:51]
	v_mfma_f32_16x16x32_bf16 v[44:47], v[164:167], v[204:207], v[44:47]
	v_mfma_f32_16x16x32_bf16 v[40:43], v[180:183], v[204:207], v[40:43]
	v_mfma_f32_16x16x32_bf16 v[36:39], v[164:167], v[212:215], v[36:39]
	v_mfma_f32_16x16x32_bf16 v[32:35], v[180:183], v[212:215], v[32:35]
	v_mfma_f32_16x16x32_bf16 v[60:63], v[176:179], v[192:195], v[60:63]
	v_mfma_f32_16x16x32_bf16 v[56:59], v[184:187], v[192:195], v[56:59]
	v_mfma_f32_16x16x32_bf16 v[52:55], v[176:179], v[200:203], v[52:55]
	v_mfma_f32_16x16x32_bf16 v[48:51], v[184:187], v[200:203], v[48:51]
	v_mfma_f32_16x16x32_bf16 v[44:47], v[176:179], v[208:211], v[44:47]
	v_mfma_f32_16x16x32_bf16 v[40:43], v[184:187], v[208:211], v[40:43]
	v_mfma_f32_16x16x32_bf16 v[36:39], v[176:179], v[216:219], v[36:39]
	v_mfma_f32_16x16x32_bf16 v[32:35], v[184:187], v[216:219], v[32:35]
	s_setprio 0
	s_barrier
	s_add_i32 s46, s73, s63
	v_lshl_add_u64 v[220:221], s[58:59], 0, v[140:141]
	s_mov_b32 m0, s46
	ds_read_b128 v[188:191], v174 offset:16384
	ds_read_b128 v[192:195], v174 offset:17408
	ds_read_b128 v[196:199], v174 offset:18432
	ds_read_b128 v[200:203], v174 offset:19456
	ds_read_b128 v[204:207], v174 offset:20480
	ds_read_b128 v[208:211], v174 offset:21504
	ds_read_b128 v[212:215], v174 offset:22528
	ds_read_b128 v[216:219], v174 offset:23552
	global_load_lds_dwordx4 v[220:221], off
	s_add_i32 m0, s46, 0x2000
	s_add_u32 s46, s58, 0x40000
	v_lshl_add_u64 v[222:223], s[58:59], 0, v[144:145]
	s_addc_u32 s47, s59, 0
	s_add_i32 s48, s76, s63
	global_load_lds_dwordx4 v[222:223], off
	v_lshl_add_u64 v[224:225], s[46:47], 0, v[140:141]
	s_mov_b32 m0, s48
	v_lshl_add_u64 v[226:227], s[60:61], 0, v[142:143]
	global_load_lds_dwordx4 v[224:225], off
	v_lshl_add_u64 v[224:225], s[46:47], 0, v[144:145]
	s_add_i32 m0, s48, 0x2000
	s_nop 0
	global_load_lds_dwordx4 v[224:225], off
	v_lshl_add_u64 v[224:225], s[60:61], 0, v[138:139]
	s_mov_b32 m0, s64
	s_nop 0
	global_load_lds_dwordx4 v[224:225], off
	s_mov_b32 m0, s65
	s_nop 0
	global_load_lds_dwordx4 v[226:227], off
	s_waitcnt vmcnt(8)
	s_waitcnt lgkmcnt(0)
	s_barrier
; #define PG8_STAGE(bufoff, gbase, voff) do { _Pragma("unroll") for (int _i = 0; _i < 2; ++_i) \
;         __builtin_amdgcn_global_load_lds((const unsigned*)((const char*)(gbase) + (voff)[_i]), (LAS unsigned*)(lds + (bufoff) + ldsw + _i * 8192), 16, 0, 0); } while (0)
; #define PG8_LDA(dst, b, h) do { _Pragma("unroll") for (int m = 0; m < 4; ++m) _Pragma("unroll") for (int k = 0; k < 2; ++k) dst[m][k] = *(const LAS bf16x8*)(lds + PG8_SA(b, h) + aoff + m * 2048 + k * 1024); } while (0)
; #define PG8_LDB(dst, b, h) do { _Pragma("unroll") for (int n = 0; n < 2; ++n) _Pragma("unroll") for (int k = 0; k < 2; ++k) dst[n][k] = *(const LAS bf16x8*)(lds + PG8_SB(b, h) + boff + n * 2048 + k * 1024); } while (0)
; #define PG8_MMA(ai, bj, At, Bt) do { __builtin_amdgcn_s_setprio(1); _Pragma("unroll") for (int m = 0; m < 4; ++m) _Pragma("unroll") for (int n = 0; n < 2; ++n) _Pragma("unroll") for (int k = 0; k < 2; ++k) \
;         acc[ai][bj][m][n] = __builtin_amdgcn_mfma_f32_16x16x32_bf16(Bt[n][k], At[m][k], acc[ai][bj][m][n], 0, 0, 0); __builtin_amdgcn_s_setprio(0); } while (0)
; #define PG8_WAIT_V(n) asm volatile("s_waitcnt vmcnt(" #n ")" ::: "memory")
; #define PG8_WAIT_L(n) asm volatile("s_waitcnt lgkmcnt(" #n ")" ::: "memory")
; #define PG8_BAR __builtin_amdgcn_s_barrier()
; #define PG8_SCHED __builtin_amdgcn_sched_barrier(0)
; template <class Epi, class Sched>
; __device__ __forceinline__ void gemm_phase(LAS unsigned char* lds, const Gemm g, const Sched& S, const Epi& E) {
;     ...
;             PG8_WAIT_V(8); PG8_WAIT_L(0); PG8_BAR; PG8_MMA(1, 0, At, B0); PG8_MMA(1, 1, At, B1); PG8_BAR; PG8_SCHED;
;             PG8_LDB(B0, 1, 0); PG8_LDB(B1, 1, 1); PG8_SCHED; PG8_LDA(At, 1, 0); PG8_STAGE(PG8_SA(0, 1), a2 + hstepA, voffA);
;             PG8_WAIT_V(8); PG8_WAIT_L(0); PG8_BAR; PG8_MMA(0, 0, At, B0); PG8_MMA(0, 1, At, B1); PG8_BAR; PG8_SCHED;
	s_setprio 1
	s_waitcnt lgkmcnt(0)
	v_mfma_f32_16x16x32_bf16 v[92:95], v[112:115], v[188:191], v[92:95]
	v_mfma_f32_16x16x32_bf16 v[88:91], v[156:159], v[188:191], v[88:91]
	v_mfma_f32_16x16x32_bf16 v[84:87], v[112:115], v[196:199], v[84:87]
	v_mfma_f32_16x16x32_bf16 v[80:83], v[156:159], v[196:199], v[80:83]
	v_mfma_f32_16x16x32_bf16 v[76:79], v[112:115], v[204:207], v[76:79]
	v_mfma_f32_16x16x32_bf16 v[72:75], v[156:159], v[204:207], v[72:75]
	v_mfma_f32_16x16x32_bf16 v[68:71], v[112:115], v[212:215], v[68:71]
	v_mfma_f32_16x16x32_bf16 v[64:67], v[156:159], v[212:215], v[64:67]
	v_mfma_f32_16x16x32_bf16 v[92:95], v[116:119], v[192:195], v[92:95]
	v_mfma_f32_16x16x32_bf16 v[88:91], v[160:163], v[192:195], v[88:91]
	v_mfma_f32_16x16x32_bf16 v[84:87], v[116:119], v[200:203], v[84:87]
	v_mfma_f32_16x16x32_bf16 v[80:83], v[160:163], v[200:203], v[80:83]
	v_mfma_f32_16x16x32_bf16 v[76:79], v[116:119], v[208:211], v[76:79]
	v_mfma_f32_16x16x32_bf16 v[72:75], v[160:163], v[208:211], v[72:75]
	v_mfma_f32_16x16x32_bf16 v[68:71], v[116:119], v[216:219], v[68:71]
	v_mfma_f32_16x16x32_bf16 v[64:67], v[160:163], v[216:219], v[64:67]
	v_mfma_f32_16x16x32_bf16 v[28:31], v[164:167], v[188:191], v[28:31]
	v_mfma_f32_16x16x32_bf16 v[24:27], v[180:183], v[188:191], v[24:27]
	v_mfma_f32_16x16x32_bf16 v[20:23], v[164:167], v[196:199], v[20:23]
	v_mfma_f32_16x16x32_bf16 v[16:19], v[180:183], v[196:199], v[16:19]
	v_mfma_f32_16x16x32_bf16 v[12:15], v[164:167], v[204:207], v[12:15]
	v_mfma_f32_16x16x32_bf16 v[8:11], v[180:183], v[204:207], v[8:11]
	v_mfma_f32_16x16x32_bf16 v[4:7], v[164:167], v[212:215], v[4:7]
	v_mfma_f32_16x16x32_bf16 v[0:3], v[180:183], v[212:215], v[0:3]
	v_mfma_f32_16x16x32_bf16 v[28:31], v[176:179], v[192:195], v[28:31]
	v_mfma_f32_16x16x32_bf16 v[24:27], v[184:187], v[192:195], v[24:27]
	v_mfma_f32_16x16x32_bf16 v[20:23], v[176:179], v[200:203], v[20:23]
	v_mfma_f32_16x16x32_bf16 v[16:19], v[184:187], v[200:203], v[16:19]
	v_mfma_f32_16x16x32_bf16 v[12:15], v[176:179], v[208:211], v[12:15]
	v_mfma_f32_16x16x32_bf16 v[8:11], v[184:187], v[208:211], v[8:11]
	v_mfma_f32_16x16x32_bf16 v[4:7], v[176:179], v[216:219], v[4:7]
	v_mfma_f32_16x16x32_bf16 v[0:3], v[184:187], v[216:219], v[0:3]
	s_setprio 0
	s_barrier
	s_add_i32 s48, 0, 0x18000
	s_add_i32 s49, 0, 0x1c000
	v_add_u32_e32 v160, s48, v153
	v_add_u32_e32 v175, s49, v153
	ds_read_b128 v[112:115], v160
	ds_read_b128 v[116:119], v160 offset:1024
	ds_read_b128 v[156:159], v160 offset:2048
	ds_read_b128 v[160:163], v160 offset:3072
	ds_read_b128 v[164:167], v175
	ds_read_b128 v[176:179], v175 offset:1024
	ds_read_b128 v[180:183], v175 offset:2048
	ds_read_b128 v[184:187], v175 offset:3072
	s_add_u32 s46, s60, 0x40000
	s_addc_u32 s47, s61, 0
	s_mov_b32 m0, s66
	v_lshl_add_u64 v[228:229], s[46:47], 0, v[138:139]
	ds_read_b128 v[188:191], v174 offset:32768
	ds_read_b128 v[192:195], v174 offset:33792
	ds_read_b128 v[196:199], v174 offset:34816
	ds_read_b128 v[200:203], v174 offset:35840
	ds_read_b128 v[204:207], v174 offset:36864
	ds_read_b128 v[208:211], v174 offset:37888
	ds_read_b128 v[212:215], v174 offset:38912
	ds_read_b128 v[216:219], v174 offset:39936
	global_load_lds_dwordx4 v[228:229], off
	v_lshl_add_u64 v[228:229], s[46:47], 0, v[142:143]
	s_mov_b32 m0, s67
	s_nop 0
	global_load_lds_dwordx4 v[228:229], off
	s_waitcnt vmcnt(8)
	s_waitcnt lgkmcnt(0)
	s_barrier
	s_setprio 1
	s_waitcnt lgkmcnt(0)
	v_mfma_f32_16x16x32_bf16 v[132:135], v[112:115], v[188:191], v[132:135]
	v_mfma_f32_16x16x32_bf16 v[128:131], v[156:159], v[188:191], v[128:131]
	v_mfma_f32_16x16x32_bf16 v[124:127], v[112:115], v[196:199], v[124:127]
	v_mfma_f32_16x16x32_bf16 v[120:123], v[156:159], v[196:199], v[120:123]
	v_mfma_f32_16x16x32_bf16 v[108:111], v[112:115], v[204:207], v[108:111]
	v_mfma_f32_16x16x32_bf16 v[104:107], v[156:159], v[204:207], v[104:107]
	v_mfma_f32_16x16x32_bf16 v[100:103], v[112:115], v[212:215], v[100:103]
	v_mfma_f32_16x16x32_bf16 v[96:99], v[156:159], v[212:215], v[96:99]
	v_mfma_f32_16x16x32_bf16 v[132:135], v[116:119], v[192:195], v[132:135]
	v_mfma_f32_16x16x32_bf16 v[128:131], v[160:163], v[192:195], v[128:131]
	v_mfma_f32_16x16x32_bf16 v[124:127], v[116:119], v[200:203], v[124:127]
	v_mfma_f32_16x16x32_bf16 v[120:123], v[160:163], v[200:203], v[120:123]
	v_mfma_f32_16x16x32_bf16 v[108:111], v[116:119], v[208:211], v[108:111]
	v_mfma_f32_16x16x32_bf16 v[104:107], v[160:163], v[208:211], v[104:107]
	v_mfma_f32_16x16x32_bf16 v[100:103], v[116:119], v[216:219], v[100:103]
	v_mfma_f32_16x16x32_bf16 v[96:99], v[160:163], v[216:219], v[96:99]
	v_mfma_f32_16x16x32_bf16 v[60:63], v[164:167], v[188:191], v[60:63]
	v_mfma_f32_16x16x32_bf16 v[56:59], v[180:183], v[188:191], v[56:59]
	v_mfma_f32_16x16x32_bf16 v[52:55], v[164:167], v[196:199], v[52:55]
	v_mfma_f32_16x16x32_bf16 v[48:51], v[180:183], v[196:199], v[48:51]
	v_mfma_f32_16x16x32_bf16 v[44:47], v[164:167], v[204:207], v[44:47]
	v_mfma_f32_16x16x32_bf16 v[40:43], v[180:183], v[204:207], v[40:43]
	v_mfma_f32_16x16x32_bf16 v[36:39], v[164:167], v[212:215], v[36:39]
	v_mfma_f32_16x16x32_bf16 v[32:35], v[180:183], v[212:215], v[32:35]
	v_mfma_f32_16x16x32_bf16 v[60:63], v[176:179], v[192:195], v[60:63]
	v_mfma_f32_16x16x32_bf16 v[56:59], v[184:187], v[192:195], v[56:59]
	v_mfma_f32_16x16x32_bf16 v[52:55], v[176:179], v[200:203], v[52:55]
	v_mfma_f32_16x16x32_bf16 v[48:51], v[184:187], v[200:203], v[48:51]
	v_mfma_f32_16x16x32_bf16 v[44:47], v[176:179], v[208:211], v[44:47]
	v_mfma_f32_16x16x32_bf16 v[40:43], v[184:187], v[208:211], v[40:43]
	v_mfma_f32_16x16x32_bf16 v[36:39], v[176:179], v[216:219], v[36:39]
	v_mfma_f32_16x16x32_bf16 v[32:35], v[184:187], v[216:219], v[32:35]
	s_setprio 0
	s_barrier
; #define PG8_STAGE(bufoff, gbase, voff) do { _Pragma("unroll") for (int _i = 0; _i < 2; ++_i) \
;         __builtin_amdgcn_global_load_lds((const unsigned*)((const char*)(gbase) + (voff)[_i]), (LAS unsigned*)(lds + (bufoff) + ldsw + _i * 8192), 16, 0, 0); } while (0)
; #define PG8_LDA(dst, b, h) do { _Pragma("unroll") for (int m = 0; m < 4; ++m) _Pragma("unroll") for (int k = 0; k < 2; ++k) dst[m][k] = *(const LAS bf16x8*)(lds + PG8_SA(b, h) + aoff + m * 2048 + k * 1024); } while (0)
; #define PG8_MMA(ai, bj, At, Bt) do { __builtin_amdgcn_s_setprio(1); _Pragma("unroll") for (int m = 0; m < 4; ++m) _Pragma("unroll") for (int n = 0; n < 2; ++n) _Pragma("unroll") for (int k = 0; k < 2; ++k) \
;         acc[ai][bj][m][n] = __builtin_amdgcn_mfma_f32_16x16x32_bf16(Bt[n][k], At[m][k], acc[ai][bj][m][n], 0, 0, 0); __builtin_amdgcn_s_setprio(0); } while (0)
; #define PG8_WAIT_V(n) asm volatile("s_waitcnt vmcnt(" #n ")" ::: "memory")
; #define PG8_WAIT_L(n) asm volatile("s_waitcnt lgkmcnt(" #n ")" ::: "memory")
; #define PG8_BAR __builtin_amdgcn_s_barrier()
; #define PG8_SCHED __builtin_amdgcn_sched_barrier(0)
; template <class Epi, class Sched>
; __device__ __forceinline__ void gemm_phase(LAS unsigned char* lds, const Gemm g, const Sched& S, const Epi& E) {
;     ...
;             PG8_LDA(At, 1, 1); PG8_STAGE(PG8_SB(1, 0), b3, voffB); PG8_STAGE(PG8_SB(1, 1), b3 + hstepB, voffB); PG8_STAGE(PG8_SA(1, 0), a3, voffA);
;             PG8_WAIT_V(8); PG8_WAIT_L(0); PG8_BAR; PG8_MMA(1, 0, At, B0); PG8_MMA(1, 1, At, B1); PG8_BAR; PG8_SCHED;
;         }
;         if (wr == 0) PG8_BAR;
	s_add_i32 s46, s48, s63
	v_lshl_add_u64 v[220:221], v[220:221], 0, s[22:23]
	s_mov_b32 m0, s46
	ds_read_b128 v[188:191], v174 offset:49152
	ds_read_b128 v[192:195], v174 offset:50176
	ds_read_b128 v[196:199], v174 offset:51200
	ds_read_b128 v[200:203], v174 offset:52224
	ds_read_b128 v[204:207], v174 offset:53248
	ds_read_b128 v[208:211], v174 offset:54272
	ds_read_b128 v[212:215], v174 offset:55296
	ds_read_b128 v[216:219], v174 offset:56320
	global_load_lds_dwordx4 v[220:221], off
	s_add_i32 m0, s46, 0x2000
	s_add_u32 s46, s58, 0x40080
	v_lshl_add_u64 v[220:221], v[222:223], 0, s[22:23]
	s_addc_u32 s47, s59, 0
	s_add_i32 s48, s49, s63
	global_load_lds_dwordx4 v[220:221], off
	v_lshl_add_u64 v[220:221], s[46:47], 0, v[140:141]
	s_mov_b32 m0, s48
	s_nop 0
	global_load_lds_dwordx4 v[220:221], off
	v_lshl_add_u64 v[220:221], s[46:47], 0, v[144:145]
	s_add_i32 m0, s48, 0x2000
	s_nop 0
	global_load_lds_dwordx4 v[220:221], off
	v_lshl_add_u64 v[220:221], v[224:225], 0, s[22:23]
	s_mov_b32 m0, s71
	s_nop 0
	global_load_lds_dwordx4 v[220:221], off
	v_lshl_add_u64 v[220:221], v[226:227], 0, s[22:23]
	s_mov_b32 m0, s72
	s_nop 0
	global_load_lds_dwordx4 v[220:221], off
	s_waitcnt vmcnt(8)
	s_waitcnt lgkmcnt(0)
	s_barrier
	s_setprio 1
	s_waitcnt lgkmcnt(0)
	v_mfma_f32_16x16x32_bf16 v[92:95], v[112:115], v[188:191], v[92:95]
	v_mfma_f32_16x16x32_bf16 v[88:91], v[156:159], v[188:191], v[88:91]
	v_mfma_f32_16x16x32_bf16 v[84:87], v[112:115], v[196:199], v[84:87]
	v_mfma_f32_16x16x32_bf16 v[80:83], v[156:159], v[196:199], v[80:83]
	v_mfma_f32_16x16x32_bf16 v[76:79], v[112:115], v[204:207], v[76:79]
	v_mfma_f32_16x16x32_bf16 v[72:75], v[156:159], v[204:207], v[72:75]
	v_mfma_f32_16x16x32_bf16 v[68:71], v[112:115], v[212:215], v[68:71]
	v_mfma_f32_16x16x32_bf16 v[64:67], v[156:159], v[212:215], v[64:67]
	v_mfma_f32_16x16x32_bf16 v[92:95], v[116:119], v[192:195], v[92:95]
	v_mfma_f32_16x16x32_bf16 v[88:91], v[160:163], v[192:195], v[88:91]
	v_mfma_f32_16x16x32_bf16 v[84:87], v[116:119], v[200:203], v[84:87]
	v_mfma_f32_16x16x32_bf16 v[80:83], v[160:163], v[200:203], v[80:83]
	v_mfma_f32_16x16x32_bf16 v[76:79], v[116:119], v[208:211], v[76:79]
	v_mfma_f32_16x16x32_bf16 v[72:75], v[160:163], v[208:211], v[72:75]
	v_mfma_f32_16x16x32_bf16 v[68:71], v[116:119], v[216:219], v[68:71]
	v_mfma_f32_16x16x32_bf16 v[64:67], v[160:163], v[216:219], v[64:67]
	v_mfma_f32_16x16x32_bf16 v[28:31], v[164:167], v[188:191], v[28:31]
	v_mfma_f32_16x16x32_bf16 v[24:27], v[180:183], v[188:191], v[24:27]
	v_mfma_f32_16x16x32_bf16 v[20:23], v[164:167], v[196:199], v[20:23]
	v_mfma_f32_16x16x32_bf16 v[16:19], v[180:183], v[196:199], v[16:19]
	v_mfma_f32_16x16x32_bf16 v[12:15], v[164:167], v[204:207], v[12:15]
	v_mfma_f32_16x16x32_bf16 v[8:11], v[180:183], v[204:207], v[8:11]
	v_mfma_f32_16x16x32_bf16 v[4:7], v[164:167], v[212:215], v[4:7]
	v_mfma_f32_16x16x32_bf16 v[0:3], v[180:183], v[212:215], v[0:3]
	v_mfma_f32_16x16x32_bf16 v[28:31], v[176:179], v[192:195], v[28:31]
	v_mfma_f32_16x16x32_bf16 v[24:27], v[184:187], v[192:195], v[24:27]
	v_mfma_f32_16x16x32_bf16 v[20:23], v[176:179], v[200:203], v[20:23]
	v_mfma_f32_16x16x32_bf16 v[16:19], v[184:187], v[200:203], v[16:19]
	v_mfma_f32_16x16x32_bf16 v[12:15], v[176:179], v[208:211], v[12:15]
	v_mfma_f32_16x16x32_bf16 v[8:11], v[184:187], v[208:211], v[8:11]
	v_mfma_f32_16x16x32_bf16 v[4:7], v[176:179], v[216:219], v[4:7]
	v_mfma_f32_16x16x32_bf16 v[0:3], v[184:187], v[216:219], v[0:3]
	s_setprio 0
	s_barrier
	s_add_i32 s43, s43, 2
	s_add_u32 s56, s56, 0x100
	s_addc_u32 s57, s57, 0
	s_add_u32 s35, s35, 0x100
	s_addc_u32 s41, s41, 0
	s_cmp_gt_u32 s43, 13
	s_cbranch_scc0 .LBB0_602
	s_and_b64 vcc, exec, s[24:25]
	s_cbranch_vccz .LBB0_605
	s_barrier

; #define PG8_STAGE(bufoff, gbase, voff) do { _Pragma("unroll") for (int _i = 0; _i < 2; ++_i) \
;         __builtin_amdgcn_global_load_lds((const unsigned*)((const char*)(gbase) + (voff)[_i]), (LAS unsigned*)(lds + (bufoff) + ldsw + _i * 8192), 16, 0, 0); } while (0)
; #define PG8_LDA(dst, b, h) do { _Pragma("unroll") for (int m = 0; m < 4; ++m) _Pragma("unroll") for (int k = 0; k < 2; ++k) dst[m][k] = *(const LAS bf16x8*)(lds + PG8_SA(b, h) + aoff + m * 2048 + k * 1024); } while (0)
; #define PG8_LDB(dst, b, h) do { _Pragma("unroll") for (int n = 0; n < 2; ++n) _Pragma("unroll") for (int k = 0; k < 2; ++k) dst[n][k] = *(const LAS bf16x8*)(lds + PG8_SB(b, h) + boff + n * 2048 + k * 1024); } while (0)
; #define PG8_MMA(ai, bj, At, Bt) do { __builtin_amdgcn_s_setprio(1); _Pragma("unroll") for (int m = 0; m < 4; ++m) _Pragma("unroll") for (int n = 0; n < 2; ++n) _Pragma("unroll") for (int k = 0; k < 2; ++k) \
;         acc[ai][bj][m][n] = __builtin_amdgcn_mfma_f32_16x16x32_bf16(Bt[n][k], At[m][k], acc[ai][bj][m][n], 0, 0, 0); __builtin_amdgcn_s_setprio(0); } while (0)
; #define PG8_WAIT_V(n) asm volatile("s_waitcnt vmcnt(" #n ")" ::: "memory")
; #define PG8_WAIT_L(n) asm volatile("s_waitcnt lgkmcnt(" #n ")" ::: "memory")
; #define PG8_BAR __builtin_amdgcn_s_barrier()
; #define PG8_SCHED __builtin_amdgcn_sched_barrier(0)
; template <class Epi, class Sched>
; __device__ __forceinline__ void gemm_phase(LAS unsigned char* lds, const Gemm g, const Sched& S, const Epi& E) {
;     ...
;         for (int t = 0; t < nt; t += 2) {
;             const bool last = (t == nt - 2);
;             const char* a1 = cA + (size_t)(t + 1) * kstep;
;             const char* a2 = last ? nA : cA + (size_t)(t + 2) * kstep; const char* b2 = last ? nB : cB + (size_t)(t + 2) * kstep;
;             const char* a3 = a2 + kstep; const char* b3 = b2 + kstep;
;             PG8_LDB(B0, 0, 0); PG8_LDB(B1, 0, 1); PG8_SCHED; PG8_LDA(At, 0, 0); PG8_STAGE(PG8_SA(1, 1), a1 + hstepA, voffA);
;             PG8_WAIT_V(8); PG8_WAIT_L(0); PG8_BAR; PG8_MMA(0, 0, At, B0); PG8_MMA(0, 1, At, B1); PG8_BAR; PG8_SCHED;
;             PG8_LDA(At, 0, 1); PG8_STAGE(PG8_SB(0, 0), b2, voffB); PG8_STAGE(PG8_SB(0, 1), b2 + hstepB, voffB); PG8_STAGE(PG8_SA(0, 0), a2, voffA);
;             PG8_WAIT_V(8); PG8_WAIT_L(0); PG8_BAR; PG8_MMA(1, 0, At, B0); PG8_MMA(1, 1, At, B1); PG8_BAR; PG8_SCHED;
.LBB0_675:
	ds_read_b128 v[160:163], v143
	ds_read_b128 v[164:167], v143 offset:1024
	ds_read_b128 v[168:171], v143 offset:2048
	ds_read_b128 v[172:175], v143 offset:3072
	ds_read_b128 v[176:179], v144
	ds_read_b128 v[180:183], v144 offset:1024
	ds_read_b128 v[184:187], v144 offset:2048
	ds_read_b128 v[188:191], v144 offset:3072
	s_add_u32 s42, s40, 0xddec0080
	s_addc_u32 s43, s41, -1
	s_cmp_lg_u32 s1, 12
	s_cselect_b32 s42, s42, 0
	s_cselect_b32 s43, s43, 0
	s_add_u32 s44, s22, s42
	s_addc_u32 s45, s23, s43
	s_add_u32 s42, s20, s42
	s_addc_u32 s43, s21, s43
	s_mov_b32 m0, s52
	v_lshl_add_u64 v[224:225], v[138:139], 0, s[40:41]
	ds_read_b128 v[192:195], v145
	ds_read_b128 v[196:199], v145 offset:1024
	ds_read_b128 v[200:203], v145 offset:2048
	ds_read_b128 v[204:207], v145 offset:3072
	ds_read_b128 v[208:211], v145 offset:4096
	ds_read_b128 v[212:215], v145 offset:5120
	ds_read_b128 v[216:219], v145 offset:6144
	ds_read_b128 v[220:223], v145 offset:7168
	global_load_lds_dwordx4 v[224:225], off
	v_lshl_add_u64 v[224:225], v[140:141], 0, s[40:41]
	s_mov_b32 m0, s53
	s_nop 0
	global_load_lds_dwordx4 v[224:225], off
	s_waitcnt vmcnt(8)
	s_waitcnt lgkmcnt(0)
	s_barrier
	s_setprio 1
	s_waitcnt lgkmcnt(0)
	v_mfma_f32_16x16x32_bf16 v[132:135], v[160:163], v[192:195], v[132:135]
	v_mfma_f32_16x16x32_bf16 v[128:131], v[168:171], v[192:195], v[128:131]
	v_mfma_f32_16x16x32_bf16 v[124:127], v[160:163], v[200:203], v[124:127]
	v_mfma_f32_16x16x32_bf16 v[120:123], v[168:171], v[200:203], v[120:123]
	v_mfma_f32_16x16x32_bf16 v[108:111], v[160:163], v[208:211], v[108:111]
	v_mfma_f32_16x16x32_bf16 v[104:107], v[168:171], v[208:211], v[104:107]
	v_mfma_f32_16x16x32_bf16 v[100:103], v[160:163], v[216:219], v[100:103]
	v_mfma_f32_16x16x32_bf16 v[96:99], v[168:171], v[216:219], v[96:99]
	v_mfma_f32_16x16x32_bf16 v[132:135], v[164:167], v[196:199], v[132:135]
	v_mfma_f32_16x16x32_bf16 v[128:131], v[172:175], v[196:199], v[128:131]
	v_mfma_f32_16x16x32_bf16 v[124:127], v[164:167], v[204:207], v[124:127]
	v_mfma_f32_16x16x32_bf16 v[120:123], v[172:175], v[204:207], v[120:123]
	v_mfma_f32_16x16x32_bf16 v[108:111], v[164:167], v[212:215], v[108:111]
	v_mfma_f32_16x16x32_bf16 v[104:107], v[172:175], v[212:215], v[104:107]
	v_mfma_f32_16x16x32_bf16 v[100:103], v[164:167], v[220:223], v[100:103]
	v_mfma_f32_16x16x32_bf16 v[96:99], v[172:175], v[220:223], v[96:99]
	v_mfma_f32_16x16x32_bf16 v[60:63], v[176:179], v[192:195], v[60:63]
	v_mfma_f32_16x16x32_bf16 v[56:59], v[184:187], v[192:195], v[56:59]
	v_mfma_f32_16x16x32_bf16 v[52:55], v[176:179], v[200:203], v[52:55]
	v_mfma_f32_16x16x32_bf16 v[48:51], v[184:187], v[200:203], v[48:51]
	v_mfma_f32_16x16x32_bf16 v[44:47], v[176:179], v[208:211], v[44:47]
	v_mfma_f32_16x16x32_bf16 v[40:43], v[184:187], v[208:211], v[40:43]
	v_mfma_f32_16x16x32_bf16 v[36:39], v[176:179], v[216:219], v[36:39]
	v_mfma_f32_16x16x32_bf16 v[32:35], v[184:187], v[216:219], v[32:35]
	v_mfma_f32_16x16x32_bf16 v[60:63], v[180:183], v[196:199], v[60:63]
	v_mfma_f32_16x16x32_bf16 v[56:59], v[188:191], v[196:199], v[56:59]
	v_mfma_f32_16x16x32_bf16 v[52:55], v[180:183], v[204:207], v[52:55]
	v_mfma_f32_16x16x32_bf16 v[48:51], v[188:191], v[204:207], v[48:51]
	v_mfma_f32_16x16x32_bf16 v[44:47], v[180:183], v[212:215], v[44:47]
	v_mfma_f32_16x16x32_bf16 v[40:43], v[188:191], v[212:215], v[40:43]
	v_mfma_f32_16x16x32_bf16 v[36:39], v[180:183], v[220:223], v[36:39]
	v_mfma_f32_16x16x32_bf16 v[32:35], v[188:191], v[220:223], v[32:35]
	s_setprio 0
	s_barrier
	s_mov_b32 m0, s54
	v_lshl_add_u64 v[224:225], s[42:43], 0, v[114:115]
	s_add_u32 s48, s42, 0x40000
	ds_read_b128 v[192:195], v145 offset:16384
	ds_read_b128 v[196:199], v145 offset:17408
	ds_read_b128 v[200:203], v145 offset:18432
	ds_read_b128 v[204:207], v145 offset:19456
	ds_read_b128 v[208:211], v145 offset:20480
	ds_read_b128 v[212:215], v145 offset:21504
	ds_read_b128 v[216:219], v145 offset:22528
	ds_read_b128 v[220:223], v145 offset:23552
	global_load_lds_dwordx4 v[224:225], off
	v_lshl_add_u64 v[226:227], s[42:43], 0, v[118:119]
	s_mov_b32 m0, s55
	s_addc_u32 s49, s43, 0
	global_load_lds_dwordx4 v[226:227], off
	v_lshl_add_u64 v[228:229], s[48:49], 0, v[114:115]
	s_mov_b32 m0, s56
	v_lshl_add_u64 v[230:231], s[44:45], 0, v[116:117]
	global_load_lds_dwordx4 v[228:229], off
	v_lshl_add_u64 v[228:229], s[48:49], 0, v[118:119]
	s_mov_b32 m0, s57
	s_nop 0
	global_load_lds_dwordx4 v[228:229], off
	v_lshl_add_u64 v[228:229], s[44:45], 0, v[112:113]
	s_mov_b32 m0, s5
	s_nop 0
	global_load_lds_dwordx4 v[228:229], off
	s_mov_b32 m0, s7
	s_nop 0
	global_load_lds_dwordx4 v[230:231], off
	s_waitcnt vmcnt(8)
	s_waitcnt lgkmcnt(0)
	s_barrier
; #define PG8_STAGE(bufoff, gbase, voff) do { _Pragma("unroll") for (int _i = 0; _i < 2; ++_i) \
;         __builtin_amdgcn_global_load_lds((const unsigned*)((const char*)(gbase) + (voff)[_i]), (LAS unsigned*)(lds + (bufoff) + ldsw + _i * 8192), 16, 0, 0); } while (0)
; #define PG8_LDA(dst, b, h) do { _Pragma("unroll") for (int m = 0; m < 4; ++m) _Pragma("unroll") for (int k = 0; k < 2; ++k) dst[m][k] = *(const LAS bf16x8*)(lds + PG8_SA(b, h) + aoff + m * 2048 + k * 1024); } while (0)
; #define PG8_LDB(dst, b, h) do { _Pragma("unroll") for (int n = 0; n < 2; ++n) _Pragma("unroll") for (int k = 0; k < 2; ++k) dst[n][k] = *(const LAS bf16x8*)(lds + PG8_SB(b, h) + boff + n * 2048 + k * 1024); } while (0)
; #define PG8_MMA(ai, bj, At, Bt) do { __builtin_amdgcn_s_setprio(1); _Pragma("unroll") for (int m = 0; m < 4; ++m) _Pragma("unroll") for (int n = 0; n < 2; ++n) _Pragma("unroll") for (int k = 0; k < 2; ++k) \
;         acc[ai][bj][m][n] = __builtin_amdgcn_mfma_f32_16x16x32_bf16(Bt[n][k], At[m][k], acc[ai][bj][m][n], 0, 0, 0); __builtin_amdgcn_s_setprio(0); } while (0)
; #define PG8_WAIT_V(n) asm volatile("s_waitcnt vmcnt(" #n ")" ::: "memory")
; #define PG8_WAIT_L(n) asm volatile("s_waitcnt lgkmcnt(" #n ")" ::: "memory")
; #define PG8_BAR __builtin_amdgcn_s_barrier()
; #define PG8_SCHED __builtin_amdgcn_sched_barrier(0)
; template <class Epi, class Sched>
; __device__ __forceinline__ void gemm_phase(LAS unsigned char* lds, const Gemm g, const Sched& S, const Epi& E) {
;     ...
;             PG8_WAIT_V(8); PG8_WAIT_L(0); PG8_BAR; PG8_MMA(1, 0, At, B0); PG8_MMA(1, 1, At, B1); PG8_BAR; PG8_SCHED;
;             PG8_LDB(B0, 1, 0); PG8_LDB(B1, 1, 1); PG8_SCHED; PG8_LDA(At, 1, 0); PG8_STAGE(PG8_SA(0, 1), a2 + hstepA, voffA);
;             PG8_WAIT_V(8); PG8_WAIT_L(0); PG8_BAR; PG8_MMA(0, 0, At, B0); PG8_MMA(0, 1, At, B1); PG8_BAR; PG8_SCHED;
	s_setprio 1
	s_waitcnt lgkmcnt(0)
	v_mfma_f32_16x16x32_bf16 v[92:95], v[160:163], v[192:195], v[92:95]
	v_mfma_f32_16x16x32_bf16 v[88:91], v[168:171], v[192:195], v[88:91]
	v_mfma_f32_16x16x32_bf16 v[84:87], v[160:163], v[200:203], v[84:87]
	v_mfma_f32_16x16x32_bf16 v[80:83], v[168:171], v[200:203], v[80:83]
	v_mfma_f32_16x16x32_bf16 v[76:79], v[160:163], v[208:211], v[76:79]
	v_mfma_f32_16x16x32_bf16 v[72:75], v[168:171], v[208:211], v[72:75]
	v_mfma_f32_16x16x32_bf16 v[68:71], v[160:163], v[216:219], v[68:71]
	v_mfma_f32_16x16x32_bf16 v[64:67], v[168:171], v[216:219], v[64:67]
	v_mfma_f32_16x16x32_bf16 v[92:95], v[164:167], v[196:199], v[92:95]
	v_mfma_f32_16x16x32_bf16 v[88:91], v[172:175], v[196:199], v[88:91]
	v_mfma_f32_16x16x32_bf16 v[84:87], v[164:167], v[204:207], v[84:87]
	v_mfma_f32_16x16x32_bf16 v[80:83], v[172:175], v[204:207], v[80:83]
	v_mfma_f32_16x16x32_bf16 v[76:79], v[164:167], v[212:215], v[76:79]
	v_mfma_f32_16x16x32_bf16 v[72:75], v[172:175], v[212:215], v[72:75]
	v_mfma_f32_16x16x32_bf16 v[68:71], v[164:167], v[220:223], v[68:71]
	v_mfma_f32_16x16x32_bf16 v[64:67], v[172:175], v[220:223], v[64:67]
	v_mfma_f32_16x16x32_bf16 v[28:31], v[176:179], v[192:195], v[28:31]
	v_mfma_f32_16x16x32_bf16 v[24:27], v[184:187], v[192:195], v[24:27]
	v_mfma_f32_16x16x32_bf16 v[20:23], v[176:179], v[200:203], v[20:23]
	v_mfma_f32_16x16x32_bf16 v[16:19], v[184:187], v[200:203], v[16:19]
	v_mfma_f32_16x16x32_bf16 v[12:15], v[176:179], v[208:211], v[12:15]
	v_mfma_f32_16x16x32_bf16 v[8:11], v[184:187], v[208:211], v[8:11]
	v_mfma_f32_16x16x32_bf16 v[4:7], v[176:179], v[216:219], v[4:7]
	v_mfma_f32_16x16x32_bf16 v[0:3], v[184:187], v[216:219], v[0:3]
	v_mfma_f32_16x16x32_bf16 v[28:31], v[180:183], v[196:199], v[28:31]
	v_mfma_f32_16x16x32_bf16 v[24:27], v[188:191], v[196:199], v[24:27]
	v_mfma_f32_16x16x32_bf16 v[20:23], v[180:183], v[204:207], v[20:23]
	v_mfma_f32_16x16x32_bf16 v[16:19], v[188:191], v[204:207], v[16:19]
	v_mfma_f32_16x16x32_bf16 v[12:15], v[180:183], v[212:215], v[12:15]
	v_mfma_f32_16x16x32_bf16 v[8:11], v[188:191], v[212:215], v[8:11]
	v_mfma_f32_16x16x32_bf16 v[4:7], v[180:183], v[220:223], v[4:7]
	v_mfma_f32_16x16x32_bf16 v[0:3], v[188:191], v[220:223], v[0:3]
	s_setprio 0
	s_barrier
	ds_read_b128 v[160:163], v146
	ds_read_b128 v[164:167], v146 offset:1024
	ds_read_b128 v[168:171], v146 offset:2048
	ds_read_b128 v[172:175], v146 offset:3072
	ds_read_b128 v[176:179], v147
	ds_read_b128 v[180:183], v147 offset:1024
	ds_read_b128 v[184:187], v147 offset:2048
	ds_read_b128 v[188:191], v147 offset:3072
	s_add_u32 s44, s44, 0x40000
	s_addc_u32 s45, s45, 0
	s_mov_b32 m0, s33
	v_lshl_add_u64 v[232:233], s[44:45], 0, v[112:113]
	ds_read_b128 v[192:195], v145 offset:32768
	ds_read_b128 v[196:199], v145 offset:33792
	ds_read_b128 v[200:203], v145 offset:34816
	ds_read_b128 v[204:207], v145 offset:35840
	ds_read_b128 v[208:211], v145 offset:36864
	ds_read_b128 v[212:215], v145 offset:37888
	ds_read_b128 v[216:219], v145 offset:38912
	ds_read_b128 v[220:223], v145 offset:39936
	global_load_lds_dwordx4 v[232:233], off
	v_lshl_add_u64 v[232:233], s[44:45], 0, v[116:117]
	s_mov_b32 m0, s34
	s_nop 0
	global_load_lds_dwordx4 v[232:233], off
	s_waitcnt vmcnt(8)
	s_waitcnt lgkmcnt(0)
	s_barrier
	s_setprio 1
	s_waitcnt lgkmcnt(0)
	v_mfma_f32_16x16x32_bf16 v[132:135], v[160:163], v[192:195], v[132:135]
	v_mfma_f32_16x16x32_bf16 v[128:131], v[168:171], v[192:195], v[128:131]
	v_mfma_f32_16x16x32_bf16 v[124:127], v[160:163], v[200:203], v[124:127]
	v_mfma_f32_16x16x32_bf16 v[120:123], v[168:171], v[200:203], v[120:123]
	v_mfma_f32_16x16x32_bf16 v[108:111], v[160:163], v[208:211], v[108:111]
	v_mfma_f32_16x16x32_bf16 v[104:107], v[168:171], v[208:211], v[104:107]
	v_mfma_f32_16x16x32_bf16 v[100:103], v[160:163], v[216:219], v[100:103]
	v_mfma_f32_16x16x32_bf16 v[96:99], v[168:171], v[216:219], v[96:99]
	v_mfma_f32_16x16x32_bf16 v[132:135], v[164:167], v[196:199], v[132:135]
	v_mfma_f32_16x16x32_bf16 v[128:131], v[172:175], v[196:199], v[128:131]
	v_mfma_f32_16x16x32_bf16 v[124:127], v[164:167], v[204:207], v[124:127]
	v_mfma_f32_16x16x32_bf16 v[120:123], v[172:175], v[204:207], v[120:123]
	v_mfma_f32_16x16x32_bf16 v[108:111], v[164:167], v[212:215], v[108:111]
	v_mfma_f32_16x16x32_bf16 v[104:107], v[172:175], v[212:215], v[104:107]
	v_mfma_f32_16x16x32_bf16 v[100:103], v[164:167], v[220:223], v[100:103]
	v_mfma_f32_16x16x32_bf16 v[96:99], v[172:175], v[220:223], v[96:99]
	v_mfma_f32_16x16x32_bf16 v[60:63], v[176:179], v[192:195], v[60:63]
	v_mfma_f32_16x16x32_bf16 v[56:59], v[184:187], v[192:195], v[56:59]
	v_mfma_f32_16x16x32_bf16 v[52:55], v[176:179], v[200:203], v[52:55]
	v_mfma_f32_16x16x32_bf16 v[48:51], v[184:187], v[200:203], v[48:51]
	v_mfma_f32_16x16x32_bf16 v[44:47], v[176:179], v[208:211], v[44:47]
	v_mfma_f32_16x16x32_bf16 v[40:43], v[184:187], v[208:211], v[40:43]
	v_mfma_f32_16x16x32_bf16 v[36:39], v[176:179], v[216:219], v[36:39]
	v_mfma_f32_16x16x32_bf16 v[32:35], v[184:187], v[216:219], v[32:35]
	v_mfma_f32_16x16x32_bf16 v[60:63], v[180:183], v[196:199], v[60:63]
	v_mfma_f32_16x16x32_bf16 v[56:59], v[188:191], v[196:199], v[56:59]
	v_mfma_f32_16x16x32_bf16 v[52:55], v[180:183], v[204:207], v[52:55]
	v_mfma_f32_16x16x32_bf16 v[48:51], v[188:191], v[204:207], v[48:51]
	v_mfma_f32_16x16x32_bf16 v[44:47], v[180:183], v[212:215], v[44:47]
	v_mfma_f32_16x16x32_bf16 v[40:43], v[188:191], v[212:215], v[40:43]
	v_mfma_f32_16x16x32_bf16 v[36:39], v[180:183], v[220:223], v[36:39]
	v_mfma_f32_16x16x32_bf16 v[32:35], v[188:191], v[220:223], v[32:35]
	s_setprio 0
	s_barrier
; #define PG8_STAGE(bufoff, gbase, voff) do { _Pragma("unroll") for (int _i = 0; _i < 2; ++_i) \
;         __builtin_amdgcn_global_load_lds((const unsigned*)((const char*)(gbase) + (voff)[_i]), (LAS unsigned*)(lds + (bufoff) + ldsw + _i * 8192), 16, 0, 0); } while (0)
; #define PG8_LDA(dst, b, h) do { _Pragma("unroll") for (int m = 0; m < 4; ++m) _Pragma("unroll") for (int k = 0; k < 2; ++k) dst[m][k] = *(const LAS bf16x8*)(lds + PG8_SA(b, h) + aoff + m * 2048 + k * 1024); } while (0)
; #define PG8_MMA(ai, bj, At, Bt) do { __builtin_amdgcn_s_setprio(1); _Pragma("unroll") for (int m = 0; m < 4; ++m) _Pragma("unroll") for (int n = 0; n < 2; ++n) _Pragma("unroll") for (int k = 0; k < 2; ++k) \
;         acc[ai][bj][m][n] = __builtin_amdgcn_mfma_f32_16x16x32_bf16(Bt[n][k], At[m][k], acc[ai][bj][m][n], 0, 0, 0); __builtin_amdgcn_s_setprio(0); } while (0)
; #define PG8_WAIT_V(n) asm volatile("s_waitcnt vmcnt(" #n ")" ::: "memory")
; #define PG8_WAIT_L(n) asm volatile("s_waitcnt lgkmcnt(" #n ")" ::: "memory")
; #define PG8_BAR __builtin_amdgcn_s_barrier()
; #define PG8_SCHED __builtin_amdgcn_sched_barrier(0)
; template <class Epi, class Sched>
; __device__ __forceinline__ void gemm_phase(LAS unsigned char* lds, const Gemm g, const Sched& S, const Epi& E) {
;     ...
;             PG8_LDA(At, 1, 1); PG8_STAGE(PG8_SB(1, 0), b3, voffB); PG8_STAGE(PG8_SB(1, 1), b3 + hstepB, voffB); PG8_STAGE(PG8_SA(1, 0), a3, voffA);
;             PG8_WAIT_V(8); PG8_WAIT_L(0); PG8_BAR; PG8_MMA(1, 0, At, B0); PG8_MMA(1, 1, At, B1); PG8_BAR; PG8_SCHED;
;         }
;         if (wr == 0) PG8_BAR;
	s_mov_b32 m0, s58
	v_lshl_add_u64 v[224:225], v[224:225], 0, s[24:25]
	s_add_u32 s42, s42, 0x40080
	ds_read_b128 v[192:195], v145 offset:49152
	ds_read_b128 v[196:199], v145 offset:50176
	ds_read_b128 v[200:203], v145 offset:51200
	ds_read_b128 v[204:207], v145 offset:52224
	ds_read_b128 v[208:211], v145 offset:53248
	ds_read_b128 v[212:215], v145 offset:54272
	ds_read_b128 v[216:219], v145 offset:55296
	ds_read_b128 v[220:223], v145 offset:56320
	global_load_lds_dwordx4 v[224:225], off
	v_lshl_add_u64 v[224:225], v[226:227], 0, s[24:25]
	s_mov_b32 m0, s59
	s_addc_u32 s43, s43, 0
	global_load_lds_dwordx4 v[224:225], off
	v_lshl_add_u64 v[224:225], s[42:43], 0, v[114:115]
	s_mov_b32 m0, s60
	s_nop 0
	global_load_lds_dwordx4 v[224:225], off
	v_lshl_add_u64 v[224:225], s[42:43], 0, v[118:119]
	s_mov_b32 m0, s61
	s_nop 0
	global_load_lds_dwordx4 v[224:225], off
	v_lshl_add_u64 v[224:225], v[228:229], 0, s[24:25]
	s_mov_b32 m0, s46
	s_nop 0
	global_load_lds_dwordx4 v[224:225], off
	v_lshl_add_u64 v[224:225], v[230:231], 0, s[24:25]
	s_mov_b32 m0, s47
	s_nop 0
	global_load_lds_dwordx4 v[224:225], off
	s_waitcnt vmcnt(8)
	s_waitcnt lgkmcnt(0)
	s_barrier
	s_setprio 1
	s_waitcnt lgkmcnt(0)
	v_mfma_f32_16x16x32_bf16 v[92:95], v[160:163], v[192:195], v[92:95]
	v_mfma_f32_16x16x32_bf16 v[88:91], v[168:171], v[192:195], v[88:91]
	v_mfma_f32_16x16x32_bf16 v[84:87], v[160:163], v[200:203], v[84:87]
	v_mfma_f32_16x16x32_bf16 v[80:83], v[168:171], v[200:203], v[80:83]
	v_mfma_f32_16x16x32_bf16 v[76:79], v[160:163], v[208:211], v[76:79]
	v_mfma_f32_16x16x32_bf16 v[72:75], v[168:171], v[208:211], v[72:75]
	v_mfma_f32_16x16x32_bf16 v[68:71], v[160:163], v[216:219], v[68:71]
	v_mfma_f32_16x16x32_bf16 v[64:67], v[168:171], v[216:219], v[64:67]
	v_mfma_f32_16x16x32_bf16 v[92:95], v[164:167], v[196:199], v[92:95]
	v_mfma_f32_16x16x32_bf16 v[88:91], v[172:175], v[196:199], v[88:91]
	v_mfma_f32_16x16x32_bf16 v[84:87], v[164:167], v[204:207], v[84:87]
	v_mfma_f32_16x16x32_bf16 v[80:83], v[172:175], v[204:207], v[80:83]
	v_mfma_f32_16x16x32_bf16 v[76:79], v[164:167], v[212:215], v[76:79]
	v_mfma_f32_16x16x32_bf16 v[72:75], v[172:175], v[212:215], v[72:75]
	v_mfma_f32_16x16x32_bf16 v[68:71], v[164:167], v[220:223], v[68:71]
	v_mfma_f32_16x16x32_bf16 v[64:67], v[172:175], v[220:223], v[64:67]
	v_mfma_f32_16x16x32_bf16 v[28:31], v[176:179], v[192:195], v[28:31]
	v_mfma_f32_16x16x32_bf16 v[24:27], v[184:187], v[192:195], v[24:27]
	v_mfma_f32_16x16x32_bf16 v[20:23], v[176:179], v[200:203], v[20:23]
	v_mfma_f32_16x16x32_bf16 v[16:19], v[184:187], v[200:203], v[16:19]
	v_mfma_f32_16x16x32_bf16 v[12:15], v[176:179], v[208:211], v[12:15]
	v_mfma_f32_16x16x32_bf16 v[8:11], v[184:187], v[208:211], v[8:11]
	v_mfma_f32_16x16x32_bf16 v[4:7], v[176:179], v[216:219], v[4:7]
	v_mfma_f32_16x16x32_bf16 v[0:3], v[184:187], v[216:219], v[0:3]
	v_mfma_f32_16x16x32_bf16 v[28:31], v[180:183], v[196:199], v[28:31]
	v_mfma_f32_16x16x32_bf16 v[24:27], v[188:191], v[196:199], v[24:27]
	v_mfma_f32_16x16x32_bf16 v[20:23], v[180:183], v[204:207], v[20:23]
	v_mfma_f32_16x16x32_bf16 v[16:19], v[188:191], v[204:207], v[16:19]
	v_mfma_f32_16x16x32_bf16 v[12:15], v[180:183], v[212:215], v[12:15]
	v_mfma_f32_16x16x32_bf16 v[8:11], v[188:191], v[212:215], v[8:11]
	v_mfma_f32_16x16x32_bf16 v[4:7], v[180:183], v[220:223], v[4:7]
	v_mfma_f32_16x16x32_bf16 v[0:3], v[188:191], v[220:223], v[0:3]
	s_setprio 0
	s_barrier
	s_add_i32 s1, s1, 2
	s_add_u32 s40, s40, 0x100
	s_addc_u32 s41, s41, 0
	s_cmp_gt_u32 s1, 13
	s_cbranch_scc0 .LBB0_675
	s_cmpk_lt_u32 s4, 0x100
	s_cbranch_scc0 .LBB0_678
	s_barrier

; #define PG8_STAGE(bufoff, gbase, voff) do { _Pragma("unroll") for (int _i = 0; _i < 2; ++_i) \
;         __builtin_amdgcn_global_load_lds((const unsigned*)((const char*)(gbase) + (voff)[_i]), (LAS unsigned*)(lds + (bufoff) + ldsw + _i * 8192), 16, 0, 0); } while (0)
; #define PG8_LDA(dst, b, h) do { _Pragma("unroll") for (int m = 0; m < 4; ++m) _Pragma("unroll") for (int k = 0; k < 2; ++k) dst[m][k] = *(const LAS bf16x8*)(lds + PG8_SA(b, h) + aoff + m * 2048 + k * 1024); } while (0)
; #define PG8_LDB(dst, b, h) do { _Pragma("unroll") for (int n = 0; n < 2; ++n) _Pragma("unroll") for (int k = 0; k < 2; ++k) dst[n][k] = *(const LAS bf16x8*)(lds + PG8_SB(b, h) + boff + n * 2048 + k * 1024); } while (0)
; #define PG8_MMA(ai, bj, At, Bt) do { __builtin_amdgcn_s_setprio(1); _Pragma("unroll") for (int m = 0; m < 4; ++m) _Pragma("unroll") for (int n = 0; n < 2; ++n) _Pragma("unroll") for (int k = 0; k < 2; ++k) \
;         acc[ai][bj][m][n] = __builtin_amdgcn_mfma_f32_16x16x32_bf16(Bt[n][k], At[m][k], acc[ai][bj][m][n], 0, 0, 0); __builtin_amdgcn_s_setprio(0); } while (0)
; #define PG8_WAIT_V(n) asm volatile("s_waitcnt vmcnt(" #n ")" ::: "memory")
; #define PG8_WAIT_L(n) asm volatile("s_waitcnt lgkmcnt(" #n ")" ::: "memory")
; #define PG8_BAR __builtin_amdgcn_s_barrier()
; #define PG8_SCHED __builtin_amdgcn_sched_barrier(0)
; template <class Epi, class Sched>
; __device__ __forceinline__ void gemm_phase(LAS unsigned char* lds, const Gemm g, const Sched& S, const Epi& E) {
;     ...
;         for (int t = 0; t < nt; t += 2) {
;             const bool last = (t == nt - 2);
;             const char* a1 = cA + (size_t)(t + 1) * kstep;
;             const char* a2 = last ? nA : cA + (size_t)(t + 2) * kstep; const char* b2 = last ? nB : cB + (size_t)(t + 2) * kstep;
;             const char* a3 = a2 + kstep; const char* b3 = b2 + kstep;
;             PG8_LDB(B0, 0, 0); PG8_LDB(B1, 0, 1); PG8_SCHED; PG8_LDA(At, 0, 0); PG8_STAGE(PG8_SA(1, 1), a1 + hstepA, voffA);
;             PG8_WAIT_V(8); PG8_WAIT_L(0); PG8_BAR; PG8_MMA(0, 0, At, B0); PG8_MMA(0, 1, At, B1); PG8_BAR; PG8_SCHED;
;             PG8_LDA(At, 0, 1); PG8_STAGE(PG8_SB(0, 0), b2, voffB); PG8_STAGE(PG8_SB(0, 1), b2 + hstepB, voffB); PG8_STAGE(PG8_SA(0, 0), a2, voffA);
;             PG8_WAIT_V(8); PG8_WAIT_L(0); PG8_BAR; PG8_MMA(1, 0, At, B0); PG8_MMA(1, 1, At, B1); PG8_BAR; PG8_SCHED;
.Ledge_p6:
.LBB0_724:
	s_add_u32 s48, s62, 0xfff80080
	s_addc_u32 s49, s63, -1
	s_add_i32 s83, 0, 0x10000
	s_cmp_eq_u32 s75, 28
	s_cselect_b32 s67, s2, s49
	s_cselect_b32 s66, s34, s48
	v_add_u32_e32 v161, s83, v159
	s_cselect_b32 s65, s35, s53
	s_cselect_b32 s64, s39, s45
	s_add_i32 s84, 0, 0x14000
	ds_read_b128 v[146:149], v161
	ds_read_b128 v[162:165], v161 offset:1024
	ds_read_b128 v[166:169], v161 offset:2048
	ds_read_b128 v[170:173], v161 offset:3072
	v_add_u32_e32 v161, s84, v159
	ds_read_b128 v[174:177], v161
	ds_read_b128 v[178:181], v161 offset:1024
	ds_read_b128 v[182:185], v161 offset:2048
	ds_read_b128 v[186:189], v161 offset:3072
	v_lshl_add_u64 v[222:223], s[62:63], 0, v[138:139]
	s_add_i32 m0, s61, 0xc000
	ds_read_b128 v[190:193], v160
	ds_read_b128 v[194:197], v160 offset:1024
	ds_read_b128 v[198:201], v160 offset:2048
	ds_read_b128 v[202:205], v160 offset:3072
	ds_read_b128 v[206:209], v160 offset:4096
	ds_read_b128 v[210:213], v160 offset:5120
	ds_read_b128 v[214:217], v160 offset:6144
	ds_read_b128 v[218:221], v160 offset:7168
	global_load_lds_dwordx4 v[222:223], off
	v_lshl_add_u64 v[222:223], s[62:63], 0, v[140:141]
	s_add_i32 m0, s61, 0xe000
	s_nop 0
	global_load_lds_dwordx4 v[222:223], off
	s_waitcnt vmcnt(8)
	s_waitcnt lgkmcnt(0)
	s_barrier
	s_setprio 1
	s_waitcnt lgkmcnt(0)
	v_mfma_f32_16x16x32_bf16 v[124:127], v[146:149], v[190:193], v[124:127]
	v_mfma_f32_16x16x32_bf16 v[120:123], v[166:169], v[190:193], v[120:123]
	v_mfma_f32_16x16x32_bf16 v[108:111], v[146:149], v[198:201], v[108:111]
	v_mfma_f32_16x16x32_bf16 v[104:107], v[166:169], v[198:201], v[104:107]
	v_mfma_f32_16x16x32_bf16 v[92:95], v[146:149], v[206:209], v[92:95]
	v_mfma_f32_16x16x32_bf16 v[88:91], v[166:169], v[206:209], v[88:91]
	v_mfma_f32_16x16x32_bf16 v[76:79], v[146:149], v[214:217], v[76:79]
	v_mfma_f32_16x16x32_bf16 v[72:75], v[166:169], v[214:217], v[72:75]
	v_mfma_f32_16x16x32_bf16 v[124:127], v[162:165], v[194:197], v[124:127]
	v_mfma_f32_16x16x32_bf16 v[120:123], v[170:173], v[194:197], v[120:123]
	v_mfma_f32_16x16x32_bf16 v[108:111], v[162:165], v[202:205], v[108:111]
	v_mfma_f32_16x16x32_bf16 v[104:107], v[170:173], v[202:205], v[104:107]
	v_mfma_f32_16x16x32_bf16 v[92:95], v[162:165], v[210:213], v[92:95]
	v_mfma_f32_16x16x32_bf16 v[88:91], v[170:173], v[210:213], v[88:91]
	v_mfma_f32_16x16x32_bf16 v[76:79], v[162:165], v[218:221], v[76:79]
	v_mfma_f32_16x16x32_bf16 v[72:75], v[170:173], v[218:221], v[72:75]
	v_mfma_f32_16x16x32_bf16 v[116:119], v[174:177], v[190:193], v[116:119]
	v_mfma_f32_16x16x32_bf16 v[112:115], v[182:185], v[190:193], v[112:115]
	v_mfma_f32_16x16x32_bf16 v[100:103], v[174:177], v[198:201], v[100:103]
	v_mfma_f32_16x16x32_bf16 v[96:99], v[182:185], v[198:201], v[96:99]
	v_mfma_f32_16x16x32_bf16 v[84:87], v[174:177], v[206:209], v[84:87]
	v_mfma_f32_16x16x32_bf16 v[80:83], v[182:185], v[206:209], v[80:83]
	v_mfma_f32_16x16x32_bf16 v[68:71], v[174:177], v[214:217], v[68:71]
	v_mfma_f32_16x16x32_bf16 v[64:67], v[182:185], v[214:217], v[64:67]
	v_mfma_f32_16x16x32_bf16 v[116:119], v[178:181], v[194:197], v[116:119]
	v_mfma_f32_16x16x32_bf16 v[112:115], v[186:189], v[194:197], v[112:115]
	v_mfma_f32_16x16x32_bf16 v[100:103], v[178:181], v[202:205], v[100:103]
	v_mfma_f32_16x16x32_bf16 v[96:99], v[186:189], v[202:205], v[96:99]
	v_mfma_f32_16x16x32_bf16 v[84:87], v[178:181], v[210:213], v[84:87]
	v_mfma_f32_16x16x32_bf16 v[80:83], v[186:189], v[210:213], v[80:83]
	v_mfma_f32_16x16x32_bf16 v[68:71], v[178:181], v[218:221], v[68:71]
	v_mfma_f32_16x16x32_bf16 v[64:67], v[186:189], v[218:221], v[64:67]
	s_setprio 0
	s_barrier
	s_add_i32 s48, s83, s76
	v_lshl_add_u64 v[222:223], s[64:65], 0, v[130:131]
	s_mov_b32 m0, s48
	ds_read_b128 v[190:193], v160 offset:16384
	ds_read_b128 v[194:197], v160 offset:17408
	ds_read_b128 v[198:201], v160 offset:18432
	ds_read_b128 v[202:205], v160 offset:19456
	ds_read_b128 v[206:209], v160 offset:20480
	ds_read_b128 v[210:213], v160 offset:21504
	ds_read_b128 v[214:217], v160 offset:22528
	ds_read_b128 v[218:221], v160 offset:23552
	global_load_lds_dwordx4 v[222:223], off
	s_add_i32 m0, s48, 0x2000
	s_add_u32 s48, s64, 0x80000
	v_lshl_add_u64 v[224:225], s[64:65], 0, v[134:135]
	s_addc_u32 s49, s65, 0
	s_add_i32 s83, s84, s76
	global_load_lds_dwordx4 v[224:225], off
	v_lshl_add_u64 v[226:227], s[48:49], 0, v[130:131]
	s_mov_b32 m0, s83
	v_lshl_add_u64 v[228:229], s[66:67], 0, v[132:133]
	global_load_lds_dwordx4 v[226:227], off
	v_lshl_add_u64 v[226:227], s[48:49], 0, v[134:135]
	s_add_i32 m0, s83, 0x2000
	s_nop 0
	global_load_lds_dwordx4 v[226:227], off
	v_lshl_add_u64 v[226:227], s[66:67], 0, v[128:129]
	s_mov_b32 m0, s61
	s_nop 0
	global_load_lds_dwordx4 v[226:227], off
	s_mov_b32 m0, s77
	s_nop 0
	global_load_lds_dwordx4 v[228:229], off
	s_waitcnt vmcnt(8)
	s_waitcnt lgkmcnt(0)
	s_barrier
; #define PG8_STAGE(bufoff, gbase, voff) do { _Pragma("unroll") for (int _i = 0; _i < 2; ++_i) \
;         __builtin_amdgcn_global_load_lds((const unsigned*)((const char*)(gbase) + (voff)[_i]), (LAS unsigned*)(lds + (bufoff) + ldsw + _i * 8192), 16, 0, 0); } while (0)
; #define PG8_LDA(dst, b, h) do { _Pragma("unroll") for (int m = 0; m < 4; ++m) _Pragma("unroll") for (int k = 0; k < 2; ++k) dst[m][k] = *(const LAS bf16x8*)(lds + PG8_SA(b, h) + aoff + m * 2048 + k * 1024); } while (0)
; #define PG8_LDB(dst, b, h) do { _Pragma("unroll") for (int n = 0; n < 2; ++n) _Pragma("unroll") for (int k = 0; k < 2; ++k) dst[n][k] = *(const LAS bf16x8*)(lds + PG8_SB(b, h) + boff + n * 2048 + k * 1024); } while (0)
; #define PG8_MMA(ai, bj, At, Bt) do { __builtin_amdgcn_s_setprio(1); _Pragma("unroll") for (int m = 0; m < 4; ++m) _Pragma("unroll") for (int n = 0; n < 2; ++n) _Pragma("unroll") for (int k = 0; k < 2; ++k) \
;         acc[ai][bj][m][n] = __builtin_amdgcn_mfma_f32_16x16x32_bf16(Bt[n][k], At[m][k], acc[ai][bj][m][n], 0, 0, 0); __builtin_amdgcn_s_setprio(0); } while (0)
; #define PG8_WAIT_V(n) asm volatile("s_waitcnt vmcnt(" #n ")" ::: "memory")
; #define PG8_WAIT_L(n) asm volatile("s_waitcnt lgkmcnt(" #n ")" ::: "memory")
; #define PG8_BAR __builtin_amdgcn_s_barrier()
; #define PG8_SCHED __builtin_amdgcn_sched_barrier(0)
; template <class Epi, class Sched>
; __device__ __forceinline__ void gemm_phase(LAS unsigned char* lds, const Gemm g, const Sched& S, const Epi& E) {
;     ...
;             PG8_WAIT_V(8); PG8_WAIT_L(0); PG8_BAR; PG8_MMA(1, 0, At, B0); PG8_MMA(1, 1, At, B1); PG8_BAR; PG8_SCHED;
;             PG8_LDB(B0, 1, 0); PG8_LDB(B1, 1, 1); PG8_SCHED; PG8_LDA(At, 1, 0); PG8_STAGE(PG8_SA(0, 1), a2 + hstepA, voffA);
;             PG8_WAIT_V(8); PG8_WAIT_L(0); PG8_BAR; PG8_MMA(0, 0, At, B0); PG8_MMA(0, 1, At, B1); PG8_BAR; PG8_SCHED;
	s_setprio 1
	s_waitcnt lgkmcnt(0)
	v_mfma_f32_16x16x32_bf16 v[60:63], v[146:149], v[190:193], v[60:63]
	v_mfma_f32_16x16x32_bf16 v[56:59], v[166:169], v[190:193], v[56:59]
	v_mfma_f32_16x16x32_bf16 v[44:47], v[146:149], v[198:201], v[44:47]
	v_mfma_f32_16x16x32_bf16 v[40:43], v[166:169], v[198:201], v[40:43]
	v_mfma_f32_16x16x32_bf16 v[28:31], v[146:149], v[206:209], v[28:31]
	v_mfma_f32_16x16x32_bf16 v[24:27], v[166:169], v[206:209], v[24:27]
	v_mfma_f32_16x16x32_bf16 v[12:15], v[146:149], v[214:217], v[12:15]
	v_mfma_f32_16x16x32_bf16 v[8:11], v[166:169], v[214:217], v[8:11]
	v_mfma_f32_16x16x32_bf16 v[60:63], v[162:165], v[194:197], v[60:63]
	v_mfma_f32_16x16x32_bf16 v[56:59], v[170:173], v[194:197], v[56:59]
	v_mfma_f32_16x16x32_bf16 v[44:47], v[162:165], v[202:205], v[44:47]
	v_mfma_f32_16x16x32_bf16 v[40:43], v[170:173], v[202:205], v[40:43]
	v_mfma_f32_16x16x32_bf16 v[28:31], v[162:165], v[210:213], v[28:31]
	v_mfma_f32_16x16x32_bf16 v[24:27], v[170:173], v[210:213], v[24:27]
	v_mfma_f32_16x16x32_bf16 v[12:15], v[162:165], v[218:221], v[12:15]
	v_mfma_f32_16x16x32_bf16 v[8:11], v[170:173], v[218:221], v[8:11]
	v_mfma_f32_16x16x32_bf16 v[52:55], v[174:177], v[190:193], v[52:55]
	v_mfma_f32_16x16x32_bf16 v[48:51], v[182:185], v[190:193], v[48:51]
	v_mfma_f32_16x16x32_bf16 v[36:39], v[174:177], v[198:201], v[36:39]
	v_mfma_f32_16x16x32_bf16 v[32:35], v[182:185], v[198:201], v[32:35]
	v_mfma_f32_16x16x32_bf16 v[20:23], v[174:177], v[206:209], v[20:23]
	v_mfma_f32_16x16x32_bf16 v[16:19], v[182:185], v[206:209], v[16:19]
	v_mfma_f32_16x16x32_bf16 v[4:7], v[174:177], v[214:217], v[4:7]
	v_mfma_f32_16x16x32_bf16 v[0:3], v[182:185], v[214:217], v[0:3]
	v_mfma_f32_16x16x32_bf16 v[52:55], v[178:181], v[194:197], v[52:55]
	v_mfma_f32_16x16x32_bf16 v[48:51], v[186:189], v[194:197], v[48:51]
	v_mfma_f32_16x16x32_bf16 v[36:39], v[178:181], v[202:205], v[36:39]
	v_mfma_f32_16x16x32_bf16 v[32:35], v[186:189], v[202:205], v[32:35]
	v_mfma_f32_16x16x32_bf16 v[20:23], v[178:181], v[210:213], v[20:23]
	v_mfma_f32_16x16x32_bf16 v[16:19], v[186:189], v[210:213], v[16:19]
	v_mfma_f32_16x16x32_bf16 v[4:7], v[178:181], v[218:221], v[4:7]
	v_mfma_f32_16x16x32_bf16 v[0:3], v[186:189], v[218:221], v[0:3]
	s_setprio 0
	s_barrier
	s_add_i32 s83, 0, 0x18000
	v_add_u32_e32 v161, s83, v159
	s_add_i32 s84, 0, 0x1c000
	ds_read_b128 v[146:149], v161
	ds_read_b128 v[162:165], v161 offset:1024
	ds_read_b128 v[166:169], v161 offset:2048
	ds_read_b128 v[170:173], v161 offset:3072
	v_add_u32_e32 v161, s84, v159
	ds_read_b128 v[174:177], v161
	ds_read_b128 v[178:181], v161 offset:1024
	ds_read_b128 v[182:185], v161 offset:2048
	ds_read_b128 v[186:189], v161 offset:3072
	s_add_u32 s48, s66, 0x80000
	s_addc_u32 s49, s67, 0
	s_mov_b32 m0, s78
	v_lshl_add_u64 v[230:231], s[48:49], 0, v[128:129]
	ds_read_b128 v[190:193], v160 offset:32768
	ds_read_b128 v[194:197], v160 offset:33792
	ds_read_b128 v[198:201], v160 offset:34816
	ds_read_b128 v[202:205], v160 offset:35840
	ds_read_b128 v[206:209], v160 offset:36864
	ds_read_b128 v[210:213], v160 offset:37888
	ds_read_b128 v[214:217], v160 offset:38912
	ds_read_b128 v[218:221], v160 offset:39936
	global_load_lds_dwordx4 v[230:231], off
	v_lshl_add_u64 v[230:231], s[48:49], 0, v[132:133]
	s_mov_b32 m0, s79
	s_nop 0
	global_load_lds_dwordx4 v[230:231], off
	s_waitcnt vmcnt(8)
	s_waitcnt lgkmcnt(0)
	s_barrier
	s_setprio 1
	s_waitcnt lgkmcnt(0)
	v_mfma_f32_16x16x32_bf16 v[124:127], v[146:149], v[190:193], v[124:127]
	v_mfma_f32_16x16x32_bf16 v[120:123], v[166:169], v[190:193], v[120:123]
	v_mfma_f32_16x16x32_bf16 v[108:111], v[146:149], v[198:201], v[108:111]
	v_mfma_f32_16x16x32_bf16 v[104:107], v[166:169], v[198:201], v[104:107]
	v_mfma_f32_16x16x32_bf16 v[92:95], v[146:149], v[206:209], v[92:95]
	v_mfma_f32_16x16x32_bf16 v[88:91], v[166:169], v[206:209], v[88:91]
	v_mfma_f32_16x16x32_bf16 v[76:79], v[146:149], v[214:217], v[76:79]
	v_mfma_f32_16x16x32_bf16 v[72:75], v[166:169], v[214:217], v[72:75]
	v_mfma_f32_16x16x32_bf16 v[124:127], v[162:165], v[194:197], v[124:127]
	v_mfma_f32_16x16x32_bf16 v[120:123], v[170:173], v[194:197], v[120:123]
	v_mfma_f32_16x16x32_bf16 v[108:111], v[162:165], v[202:205], v[108:111]
	v_mfma_f32_16x16x32_bf16 v[104:107], v[170:173], v[202:205], v[104:107]
	v_mfma_f32_16x16x32_bf16 v[92:95], v[162:165], v[210:213], v[92:95]
	v_mfma_f32_16x16x32_bf16 v[88:91], v[170:173], v[210:213], v[88:91]
	v_mfma_f32_16x16x32_bf16 v[76:79], v[162:165], v[218:221], v[76:79]
	v_mfma_f32_16x16x32_bf16 v[72:75], v[170:173], v[218:221], v[72:75]
	v_mfma_f32_16x16x32_bf16 v[116:119], v[174:177], v[190:193], v[116:119]
	v_mfma_f32_16x16x32_bf16 v[112:115], v[182:185], v[190:193], v[112:115]
	v_mfma_f32_16x16x32_bf16 v[100:103], v[174:177], v[198:201], v[100:103]
	v_mfma_f32_16x16x32_bf16 v[96:99], v[182:185], v[198:201], v[96:99]
	v_mfma_f32_16x16x32_bf16 v[84:87], v[174:177], v[206:209], v[84:87]
	v_mfma_f32_16x16x32_bf16 v[80:83], v[182:185], v[206:209], v[80:83]
	v_mfma_f32_16x16x32_bf16 v[68:71], v[174:177], v[214:217], v[68:71]
	v_mfma_f32_16x16x32_bf16 v[64:67], v[182:185], v[214:217], v[64:67]
	v_mfma_f32_16x16x32_bf16 v[116:119], v[178:181], v[194:197], v[116:119]
	v_mfma_f32_16x16x32_bf16 v[112:115], v[186:189], v[194:197], v[112:115]
	v_mfma_f32_16x16x32_bf16 v[100:103], v[178:181], v[202:205], v[100:103]
	v_mfma_f32_16x16x32_bf16 v[96:99], v[186:189], v[202:205], v[96:99]
	v_mfma_f32_16x16x32_bf16 v[84:87], v[178:181], v[210:213], v[84:87]
	v_mfma_f32_16x16x32_bf16 v[80:83], v[186:189], v[210:213], v[80:83]
	v_mfma_f32_16x16x32_bf16 v[68:71], v[178:181], v[218:221], v[68:71]
	v_mfma_f32_16x16x32_bf16 v[64:67], v[186:189], v[218:221], v[64:67]
	s_setprio 0
	s_barrier
; #define PG8_STAGE(bufoff, gbase, voff) do { _Pragma("unroll") for (int _i = 0; _i < 2; ++_i) \
;         __builtin_amdgcn_global_load_lds((const unsigned*)((const char*)(gbase) + (voff)[_i]), (LAS unsigned*)(lds + (bufoff) + ldsw + _i * 8192), 16, 0, 0); } while (0)
; #define PG8_LDA(dst, b, h) do { _Pragma("unroll") for (int m = 0; m < 4; ++m) _Pragma("unroll") for (int k = 0; k < 2; ++k) dst[m][k] = *(const LAS bf16x8*)(lds + PG8_SA(b, h) + aoff + m * 2048 + k * 1024); } while (0)
; #define PG8_MMA(ai, bj, At, Bt) do { __builtin_amdgcn_s_setprio(1); _Pragma("unroll") for (int m = 0; m < 4; ++m) _Pragma("unroll") for (int n = 0; n < 2; ++n) _Pragma("unroll") for (int k = 0; k < 2; ++k) \
;         acc[ai][bj][m][n] = __builtin_amdgcn_mfma_f32_16x16x32_bf16(Bt[n][k], At[m][k], acc[ai][bj][m][n], 0, 0, 0); __builtin_amdgcn_s_setprio(0); } while (0)
; #define PG8_WAIT_V(n) asm volatile("s_waitcnt vmcnt(" #n ")" ::: "memory")
; #define PG8_WAIT_L(n) asm volatile("s_waitcnt lgkmcnt(" #n ")" ::: "memory")
; #define PG8_BAR __builtin_amdgcn_s_barrier()
; #define PG8_SCHED __builtin_amdgcn_sched_barrier(0)
; template <class Epi, class Sched>
; __device__ __forceinline__ void gemm_phase(LAS unsigned char* lds, const Gemm g, const Sched& S, const Epi& E) {
;     ...
;             PG8_LDA(At, 1, 1); PG8_STAGE(PG8_SB(1, 0), b3, voffB); PG8_STAGE(PG8_SB(1, 1), b3 + hstepB, voffB); PG8_STAGE(PG8_SA(1, 0), a3, voffA);
;             PG8_WAIT_V(8); PG8_WAIT_L(0); PG8_BAR; PG8_MMA(1, 0, At, B0); PG8_MMA(1, 1, At, B1); PG8_BAR; PG8_SCHED;
;         }
;         if (wr == 0) PG8_BAR;
	s_add_i32 s48, s83, s76
	v_lshl_add_u64 v[222:223], v[222:223], 0, s[22:23]
	s_mov_b32 m0, s48
	ds_read_b128 v[190:193], v160 offset:49152
	ds_read_b128 v[194:197], v160 offset:50176
	ds_read_b128 v[198:201], v160 offset:51200
	ds_read_b128 v[202:205], v160 offset:52224
	ds_read_b128 v[206:209], v160 offset:53248
	ds_read_b128 v[210:213], v160 offset:54272
	ds_read_b128 v[214:217], v160 offset:55296
	ds_read_b128 v[218:221], v160 offset:56320
	global_load_lds_dwordx4 v[222:223], off
	s_add_i32 m0, s48, 0x2000
	s_add_u32 s48, s64, 0x80080
	v_lshl_add_u64 v[222:223], v[224:225], 0, s[22:23]
	s_addc_u32 s49, s65, 0
	s_add_i32 s64, s84, s76
	global_load_lds_dwordx4 v[222:223], off
	v_lshl_add_u64 v[222:223], s[48:49], 0, v[130:131]
	s_mov_b32 m0, s64
	s_nop 0
	global_load_lds_dwordx4 v[222:223], off
	v_lshl_add_u64 v[222:223], s[48:49], 0, v[134:135]
	s_add_i32 m0, s64, 0x2000
	s_nop 0
	global_load_lds_dwordx4 v[222:223], off
	v_lshl_add_u64 v[222:223], v[226:227], 0, s[22:23]
	s_mov_b32 m0, s80
	s_nop 0
	global_load_lds_dwordx4 v[222:223], off
	v_lshl_add_u64 v[222:223], v[228:229], 0, s[22:23]
	s_mov_b32 m0, s81
	s_nop 0
	global_load_lds_dwordx4 v[222:223], off
	s_waitcnt vmcnt(8)
	s_waitcnt lgkmcnt(0)
	s_barrier
	s_setprio 1
	s_waitcnt lgkmcnt(0)
	v_mfma_f32_16x16x32_bf16 v[60:63], v[146:149], v[190:193], v[60:63]
	v_mfma_f32_16x16x32_bf16 v[56:59], v[166:169], v[190:193], v[56:59]
	v_mfma_f32_16x16x32_bf16 v[44:47], v[146:149], v[198:201], v[44:47]
	v_mfma_f32_16x16x32_bf16 v[40:43], v[166:169], v[198:201], v[40:43]
	v_mfma_f32_16x16x32_bf16 v[28:31], v[146:149], v[206:209], v[28:31]
	v_mfma_f32_16x16x32_bf16 v[24:27], v[166:169], v[206:209], v[24:27]
	v_mfma_f32_16x16x32_bf16 v[12:15], v[146:149], v[214:217], v[12:15]
	v_mfma_f32_16x16x32_bf16 v[8:11], v[166:169], v[214:217], v[8:11]
	v_mfma_f32_16x16x32_bf16 v[60:63], v[162:165], v[194:197], v[60:63]
	v_mfma_f32_16x16x32_bf16 v[56:59], v[170:173], v[194:197], v[56:59]
	v_mfma_f32_16x16x32_bf16 v[44:47], v[162:165], v[202:205], v[44:47]
	v_mfma_f32_16x16x32_bf16 v[40:43], v[170:173], v[202:205], v[40:43]
	v_mfma_f32_16x16x32_bf16 v[28:31], v[162:165], v[210:213], v[28:31]
	v_mfma_f32_16x16x32_bf16 v[24:27], v[170:173], v[210:213], v[24:27]
	v_mfma_f32_16x16x32_bf16 v[12:15], v[162:165], v[218:221], v[12:15]
	v_mfma_f32_16x16x32_bf16 v[8:11], v[170:173], v[218:221], v[8:11]
	v_mfma_f32_16x16x32_bf16 v[52:55], v[174:177], v[190:193], v[52:55]
	v_mfma_f32_16x16x32_bf16 v[48:51], v[182:185], v[190:193], v[48:51]
	v_mfma_f32_16x16x32_bf16 v[36:39], v[174:177], v[198:201], v[36:39]
	v_mfma_f32_16x16x32_bf16 v[32:35], v[182:185], v[198:201], v[32:35]
	v_mfma_f32_16x16x32_bf16 v[20:23], v[174:177], v[206:209], v[20:23]
	v_mfma_f32_16x16x32_bf16 v[16:19], v[182:185], v[206:209], v[16:19]
	v_mfma_f32_16x16x32_bf16 v[4:7], v[174:177], v[214:217], v[4:7]
	v_mfma_f32_16x16x32_bf16 v[0:3], v[182:185], v[214:217], v[0:3]
	v_mfma_f32_16x16x32_bf16 v[52:55], v[178:181], v[194:197], v[52:55]
	v_mfma_f32_16x16x32_bf16 v[48:51], v[186:189], v[194:197], v[48:51]
	v_mfma_f32_16x16x32_bf16 v[36:39], v[178:181], v[202:205], v[36:39]
	v_mfma_f32_16x16x32_bf16 v[32:35], v[186:189], v[202:205], v[32:35]
	v_mfma_f32_16x16x32_bf16 v[20:23], v[178:181], v[210:213], v[20:23]
	v_mfma_f32_16x16x32_bf16 v[16:19], v[186:189], v[210:213], v[16:19]
	v_mfma_f32_16x16x32_bf16 v[4:7], v[178:181], v[218:221], v[4:7]
	v_mfma_f32_16x16x32_bf16 v[0:3], v[186:189], v[218:221], v[0:3]
	s_setprio 0
	s_barrier
	s_add_i32 s75, s75, 2
	s_add_u32 s62, s62, 0x100
	s_addc_u32 s63, s63, 0
	s_add_u32 s45, s45, 0x100
	s_addc_u32 s53, s53, 0
	s_cmp_gt_u32 s75, 29
	s_cbranch_scc0 .LBB0_724
	s_and_b64 vcc, exec, s[42:43]
	s_cbranch_vccz .LBB0_727
	s_barrier

; #define PG8_STAGE(bufoff, gbase, voff) do { _Pragma("unroll") for (int _i = 0; _i < 2; ++_i) \
;         __builtin_amdgcn_global_load_lds((const unsigned*)((const char*)(gbase) + (voff)[_i]), (LAS unsigned*)(lds + (bufoff) + ldsw + _i * 8192), 16, 0, 0); } while (0)
; #define PG8_LDA(dst, b, h) do { _Pragma("unroll") for (int m = 0; m < 4; ++m) _Pragma("unroll") for (int k = 0; k < 2; ++k) dst[m][k] = *(const LAS bf16x8*)(lds + PG8_SA(b, h) + aoff + m * 2048 + k * 1024); } while (0)
; #define PG8_LDB(dst, b, h) do { _Pragma("unroll") for (int n = 0; n < 2; ++n) _Pragma("unroll") for (int k = 0; k < 2; ++k) dst[n][k] = *(const LAS bf16x8*)(lds + PG8_SB(b, h) + boff + n * 2048 + k * 1024); } while (0)
; #define PG8_MMA(ai, bj, At, Bt) do { __builtin_amdgcn_s_setprio(1); _Pragma("unroll") for (int m = 0; m < 4; ++m) _Pragma("unroll") for (int n = 0; n < 2; ++n) _Pragma("unroll") for (int k = 0; k < 2; ++k) \
;         acc[ai][bj][m][n] = __builtin_amdgcn_mfma_f32_16x16x32_bf16(Bt[n][k], At[m][k], acc[ai][bj][m][n], 0, 0, 0); __builtin_amdgcn_s_setprio(0); } while (0)
; #define PG8_WAIT_V(n) asm volatile("s_waitcnt vmcnt(" #n ")" ::: "memory")
; #define PG8_WAIT_L(n) asm volatile("s_waitcnt lgkmcnt(" #n ")" ::: "memory")
; #define PG8_BAR __builtin_amdgcn_s_barrier()
; #define PG8_SCHED __builtin_amdgcn_sched_barrier(0)
; template <class Epi, class Sched>
; __device__ __forceinline__ void gemm_phase(LAS unsigned char* lds, const Gemm g, const Sched& S, const Epi& E) {
;     ...
;         for (int t = 0; t < nt; t += 2) {
;             const bool last = (t == nt - 2);
;             const char* a1 = cA + (size_t)(t + 1) * kstep;
;             const char* a2 = last ? nA : cA + (size_t)(t + 2) * kstep; const char* b2 = last ? nB : cB + (size_t)(t + 2) * kstep;
;             const char* a3 = a2 + kstep; const char* b3 = b2 + kstep;
;             PG8_LDB(B0, 0, 0); PG8_LDB(B1, 0, 1); PG8_SCHED; PG8_LDA(At, 0, 0); PG8_STAGE(PG8_SA(1, 1), a1 + hstepA, voffA);
;             PG8_WAIT_V(8); PG8_WAIT_L(0); PG8_BAR; PG8_MMA(0, 0, At, B0); PG8_MMA(0, 1, At, B1); PG8_BAR; PG8_SCHED;
;             PG8_LDA(At, 0, 1); PG8_STAGE(PG8_SB(0, 0), b2, voffB); PG8_STAGE(PG8_SB(0, 1), b2 + hstepB, voffB); PG8_STAGE(PG8_SA(0, 0), a2, voffA);
;             PG8_WAIT_V(8); PG8_WAIT_L(0); PG8_BAR; PG8_MMA(1, 0, At, B0); PG8_MMA(1, 1, At, B1); PG8_BAR; PG8_SCHED;
.LBB0_761:
	ds_read_b128 v[148:151], v143
	ds_read_b128 v[154:157], v143 offset:1024
	ds_read_b128 v[158:161], v143 offset:2048
	ds_read_b128 v[162:165], v143 offset:3072
	ds_read_b128 v[166:169], v144
	ds_read_b128 v[170:173], v144 offset:1024
	ds_read_b128 v[174:177], v144 offset:2048
	ds_read_b128 v[178:181], v144 offset:3072
	s_add_u32 s12, s10, 0xfa480080
	s_addc_u32 s13, s11, -1
	s_cmp_lg_u32 s34, 28
	s_cselect_b32 s12, s12, 0
	s_cselect_b32 s13, s13, 0
	s_add_u32 s18, s6, s12
	s_addc_u32 s19, s7, s13
	s_add_u32 s12, s0, s12
	s_addc_u32 s13, s1, s13
	s_mov_b32 m0, s35
	v_lshl_add_u64 v[214:215], v[138:139], 0, s[10:11]
	ds_read_b128 v[182:185], v145
	ds_read_b128 v[186:189], v145 offset:1024
	ds_read_b128 v[190:193], v145 offset:2048
	ds_read_b128 v[194:197], v145 offset:3072
	ds_read_b128 v[198:201], v145 offset:4096
	ds_read_b128 v[202:205], v145 offset:5120
	ds_read_b128 v[206:209], v145 offset:6144
	ds_read_b128 v[210:213], v145 offset:7168
	global_load_lds_dwordx4 v[214:215], off
	v_lshl_add_u64 v[214:215], v[140:141], 0, s[10:11]
	s_mov_b32 m0, s36
	s_nop 0
	global_load_lds_dwordx4 v[214:215], off
	s_waitcnt vmcnt(8)
	s_waitcnt lgkmcnt(0)
	s_barrier
	s_setprio 1
	s_waitcnt lgkmcnt(0)
	v_mfma_f32_16x16x32_bf16 v[124:127], v[148:151], v[182:185], v[124:127]
	v_mfma_f32_16x16x32_bf16 v[120:123], v[158:161], v[182:185], v[120:123]
	v_mfma_f32_16x16x32_bf16 v[108:111], v[148:151], v[190:193], v[108:111]
	v_mfma_f32_16x16x32_bf16 v[104:107], v[158:161], v[190:193], v[104:107]
	v_mfma_f32_16x16x32_bf16 v[92:95], v[148:151], v[198:201], v[92:95]
	v_mfma_f32_16x16x32_bf16 v[88:91], v[158:161], v[198:201], v[88:91]
	v_mfma_f32_16x16x32_bf16 v[76:79], v[148:151], v[206:209], v[76:79]
	v_mfma_f32_16x16x32_bf16 v[72:75], v[158:161], v[206:209], v[72:75]
	v_mfma_f32_16x16x32_bf16 v[124:127], v[154:157], v[186:189], v[124:127]
	v_mfma_f32_16x16x32_bf16 v[120:123], v[162:165], v[186:189], v[120:123]
	v_mfma_f32_16x16x32_bf16 v[108:111], v[154:157], v[194:197], v[108:111]
	v_mfma_f32_16x16x32_bf16 v[104:107], v[162:165], v[194:197], v[104:107]
	v_mfma_f32_16x16x32_bf16 v[92:95], v[154:157], v[202:205], v[92:95]
	v_mfma_f32_16x16x32_bf16 v[88:91], v[162:165], v[202:205], v[88:91]
	v_mfma_f32_16x16x32_bf16 v[76:79], v[154:157], v[210:213], v[76:79]
	v_mfma_f32_16x16x32_bf16 v[72:75], v[162:165], v[210:213], v[72:75]
	v_mfma_f32_16x16x32_bf16 v[116:119], v[166:169], v[182:185], v[116:119]
	v_mfma_f32_16x16x32_bf16 v[112:115], v[174:177], v[182:185], v[112:115]
	v_mfma_f32_16x16x32_bf16 v[100:103], v[166:169], v[190:193], v[100:103]
	v_mfma_f32_16x16x32_bf16 v[96:99], v[174:177], v[190:193], v[96:99]
	v_mfma_f32_16x16x32_bf16 v[84:87], v[166:169], v[198:201], v[84:87]
	v_mfma_f32_16x16x32_bf16 v[80:83], v[174:177], v[198:201], v[80:83]
	v_mfma_f32_16x16x32_bf16 v[68:71], v[166:169], v[206:209], v[68:71]
	v_mfma_f32_16x16x32_bf16 v[64:67], v[174:177], v[206:209], v[64:67]
	v_mfma_f32_16x16x32_bf16 v[116:119], v[170:173], v[186:189], v[116:119]
	v_mfma_f32_16x16x32_bf16 v[112:115], v[178:181], v[186:189], v[112:115]
	v_mfma_f32_16x16x32_bf16 v[100:103], v[170:173], v[194:197], v[100:103]
	v_mfma_f32_16x16x32_bf16 v[96:99], v[178:181], v[194:197], v[96:99]
	v_mfma_f32_16x16x32_bf16 v[84:87], v[170:173], v[202:205], v[84:87]
	v_mfma_f32_16x16x32_bf16 v[80:83], v[178:181], v[202:205], v[80:83]
	v_mfma_f32_16x16x32_bf16 v[68:71], v[170:173], v[210:213], v[68:71]
	v_mfma_f32_16x16x32_bf16 v[64:67], v[178:181], v[210:213], v[64:67]
	s_setprio 0
	s_barrier
	s_mov_b32 m0, s37
	v_lshl_add_u64 v[214:215], s[12:13], 0, v[130:131]
	s_add_u32 s46, s12, 0x80000
	ds_read_b128 v[182:185], v145 offset:16384
	ds_read_b128 v[186:189], v145 offset:17408
	ds_read_b128 v[190:193], v145 offset:18432
	ds_read_b128 v[194:197], v145 offset:19456
	ds_read_b128 v[198:201], v145 offset:20480
	ds_read_b128 v[202:205], v145 offset:21504
	ds_read_b128 v[206:209], v145 offset:22528
	ds_read_b128 v[210:213], v145 offset:23552
	global_load_lds_dwordx4 v[214:215], off
	v_lshl_add_u64 v[216:217], s[12:13], 0, v[134:135]
	s_mov_b32 m0, s38
	s_addc_u32 s47, s13, 0
	global_load_lds_dwordx4 v[216:217], off
	v_lshl_add_u64 v[218:219], s[46:47], 0, v[130:131]
	s_mov_b32 m0, s39
	v_lshl_add_u64 v[220:221], s[18:19], 0, v[132:133]
	global_load_lds_dwordx4 v[218:219], off
	v_lshl_add_u64 v[218:219], s[46:47], 0, v[134:135]
	s_mov_b32 m0, s40
	s_nop 0
	global_load_lds_dwordx4 v[218:219], off
	v_lshl_add_u64 v[218:219], s[18:19], 0, v[128:129]
	s_mov_b32 m0, s20
	s_nop 0
	global_load_lds_dwordx4 v[218:219], off
	s_mov_b32 m0, s21
	s_nop 0
	global_load_lds_dwordx4 v[220:221], off
	s_waitcnt vmcnt(8)
	s_waitcnt lgkmcnt(0)
	s_barrier
; #define PG8_STAGE(bufoff, gbase, voff) do { _Pragma("unroll") for (int _i = 0; _i < 2; ++_i) \
;         __builtin_amdgcn_global_load_lds((const unsigned*)((const char*)(gbase) + (voff)[_i]), (LAS unsigned*)(lds + (bufoff) + ldsw + _i * 8192), 16, 0, 0); } while (0)
; #define PG8_LDA(dst, b, h) do { _Pragma("unroll") for (int m = 0; m < 4; ++m) _Pragma("unroll") for (int k = 0; k < 2; ++k) dst[m][k] = *(const LAS bf16x8*)(lds + PG8_SA(b, h) + aoff + m * 2048 + k * 1024); } while (0)
; #define PG8_LDB(dst, b, h) do { _Pragma("unroll") for (int n = 0; n < 2; ++n) _Pragma("unroll") for (int k = 0; k < 2; ++k) dst[n][k] = *(const LAS bf16x8*)(lds + PG8_SB(b, h) + boff + n * 2048 + k * 1024); } while (0)
; #define PG8_MMA(ai, bj, At, Bt) do { __builtin_amdgcn_s_setprio(1); _Pragma("unroll") for (int m = 0; m < 4; ++m) _Pragma("unroll") for (int n = 0; n < 2; ++n) _Pragma("unroll") for (int k = 0; k < 2; ++k) \
;         acc[ai][bj][m][n] = __builtin_amdgcn_mfma_f32_16x16x32_bf16(Bt[n][k], At[m][k], acc[ai][bj][m][n], 0, 0, 0); __builtin_amdgcn_s_setprio(0); } while (0)
; #define PG8_WAIT_V(n) asm volatile("s_waitcnt vmcnt(" #n ")" ::: "memory")
; #define PG8_WAIT_L(n) asm volatile("s_waitcnt lgkmcnt(" #n ")" ::: "memory")
; #define PG8_BAR __builtin_amdgcn_s_barrier()
; #define PG8_SCHED __builtin_amdgcn_sched_barrier(0)
; template <class Epi, class Sched>
; __device__ __forceinline__ void gemm_phase(LAS unsigned char* lds, const Gemm g, const Sched& S, const Epi& E) {
;     ...
;             PG8_WAIT_V(8); PG8_WAIT_L(0); PG8_BAR; PG8_MMA(1, 0, At, B0); PG8_MMA(1, 1, At, B1); PG8_BAR; PG8_SCHED;
;             PG8_LDB(B0, 1, 0); PG8_LDB(B1, 1, 1); PG8_SCHED; PG8_LDA(At, 1, 0); PG8_STAGE(PG8_SA(0, 1), a2 + hstepA, voffA);
;             PG8_WAIT_V(8); PG8_WAIT_L(0); PG8_BAR; PG8_MMA(0, 0, At, B0); PG8_MMA(0, 1, At, B1); PG8_BAR; PG8_SCHED;
	s_setprio 1
	s_waitcnt lgkmcnt(0)
	v_mfma_f32_16x16x32_bf16 v[60:63], v[148:151], v[182:185], v[60:63]
	v_mfma_f32_16x16x32_bf16 v[56:59], v[158:161], v[182:185], v[56:59]
	v_mfma_f32_16x16x32_bf16 v[44:47], v[148:151], v[190:193], v[44:47]
	v_mfma_f32_16x16x32_bf16 v[40:43], v[158:161], v[190:193], v[40:43]
	v_mfma_f32_16x16x32_bf16 v[28:31], v[148:151], v[198:201], v[28:31]
	v_mfma_f32_16x16x32_bf16 v[24:27], v[158:161], v[198:201], v[24:27]
	v_mfma_f32_16x16x32_bf16 v[12:15], v[148:151], v[206:209], v[12:15]
	v_mfma_f32_16x16x32_bf16 v[8:11], v[158:161], v[206:209], v[8:11]
	v_mfma_f32_16x16x32_bf16 v[60:63], v[154:157], v[186:189], v[60:63]
	v_mfma_f32_16x16x32_bf16 v[56:59], v[162:165], v[186:189], v[56:59]
	v_mfma_f32_16x16x32_bf16 v[44:47], v[154:157], v[194:197], v[44:47]
	v_mfma_f32_16x16x32_bf16 v[40:43], v[162:165], v[194:197], v[40:43]
	v_mfma_f32_16x16x32_bf16 v[28:31], v[154:157], v[202:205], v[28:31]
	v_mfma_f32_16x16x32_bf16 v[24:27], v[162:165], v[202:205], v[24:27]
	v_mfma_f32_16x16x32_bf16 v[12:15], v[154:157], v[210:213], v[12:15]
	v_mfma_f32_16x16x32_bf16 v[8:11], v[162:165], v[210:213], v[8:11]
	v_mfma_f32_16x16x32_bf16 v[52:55], v[166:169], v[182:185], v[52:55]
	v_mfma_f32_16x16x32_bf16 v[48:51], v[174:177], v[182:185], v[48:51]
	v_mfma_f32_16x16x32_bf16 v[36:39], v[166:169], v[190:193], v[36:39]
	v_mfma_f32_16x16x32_bf16 v[32:35], v[174:177], v[190:193], v[32:35]
	v_mfma_f32_16x16x32_bf16 v[20:23], v[166:169], v[198:201], v[20:23]
	v_mfma_f32_16x16x32_bf16 v[16:19], v[174:177], v[198:201], v[16:19]
	v_mfma_f32_16x16x32_bf16 v[4:7], v[166:169], v[206:209], v[4:7]
	v_mfma_f32_16x16x32_bf16 v[0:3], v[174:177], v[206:209], v[0:3]
	v_mfma_f32_16x16x32_bf16 v[52:55], v[170:173], v[186:189], v[52:55]
	v_mfma_f32_16x16x32_bf16 v[48:51], v[178:181], v[186:189], v[48:51]
	v_mfma_f32_16x16x32_bf16 v[36:39], v[170:173], v[194:197], v[36:39]
	v_mfma_f32_16x16x32_bf16 v[32:35], v[178:181], v[194:197], v[32:35]
	v_mfma_f32_16x16x32_bf16 v[20:23], v[170:173], v[202:205], v[20:23]
	v_mfma_f32_16x16x32_bf16 v[16:19], v[178:181], v[202:205], v[16:19]
	v_mfma_f32_16x16x32_bf16 v[4:7], v[170:173], v[210:213], v[4:7]
	v_mfma_f32_16x16x32_bf16 v[0:3], v[178:181], v[210:213], v[0:3]
	s_setprio 0
	s_barrier
	ds_read_b128 v[148:151], v146
	ds_read_b128 v[154:157], v146 offset:1024
	ds_read_b128 v[158:161], v146 offset:2048
	ds_read_b128 v[162:165], v146 offset:3072
	ds_read_b128 v[166:169], v147
	ds_read_b128 v[170:173], v147 offset:1024
	ds_read_b128 v[174:177], v147 offset:2048
	ds_read_b128 v[178:181], v147 offset:3072
	s_add_u32 s18, s18, 0x80000
	s_addc_u32 s19, s19, 0
	s_mov_b32 m0, s22
	v_lshl_add_u64 v[222:223], s[18:19], 0, v[128:129]
	ds_read_b128 v[182:185], v145 offset:32768
	ds_read_b128 v[186:189], v145 offset:33792
	ds_read_b128 v[190:193], v145 offset:34816
	ds_read_b128 v[194:197], v145 offset:35840
	ds_read_b128 v[198:201], v145 offset:36864
	ds_read_b128 v[202:205], v145 offset:37888
	ds_read_b128 v[206:209], v145 offset:38912
	ds_read_b128 v[210:213], v145 offset:39936
	global_load_lds_dwordx4 v[222:223], off
	v_lshl_add_u64 v[222:223], s[18:19], 0, v[132:133]
	s_mov_b32 m0, s24
	s_nop 0
	global_load_lds_dwordx4 v[222:223], off
	s_waitcnt vmcnt(8)
	s_waitcnt lgkmcnt(0)
	s_barrier
	s_setprio 1
	s_waitcnt lgkmcnt(0)
	v_mfma_f32_16x16x32_bf16 v[124:127], v[148:151], v[182:185], v[124:127]
	v_mfma_f32_16x16x32_bf16 v[120:123], v[158:161], v[182:185], v[120:123]
	v_mfma_f32_16x16x32_bf16 v[108:111], v[148:151], v[190:193], v[108:111]
	v_mfma_f32_16x16x32_bf16 v[104:107], v[158:161], v[190:193], v[104:107]
	v_mfma_f32_16x16x32_bf16 v[92:95], v[148:151], v[198:201], v[92:95]
	v_mfma_f32_16x16x32_bf16 v[88:91], v[158:161], v[198:201], v[88:91]
	v_mfma_f32_16x16x32_bf16 v[76:79], v[148:151], v[206:209], v[76:79]
	v_mfma_f32_16x16x32_bf16 v[72:75], v[158:161], v[206:209], v[72:75]
	v_mfma_f32_16x16x32_bf16 v[124:127], v[154:157], v[186:189], v[124:127]
	v_mfma_f32_16x16x32_bf16 v[120:123], v[162:165], v[186:189], v[120:123]
	v_mfma_f32_16x16x32_bf16 v[108:111], v[154:157], v[194:197], v[108:111]
	v_mfma_f32_16x16x32_bf16 v[104:107], v[162:165], v[194:197], v[104:107]
	v_mfma_f32_16x16x32_bf16 v[92:95], v[154:157], v[202:205], v[92:95]
	v_mfma_f32_16x16x32_bf16 v[88:91], v[162:165], v[202:205], v[88:91]
	v_mfma_f32_16x16x32_bf16 v[76:79], v[154:157], v[210:213], v[76:79]
	v_mfma_f32_16x16x32_bf16 v[72:75], v[162:165], v[210:213], v[72:75]
	v_mfma_f32_16x16x32_bf16 v[116:119], v[166:169], v[182:185], v[116:119]
	v_mfma_f32_16x16x32_bf16 v[112:115], v[174:177], v[182:185], v[112:115]
	v_mfma_f32_16x16x32_bf16 v[100:103], v[166:169], v[190:193], v[100:103]
	v_mfma_f32_16x16x32_bf16 v[96:99], v[174:177], v[190:193], v[96:99]
	v_mfma_f32_16x16x32_bf16 v[84:87], v[166:169], v[198:201], v[84:87]
	v_mfma_f32_16x16x32_bf16 v[80:83], v[174:177], v[198:201], v[80:83]
	v_mfma_f32_16x16x32_bf16 v[68:71], v[166:169], v[206:209], v[68:71]
	v_mfma_f32_16x16x32_bf16 v[64:67], v[174:177], v[206:209], v[64:67]
	v_mfma_f32_16x16x32_bf16 v[116:119], v[170:173], v[186:189], v[116:119]
	v_mfma_f32_16x16x32_bf16 v[112:115], v[178:181], v[186:189], v[112:115]
	v_mfma_f32_16x16x32_bf16 v[100:103], v[170:173], v[194:197], v[100:103]
	v_mfma_f32_16x16x32_bf16 v[96:99], v[178:181], v[194:197], v[96:99]
	v_mfma_f32_16x16x32_bf16 v[84:87], v[170:173], v[202:205], v[84:87]
	v_mfma_f32_16x16x32_bf16 v[80:83], v[178:181], v[202:205], v[80:83]
	v_mfma_f32_16x16x32_bf16 v[68:71], v[170:173], v[210:213], v[68:71]
	v_mfma_f32_16x16x32_bf16 v[64:67], v[178:181], v[210:213], v[64:67]
	s_setprio 0
	s_barrier
; #define PG8_STAGE(bufoff, gbase, voff) do { _Pragma("unroll") for (int _i = 0; _i < 2; ++_i) \
;         __builtin_amdgcn_global_load_lds((const unsigned*)((const char*)(gbase) + (voff)[_i]), (LAS unsigned*)(lds + (bufoff) + ldsw + _i * 8192), 16, 0, 0); } while (0)
; #define PG8_LDA(dst, b, h) do { _Pragma("unroll") for (int m = 0; m < 4; ++m) _Pragma("unroll") for (int k = 0; k < 2; ++k) dst[m][k] = *(const LAS bf16x8*)(lds + PG8_SA(b, h) + aoff + m * 2048 + k * 1024); } while (0)
; #define PG8_MMA(ai, bj, At, Bt) do { __builtin_amdgcn_s_setprio(1); _Pragma("unroll") for (int m = 0; m < 4; ++m) _Pragma("unroll") for (int n = 0; n < 2; ++n) _Pragma("unroll") for (int k = 0; k < 2; ++k) \
;         acc[ai][bj][m][n] = __builtin_amdgcn_mfma_f32_16x16x32_bf16(Bt[n][k], At[m][k], acc[ai][bj][m][n], 0, 0, 0); __builtin_amdgcn_s_setprio(0); } while (0)
; #define PG8_WAIT_V(n) asm volatile("s_waitcnt vmcnt(" #n ")" ::: "memory")
; #define PG8_WAIT_L(n) asm volatile("s_waitcnt lgkmcnt(" #n ")" ::: "memory")
; #define PG8_BAR __builtin_amdgcn_s_barrier()
; #define PG8_SCHED __builtin_amdgcn_sched_barrier(0)
; template <class Epi, class Sched>
; __device__ __forceinline__ void gemm_phase(LAS unsigned char* lds, const Gemm g, const Sched& S, const Epi& E) {
;     ...
;             PG8_LDA(At, 1, 1); PG8_STAGE(PG8_SB(1, 0), b3, voffB); PG8_STAGE(PG8_SB(1, 1), b3 + hstepB, voffB); PG8_STAGE(PG8_SA(1, 0), a3, voffA);
;             PG8_WAIT_V(8); PG8_WAIT_L(0); PG8_BAR; PG8_MMA(1, 0, At, B0); PG8_MMA(1, 1, At, B1); PG8_BAR; PG8_SCHED;
;         }
;         if (wr == 0) PG8_BAR;
	s_mov_b32 m0, s41
	v_lshl_add_u64 v[214:215], v[214:215], 0, s[8:9]
	s_add_u32 s12, s12, 0x80080
	ds_read_b128 v[182:185], v145 offset:49152
	ds_read_b128 v[186:189], v145 offset:50176
	ds_read_b128 v[190:193], v145 offset:51200
	ds_read_b128 v[194:197], v145 offset:52224
	ds_read_b128 v[198:201], v145 offset:53248
	ds_read_b128 v[202:205], v145 offset:54272
	ds_read_b128 v[206:209], v145 offset:55296
	ds_read_b128 v[210:213], v145 offset:56320
	global_load_lds_dwordx4 v[214:215], off
	v_lshl_add_u64 v[214:215], v[216:217], 0, s[8:9]
	s_mov_b32 m0, s42
	s_addc_u32 s13, s13, 0
	global_load_lds_dwordx4 v[214:215], off
	v_lshl_add_u64 v[214:215], s[12:13], 0, v[130:131]
	s_mov_b32 m0, s43
	s_nop 0
	global_load_lds_dwordx4 v[214:215], off
	v_lshl_add_u64 v[214:215], s[12:13], 0, v[134:135]
	s_mov_b32 m0, s44
	s_nop 0
	global_load_lds_dwordx4 v[214:215], off
	v_lshl_add_u64 v[214:215], v[218:219], 0, s[8:9]
	s_mov_b32 m0, s25
	s_nop 0
	global_load_lds_dwordx4 v[214:215], off
	v_lshl_add_u64 v[214:215], v[220:221], 0, s[8:9]
	s_mov_b32 m0, s33
	s_nop 0
	global_load_lds_dwordx4 v[214:215], off
	s_waitcnt vmcnt(8)
	s_waitcnt lgkmcnt(0)
	s_barrier
	s_setprio 1
	s_waitcnt lgkmcnt(0)
	v_mfma_f32_16x16x32_bf16 v[60:63], v[148:151], v[182:185], v[60:63]
	v_mfma_f32_16x16x32_bf16 v[56:59], v[158:161], v[182:185], v[56:59]
	v_mfma_f32_16x16x32_bf16 v[44:47], v[148:151], v[190:193], v[44:47]
	v_mfma_f32_16x16x32_bf16 v[40:43], v[158:161], v[190:193], v[40:43]
	v_mfma_f32_16x16x32_bf16 v[28:31], v[148:151], v[198:201], v[28:31]
	v_mfma_f32_16x16x32_bf16 v[24:27], v[158:161], v[198:201], v[24:27]
	v_mfma_f32_16x16x32_bf16 v[12:15], v[148:151], v[206:209], v[12:15]
	v_mfma_f32_16x16x32_bf16 v[8:11], v[158:161], v[206:209], v[8:11]
	v_mfma_f32_16x16x32_bf16 v[60:63], v[154:157], v[186:189], v[60:63]
	v_mfma_f32_16x16x32_bf16 v[56:59], v[162:165], v[186:189], v[56:59]
	v_mfma_f32_16x16x32_bf16 v[44:47], v[154:157], v[194:197], v[44:47]
	v_mfma_f32_16x16x32_bf16 v[40:43], v[162:165], v[194:197], v[40:43]
	v_mfma_f32_16x16x32_bf16 v[28:31], v[154:157], v[202:205], v[28:31]
	v_mfma_f32_16x16x32_bf16 v[24:27], v[162:165], v[202:205], v[24:27]
	v_mfma_f32_16x16x32_bf16 v[12:15], v[154:157], v[210:213], v[12:15]
	v_mfma_f32_16x16x32_bf16 v[8:11], v[162:165], v[210:213], v[8:11]
	v_mfma_f32_16x16x32_bf16 v[52:55], v[166:169], v[182:185], v[52:55]
	v_mfma_f32_16x16x32_bf16 v[48:51], v[174:177], v[182:185], v[48:51]
	v_mfma_f32_16x16x32_bf16 v[36:39], v[166:169], v[190:193], v[36:39]
	v_mfma_f32_16x16x32_bf16 v[32:35], v[174:177], v[190:193], v[32:35]
	v_mfma_f32_16x16x32_bf16 v[20:23], v[166:169], v[198:201], v[20:23]
	v_mfma_f32_16x16x32_bf16 v[16:19], v[174:177], v[198:201], v[16:19]
	v_mfma_f32_16x16x32_bf16 v[4:7], v[166:169], v[206:209], v[4:7]
	v_mfma_f32_16x16x32_bf16 v[0:3], v[174:177], v[206:209], v[0:3]
	v_mfma_f32_16x16x32_bf16 v[52:55], v[170:173], v[186:189], v[52:55]
	v_mfma_f32_16x16x32_bf16 v[48:51], v[178:181], v[186:189], v[48:51]
	v_mfma_f32_16x16x32_bf16 v[36:39], v[170:173], v[194:197], v[36:39]
	v_mfma_f32_16x16x32_bf16 v[32:35], v[178:181], v[194:197], v[32:35]
	v_mfma_f32_16x16x32_bf16 v[20:23], v[170:173], v[202:205], v[20:23]
	v_mfma_f32_16x16x32_bf16 v[16:19], v[178:181], v[202:205], v[16:19]
	v_mfma_f32_16x16x32_bf16 v[4:7], v[170:173], v[210:213], v[4:7]
	v_mfma_f32_16x16x32_bf16 v[0:3], v[178:181], v[210:213], v[0:3]
	s_setprio 0
	s_barrier
	s_add_i32 s34, s34, 2
	s_add_u32 s10, s10, 0x100
	s_addc_u32 s11, s11, 0
	s_cmp_gt_u32 s34, 29
	s_cbranch_scc0 .LBB0_761
	s_cmpk_lt_u32 s5, 0x100
	s_cbranch_scc0 .LBB0_764
	s_barrier

; #define PG8_STAGE(bufoff, gbase, voff) do { _Pragma("unroll") for (int _i = 0; _i < 2; ++_i) \
;         __builtin_amdgcn_global_load_lds((const unsigned*)((const char*)(gbase) + (voff)[_i]), (LAS unsigned*)(lds + (bufoff) + ldsw + _i * 8192), 16, 0, 0); } while (0)
; #define PG8_LDA(dst, b, h) do { _Pragma("unroll") for (int m = 0; m < 4; ++m) _Pragma("unroll") for (int k = 0; k < 2; ++k) dst[m][k] = *(const LAS bf16x8*)(lds + PG8_SA(b, h) + aoff + m * 2048 + k * 1024); } while (0)
; #define PG8_LDB(dst, b, h) do { _Pragma("unroll") for (int n = 0; n < 2; ++n) _Pragma("unroll") for (int k = 0; k < 2; ++k) dst[n][k] = *(const LAS bf16x8*)(lds + PG8_SB(b, h) + boff + n * 2048 + k * 1024); } while (0)
; #define PG8_MMA(ai, bj, At, Bt) do { __builtin_amdgcn_s_setprio(1); _Pragma("unroll") for (int m = 0; m < 4; ++m) _Pragma("unroll") for (int n = 0; n < 2; ++n) _Pragma("unroll") for (int k = 0; k < 2; ++k) \
;         acc[ai][bj][m][n] = __builtin_amdgcn_mfma_f32_16x16x32_bf16(Bt[n][k], At[m][k], acc[ai][bj][m][n], 0, 0, 0); __builtin_amdgcn_s_setprio(0); } while (0)
; #define PG8_WAIT_V(n) asm volatile("s_waitcnt vmcnt(" #n ")" ::: "memory")
; #define PG8_WAIT_L(n) asm volatile("s_waitcnt lgkmcnt(" #n ")" ::: "memory")
; #define PG8_BAR __builtin_amdgcn_s_barrier()
; #define PG8_SCHED __builtin_amdgcn_sched_barrier(0)
; template <class Epi, class Sched>
; __device__ __forceinline__ void gemm_phase(LAS unsigned char* lds, const Gemm g, const Sched& S, const Epi& E) {
;     ...
;             const bool last = (t == nt - 2);
;             const char* a1 = cA + (size_t)(t + 1) * kstep;
;             const char* a2 = last ? nA : cA + (size_t)(t + 2) * kstep; const char* b2 = last ? nB : cB + (size_t)(t + 2) * kstep;
;             const char* a3 = a2 + kstep; const char* b3 = b2 + kstep;
;             PG8_LDB(B0, 0, 0); PG8_LDB(B1, 0, 1); PG8_SCHED; PG8_LDA(At, 0, 0); PG8_STAGE(PG8_SA(1, 1), a1 + hstepA, voffA);
;             PG8_WAIT_V(8); PG8_WAIT_L(0); PG8_BAR; PG8_MMA(0, 0, At, B0); PG8_MMA(0, 1, At, B1); PG8_BAR; PG8_SCHED;
;             PG8_LDA(At, 0, 1); PG8_STAGE(PG8_SB(0, 0), b2, voffB); PG8_STAGE(PG8_SB(0, 1), b2 + hstepB, voffB); PG8_STAGE(PG8_SA(0, 0), a2, voffA);
;             PG8_WAIT_V(8); PG8_WAIT_L(0); PG8_BAR; PG8_MMA(1, 0, At, B0); PG8_MMA(1, 1, At, B1); PG8_BAR; PG8_SCHED;
.Ledge_p7:
.LBB0_837:
	ds_read_b128 v[146:149], v155
	ds_read_b128 v[160:163], v155 offset:1024
	ds_read_b128 v[164:167], v155 offset:2048
	ds_read_b128 v[168:171], v155 offset:3072
	ds_read_b128 v[172:175], v156
	ds_read_b128 v[176:179], v156 offset:1024
	ds_read_b128 v[180:183], v156 offset:2048
	ds_read_b128 v[184:187], v156 offset:3072
	s_add_u32 s38, s36, 0xfff80800
	s_addc_u32 s39, s37, -1
	s_cmp_eq_u32 s55, 28
	s_cselect_b32 s41, s19, s39
	s_cselect_b32 s40, s51, s38
	s_cselect_b32 s39, s17, s54
	s_cselect_b32 s38, s52, s53
	s_add_i32 m0, s25, 0xc000
	ds_read_b128 v[188:191], v157
	ds_read_b128 v[192:195], v157 offset:1024
	ds_read_b128 v[196:199], v157 offset:2048
	ds_read_b128 v[200:203], v157 offset:3072
	ds_read_b128 v[204:207], v157 offset:4096
	ds_read_b128 v[208:211], v157 offset:5120
	ds_read_b128 v[212:215], v157 offset:6144
	ds_read_b128 v[216:219], v157 offset:7168
	global_load_lds_dwordx4 v138, s[36:37]
	s_add_i32 m0, s25, 0xe000
	s_nop 0
	global_load_lds_dwordx4 v140, s[36:37]
	s_waitcnt vmcnt(8)
	s_waitcnt lgkmcnt(0)
	s_barrier
	s_setprio 1
	s_waitcnt lgkmcnt(0)
	v_mfma_f32_16x16x32_bf16 v[124:127], v[146:149], v[188:191], v[124:127]
	v_mfma_f32_16x16x32_bf16 v[120:123], v[164:167], v[188:191], v[120:123]
	v_mfma_f32_16x16x32_bf16 v[108:111], v[146:149], v[196:199], v[108:111]
	v_mfma_f32_16x16x32_bf16 v[104:107], v[164:167], v[196:199], v[104:107]
	v_mfma_f32_16x16x32_bf16 v[92:95], v[146:149], v[204:207], v[92:95]
	v_mfma_f32_16x16x32_bf16 v[88:91], v[164:167], v[204:207], v[88:91]
	v_mfma_f32_16x16x32_bf16 v[76:79], v[146:149], v[212:215], v[76:79]
	v_mfma_f32_16x16x32_bf16 v[72:75], v[164:167], v[212:215], v[72:75]
	v_mfma_f32_16x16x32_bf16 v[124:127], v[160:163], v[192:195], v[124:127]
	v_mfma_f32_16x16x32_bf16 v[120:123], v[168:171], v[192:195], v[120:123]
	v_mfma_f32_16x16x32_bf16 v[108:111], v[160:163], v[200:203], v[108:111]
	v_mfma_f32_16x16x32_bf16 v[104:107], v[168:171], v[200:203], v[104:107]
	v_mfma_f32_16x16x32_bf16 v[92:95], v[160:163], v[208:211], v[92:95]
	v_mfma_f32_16x16x32_bf16 v[88:91], v[168:171], v[208:211], v[88:91]
	v_mfma_f32_16x16x32_bf16 v[76:79], v[160:163], v[216:219], v[76:79]
	v_mfma_f32_16x16x32_bf16 v[72:75], v[168:171], v[216:219], v[72:75]
	v_mfma_f32_16x16x32_bf16 v[116:119], v[172:175], v[188:191], v[116:119]
	v_mfma_f32_16x16x32_bf16 v[112:115], v[180:183], v[188:191], v[112:115]
	v_mfma_f32_16x16x32_bf16 v[100:103], v[172:175], v[196:199], v[100:103]
	v_mfma_f32_16x16x32_bf16 v[96:99], v[180:183], v[196:199], v[96:99]
	v_mfma_f32_16x16x32_bf16 v[84:87], v[172:175], v[204:207], v[84:87]
	v_mfma_f32_16x16x32_bf16 v[80:83], v[180:183], v[204:207], v[80:83]
	v_mfma_f32_16x16x32_bf16 v[68:71], v[172:175], v[212:215], v[68:71]
	v_mfma_f32_16x16x32_bf16 v[64:67], v[180:183], v[212:215], v[64:67]
	v_mfma_f32_16x16x32_bf16 v[116:119], v[176:179], v[192:195], v[116:119]
	v_mfma_f32_16x16x32_bf16 v[112:115], v[184:187], v[192:195], v[112:115]
	v_mfma_f32_16x16x32_bf16 v[100:103], v[176:179], v[200:203], v[100:103]
	v_mfma_f32_16x16x32_bf16 v[96:99], v[184:187], v[200:203], v[96:99]
	v_mfma_f32_16x16x32_bf16 v[84:87], v[176:179], v[208:211], v[84:87]
	v_mfma_f32_16x16x32_bf16 v[80:83], v[184:187], v[208:211], v[80:83]
	v_mfma_f32_16x16x32_bf16 v[68:71], v[176:179], v[216:219], v[68:71]
	v_mfma_f32_16x16x32_bf16 v[64:67], v[184:187], v[216:219], v[64:67]
	s_setprio 0
	s_barrier
	s_add_i32 s48, s46, s5
	s_mov_b32 m0, s48
	ds_read_b128 v[188:191], v157 offset:16384
	ds_read_b128 v[192:195], v157 offset:17408
	ds_read_b128 v[196:199], v157 offset:18432
	ds_read_b128 v[200:203], v157 offset:19456
	ds_read_b128 v[204:207], v157 offset:20480
	ds_read_b128 v[208:211], v157 offset:21504
	ds_read_b128 v[212:215], v157 offset:22528
	ds_read_b128 v[216:219], v157 offset:23552
	global_load_lds_dwordx4 v130, s[38:39]
	s_add_i32 m0, s48, 0x2000
	s_add_u32 s48, s38, 0x80000
	s_addc_u32 s49, s39, 0
	s_add_i32 s56, s47, s5
	global_load_lds_dwordx4 v134, s[38:39]
	s_mov_b32 m0, s56
	s_nop 0
	global_load_lds_dwordx4 v130, s[48:49]
	s_add_i32 m0, s56, 0x2000
	s_nop 0
	global_load_lds_dwordx4 v134, s[48:49]
	s_mov_b32 m0, s25
	s_nop 0
	global_load_lds_dwordx4 v128, s[40:41]
	s_mov_b32 m0, s33
	s_nop 0
	global_load_lds_dwordx4 v132, s[40:41]
	s_waitcnt vmcnt(8)
	s_waitcnt lgkmcnt(0)
	s_barrier
	s_setprio 1
	s_waitcnt lgkmcnt(0)
	v_mfma_f32_16x16x32_bf16 v[60:63], v[146:149], v[188:191], v[60:63]
	v_mfma_f32_16x16x32_bf16 v[56:59], v[164:167], v[188:191], v[56:59]
	v_mfma_f32_16x16x32_bf16 v[44:47], v[146:149], v[196:199], v[44:47]
	v_mfma_f32_16x16x32_bf16 v[40:43], v[164:167], v[196:199], v[40:43]
	v_mfma_f32_16x16x32_bf16 v[28:31], v[146:149], v[204:207], v[28:31]
	v_mfma_f32_16x16x32_bf16 v[24:27], v[164:167], v[204:207], v[24:27]
	v_mfma_f32_16x16x32_bf16 v[12:15], v[146:149], v[212:215], v[12:15]
	v_mfma_f32_16x16x32_bf16 v[8:11], v[164:167], v[212:215], v[8:11]
	v_mfma_f32_16x16x32_bf16 v[60:63], v[160:163], v[192:195], v[60:63]
	v_mfma_f32_16x16x32_bf16 v[56:59], v[168:171], v[192:195], v[56:59]
	v_mfma_f32_16x16x32_bf16 v[44:47], v[160:163], v[200:203], v[44:47]
	v_mfma_f32_16x16x32_bf16 v[40:43], v[168:171], v[200:203], v[40:43]
	v_mfma_f32_16x16x32_bf16 v[28:31], v[160:163], v[208:211], v[28:31]
	v_mfma_f32_16x16x32_bf16 v[24:27], v[168:171], v[208:211], v[24:27]
	v_mfma_f32_16x16x32_bf16 v[12:15], v[160:163], v[216:219], v[12:15]
	v_mfma_f32_16x16x32_bf16 v[8:11], v[168:171], v[216:219], v[8:11]
	v_mfma_f32_16x16x32_bf16 v[52:55], v[172:175], v[188:191], v[52:55]
	v_mfma_f32_16x16x32_bf16 v[48:51], v[180:183], v[188:191], v[48:51]
	v_mfma_f32_16x16x32_bf16 v[36:39], v[172:175], v[196:199], v[36:39]
	v_mfma_f32_16x16x32_bf16 v[32:35], v[180:183], v[196:199], v[32:35]
	v_mfma_f32_16x16x32_bf16 v[20:23], v[172:175], v[204:207], v[20:23]
	v_mfma_f32_16x16x32_bf16 v[16:19], v[180:183], v[204:207], v[16:19]
	v_mfma_f32_16x16x32_bf16 v[4:7], v[172:175], v[212:215], v[4:7]
	v_mfma_f32_16x16x32_bf16 v[0:3], v[180:183], v[212:215], v[0:3]
	v_mfma_f32_16x16x32_bf16 v[52:55], v[176:179], v[192:195], v[52:55]
	v_mfma_f32_16x16x32_bf16 v[48:51], v[184:187], v[192:195], v[48:51]
	v_mfma_f32_16x16x32_bf16 v[36:39], v[176:179], v[200:203], v[36:39]
	v_mfma_f32_16x16x32_bf16 v[32:35], v[184:187], v[200:203], v[32:35]
	v_mfma_f32_16x16x32_bf16 v[20:23], v[176:179], v[208:211], v[20:23]
	v_mfma_f32_16x16x32_bf16 v[16:19], v[184:187], v[208:211], v[16:19]
	v_mfma_f32_16x16x32_bf16 v[4:7], v[176:179], v[216:219], v[4:7]
	v_mfma_f32_16x16x32_bf16 v[0:3], v[184:187], v[216:219], v[0:3]
	s_setprio 0
	s_barrier
; #define PG8_STAGE(bufoff, gbase, voff) do { _Pragma("unroll") for (int _i = 0; _i < 2; ++_i) \
;         __builtin_amdgcn_global_load_lds((const unsigned*)((const char*)(gbase) + (voff)[_i]), (LAS unsigned*)(lds + (bufoff) + ldsw + _i * 8192), 16, 0, 0); } while (0)
; #define PG8_LDA(dst, b, h) do { _Pragma("unroll") for (int m = 0; m < 4; ++m) _Pragma("unroll") for (int k = 0; k < 2; ++k) dst[m][k] = *(const LAS bf16x8*)(lds + PG8_SA(b, h) + aoff + m * 2048 + k * 1024); } while (0)
; #define PG8_LDB(dst, b, h) do { _Pragma("unroll") for (int n = 0; n < 2; ++n) _Pragma("unroll") for (int k = 0; k < 2; ++k) dst[n][k] = *(const LAS bf16x8*)(lds + PG8_SB(b, h) + boff + n * 2048 + k * 1024); } while (0)
; #define PG8_MMA(ai, bj, At, Bt) do { __builtin_amdgcn_s_setprio(1); _Pragma("unroll") for (int m = 0; m < 4; ++m) _Pragma("unroll") for (int n = 0; n < 2; ++n) _Pragma("unroll") for (int k = 0; k < 2; ++k) \
;         acc[ai][bj][m][n] = __builtin_amdgcn_mfma_f32_16x16x32_bf16(Bt[n][k], At[m][k], acc[ai][bj][m][n], 0, 0, 0); __builtin_amdgcn_s_setprio(0); } while (0)
; #define PG8_WAIT_V(n) asm volatile("s_waitcnt vmcnt(" #n ")" ::: "memory")
; #define PG8_WAIT_L(n) asm volatile("s_waitcnt lgkmcnt(" #n ")" ::: "memory")
; #define PG8_BAR __builtin_amdgcn_s_barrier()
; #define PG8_SCHED __builtin_amdgcn_sched_barrier(0)
; template <class Epi, class Sched>
; __device__ __forceinline__ void gemm_phase(LAS unsigned char* lds, const Gemm g, const Sched& S, const Epi& E) {
;     ...
;             PG8_LDB(B0, 1, 0); PG8_LDB(B1, 1, 1); PG8_SCHED; PG8_LDA(At, 1, 0); PG8_STAGE(PG8_SA(0, 1), a2 + hstepA, voffA);
;             PG8_WAIT_V(8); PG8_WAIT_L(0); PG8_BAR; PG8_MMA(0, 0, At, B0); PG8_MMA(0, 1, At, B1); PG8_BAR; PG8_SCHED;
;             PG8_LDA(At, 1, 1); PG8_STAGE(PG8_SB(1, 0), b3, voffB); PG8_STAGE(PG8_SB(1, 1), b3 + hstepB, voffB); PG8_STAGE(PG8_SA(1, 0), a3, voffA);
;             PG8_WAIT_V(8); PG8_WAIT_L(0); PG8_BAR; PG8_MMA(1, 0, At, B0); PG8_MMA(1, 1, At, B1); PG8_BAR; PG8_SCHED;
;         }
	s_add_i32 s48, 0, 0x18000
	v_add_u32_e32 v159, s48, v153
	s_add_i32 s49, 0, 0x1c000
	ds_read_b128 v[146:149], v159
	ds_read_b128 v[160:163], v159 offset:1024
	ds_read_b128 v[164:167], v159 offset:2048
	ds_read_b128 v[168:171], v159 offset:3072
	v_add_u32_e32 v159, s49, v153
	ds_read_b128 v[172:175], v159
	ds_read_b128 v[176:179], v159 offset:1024
	ds_read_b128 v[180:183], v159 offset:2048
	ds_read_b128 v[184:187], v159 offset:3072
	s_add_u32 s40, s40, 0x80000
	s_addc_u32 s41, s41, 0
	s_mov_b32 m0, s34
	ds_read_b128 v[188:191], v157 offset:32768
	ds_read_b128 v[192:195], v157 offset:33792
	ds_read_b128 v[196:199], v157 offset:34816
	ds_read_b128 v[200:203], v157 offset:35840
	ds_read_b128 v[204:207], v157 offset:36864
	ds_read_b128 v[208:211], v157 offset:37888
	ds_read_b128 v[212:215], v157 offset:38912
	ds_read_b128 v[216:219], v157 offset:39936
	global_load_lds_dwordx4 v128, s[40:41]
	s_mov_b32 m0, s35
	s_nop 0
	global_load_lds_dwordx4 v132, s[40:41]
	s_waitcnt vmcnt(8)
	s_waitcnt lgkmcnt(0)
	s_barrier
	s_setprio 1
	s_waitcnt lgkmcnt(0)
	v_mfma_f32_16x16x32_bf16 v[124:127], v[146:149], v[188:191], v[124:127]
	v_mfma_f32_16x16x32_bf16 v[120:123], v[164:167], v[188:191], v[120:123]
	v_mfma_f32_16x16x32_bf16 v[108:111], v[146:149], v[196:199], v[108:111]
	v_mfma_f32_16x16x32_bf16 v[104:107], v[164:167], v[196:199], v[104:107]
	v_mfma_f32_16x16x32_bf16 v[92:95], v[146:149], v[204:207], v[92:95]
	v_mfma_f32_16x16x32_bf16 v[88:91], v[164:167], v[204:207], v[88:91]
	v_mfma_f32_16x16x32_bf16 v[76:79], v[146:149], v[212:215], v[76:79]
	v_mfma_f32_16x16x32_bf16 v[72:75], v[164:167], v[212:215], v[72:75]
	v_mfma_f32_16x16x32_bf16 v[124:127], v[160:163], v[192:195], v[124:127]
	v_mfma_f32_16x16x32_bf16 v[120:123], v[168:171], v[192:195], v[120:123]
	v_mfma_f32_16x16x32_bf16 v[108:111], v[160:163], v[200:203], v[108:111]
	v_mfma_f32_16x16x32_bf16 v[104:107], v[168:171], v[200:203], v[104:107]
	v_mfma_f32_16x16x32_bf16 v[92:95], v[160:163], v[208:211], v[92:95]
	v_mfma_f32_16x16x32_bf16 v[88:91], v[168:171], v[208:211], v[88:91]
	v_mfma_f32_16x16x32_bf16 v[76:79], v[160:163], v[216:219], v[76:79]
	v_mfma_f32_16x16x32_bf16 v[72:75], v[168:171], v[216:219], v[72:75]
	v_mfma_f32_16x16x32_bf16 v[116:119], v[172:175], v[188:191], v[116:119]
	v_mfma_f32_16x16x32_bf16 v[112:115], v[180:183], v[188:191], v[112:115]
	v_mfma_f32_16x16x32_bf16 v[100:103], v[172:175], v[196:199], v[100:103]
	v_mfma_f32_16x16x32_bf16 v[96:99], v[180:183], v[196:199], v[96:99]
	v_mfma_f32_16x16x32_bf16 v[84:87], v[172:175], v[204:207], v[84:87]
	v_mfma_f32_16x16x32_bf16 v[80:83], v[180:183], v[204:207], v[80:83]
	v_mfma_f32_16x16x32_bf16 v[68:71], v[172:175], v[212:215], v[68:71]
	v_mfma_f32_16x16x32_bf16 v[64:67], v[180:183], v[212:215], v[64:67]
	v_mfma_f32_16x16x32_bf16 v[116:119], v[176:179], v[192:195], v[116:119]
	v_mfma_f32_16x16x32_bf16 v[112:115], v[184:187], v[192:195], v[112:115]
	v_mfma_f32_16x16x32_bf16 v[100:103], v[176:179], v[200:203], v[100:103]
	v_mfma_f32_16x16x32_bf16 v[96:99], v[184:187], v[200:203], v[96:99]
	v_mfma_f32_16x16x32_bf16 v[84:87], v[176:179], v[208:211], v[84:87]
	v_mfma_f32_16x16x32_bf16 v[80:83], v[184:187], v[208:211], v[80:83]
	v_mfma_f32_16x16x32_bf16 v[68:71], v[176:179], v[216:219], v[68:71]
	v_mfma_f32_16x16x32_bf16 v[64:67], v[184:187], v[216:219], v[64:67]
	s_setprio 0
	s_barrier
	s_add_i32 s56, s48, s5
	s_add_u32 s100, s38, 0x80
	s_addc_u32 s101, s39, 0
	s_mov_b32 m0, s56
	ds_read_b128 v[188:191], v157 offset:49152
	ds_read_b128 v[192:195], v157 offset:50176
	ds_read_b128 v[196:199], v157 offset:51200
	ds_read_b128 v[200:203], v157 offset:52224
	ds_read_b128 v[204:207], v157 offset:53248
	ds_read_b128 v[208:211], v157 offset:54272
	ds_read_b128 v[212:215], v157 offset:55296
	ds_read_b128 v[216:219], v157 offset:56320
	global_load_lds_dwordx4 v130, s[100:101]
	s_add_i32 m0, s56, 0x2000
	s_add_u32 s38, s38, 0x80080
	s_addc_u32 s39, s39, 0
	s_add_i32 s56, s49, s5
	global_load_lds_dwordx4 v134, s[100:101]
	s_mov_b32 m0, s56
	s_nop 0
	global_load_lds_dwordx4 v130, s[38:39]
	s_add_i32 m0, s56, 0x2000
	s_nop 0
	global_load_lds_dwordx4 v134, s[38:39]
	s_add_u32 s100, s40, 0xfff80800
	s_addc_u32 s101, s41, -1
	s_mov_b32 m0, s43
	s_nop 0
	global_load_lds_dwordx4 v128, s[100:101]
	s_mov_b32 m0, s44
	s_nop 0
	global_load_lds_dwordx4 v132, s[100:101]
	s_waitcnt vmcnt(8)
	s_waitcnt lgkmcnt(0)
	s_barrier
	s_setprio 1
	s_waitcnt lgkmcnt(0)
	v_mfma_f32_16x16x32_bf16 v[60:63], v[146:149], v[188:191], v[60:63]
	v_mfma_f32_16x16x32_bf16 v[56:59], v[164:167], v[188:191], v[56:59]
	v_mfma_f32_16x16x32_bf16 v[44:47], v[146:149], v[196:199], v[44:47]
	v_mfma_f32_16x16x32_bf16 v[40:43], v[164:167], v[196:199], v[40:43]
	v_mfma_f32_16x16x32_bf16 v[28:31], v[146:149], v[204:207], v[28:31]
	v_mfma_f32_16x16x32_bf16 v[24:27], v[164:167], v[204:207], v[24:27]
	v_mfma_f32_16x16x32_bf16 v[12:15], v[146:149], v[212:215], v[12:15]
	v_mfma_f32_16x16x32_bf16 v[8:11], v[164:167], v[212:215], v[8:11]
	v_mfma_f32_16x16x32_bf16 v[60:63], v[160:163], v[192:195], v[60:63]
	v_mfma_f32_16x16x32_bf16 v[56:59], v[168:171], v[192:195], v[56:59]
	v_mfma_f32_16x16x32_bf16 v[44:47], v[160:163], v[200:203], v[44:47]
	v_mfma_f32_16x16x32_bf16 v[40:43], v[168:171], v[200:203], v[40:43]
	v_mfma_f32_16x16x32_bf16 v[28:31], v[160:163], v[208:211], v[28:31]
	v_mfma_f32_16x16x32_bf16 v[24:27], v[168:171], v[208:211], v[24:27]
	v_mfma_f32_16x16x32_bf16 v[12:15], v[160:163], v[216:219], v[12:15]
	v_mfma_f32_16x16x32_bf16 v[8:11], v[168:171], v[216:219], v[8:11]
	v_mfma_f32_16x16x32_bf16 v[52:55], v[172:175], v[188:191], v[52:55]
	v_mfma_f32_16x16x32_bf16 v[48:51], v[180:183], v[188:191], v[48:51]
	v_mfma_f32_16x16x32_bf16 v[36:39], v[172:175], v[196:199], v[36:39]
	v_mfma_f32_16x16x32_bf16 v[32:35], v[180:183], v[196:199], v[32:35]
	v_mfma_f32_16x16x32_bf16 v[20:23], v[172:175], v[204:207], v[20:23]
	v_mfma_f32_16x16x32_bf16 v[16:19], v[180:183], v[204:207], v[16:19]
	v_mfma_f32_16x16x32_bf16 v[4:7], v[172:175], v[212:215], v[4:7]
	v_mfma_f32_16x16x32_bf16 v[0:3], v[180:183], v[212:215], v[0:3]
	v_mfma_f32_16x16x32_bf16 v[52:55], v[176:179], v[192:195], v[52:55]
	v_mfma_f32_16x16x32_bf16 v[48:51], v[184:187], v[192:195], v[48:51]
	v_mfma_f32_16x16x32_bf16 v[36:39], v[176:179], v[200:203], v[36:39]
	v_mfma_f32_16x16x32_bf16 v[32:35], v[184:187], v[200:203], v[32:35]
	v_mfma_f32_16x16x32_bf16 v[20:23], v[176:179], v[208:211], v[20:23]
	v_mfma_f32_16x16x32_bf16 v[16:19], v[184:187], v[208:211], v[16:19]
	v_mfma_f32_16x16x32_bf16 v[4:7], v[176:179], v[216:219], v[4:7]
	v_mfma_f32_16x16x32_bf16 v[0:3], v[184:187], v[216:219], v[0:3]
	s_setprio 0
	s_barrier
	s_add_i32 s55, s55, 2
	s_add_u32 s36, s36, 0x1000
	s_addc_u32 s37, s37, 0
	s_add_u32 s53, s53, 0x100
	s_addc_u32 s54, s54, 0
	s_cmp_gt_u32 s55, 29
	s_cbranch_scc0 .LBB0_837
	s_and_b64 vcc, exec, s[12:13]
	s_cbranch_vccz .LBB0_840
	s_barrier

; #define PG8_STAGE(bufoff, gbase, voff) do { _Pragma("unroll") for (int _i = 0; _i < 2; ++_i) \
;         __builtin_amdgcn_global_load_lds((const unsigned*)((const char*)(gbase) + (voff)[_i]), (LAS unsigned*)(lds + (bufoff) + ldsw + _i * 8192), 16, 0, 0); } while (0)
; #define PG8_LDA(dst, b, h) do { _Pragma("unroll") for (int m = 0; m < 4; ++m) _Pragma("unroll") for (int k = 0; k < 2; ++k) dst[m][k] = *(const LAS bf16x8*)(lds + PG8_SA(b, h) + aoff + m * 2048 + k * 1024); } while (0)
; #define PG8_LDB(dst, b, h) do { _Pragma("unroll") for (int n = 0; n < 2; ++n) _Pragma("unroll") for (int k = 0; k < 2; ++k) dst[n][k] = *(const LAS bf16x8*)(lds + PG8_SB(b, h) + boff + n * 2048 + k * 1024); } while (0)
; #define PG8_MMA(ai, bj, At, Bt) do { __builtin_amdgcn_s_setprio(1); _Pragma("unroll") for (int m = 0; m < 4; ++m) _Pragma("unroll") for (int n = 0; n < 2; ++n) _Pragma("unroll") for (int k = 0; k < 2; ++k) \
;         acc[ai][bj][m][n] = __builtin_amdgcn_mfma_f32_16x16x32_bf16(Bt[n][k], At[m][k], acc[ai][bj][m][n], 0, 0, 0); __builtin_amdgcn_s_setprio(0); } while (0)
; #define PG8_WAIT_V(n) asm volatile("s_waitcnt vmcnt(" #n ")" ::: "memory")
; #define PG8_WAIT_L(n) asm volatile("s_waitcnt lgkmcnt(" #n ")" ::: "memory")
; #define PG8_BAR __builtin_amdgcn_s_barrier()
; #define PG8_SCHED __builtin_amdgcn_sched_barrier(0)
; template <class Epi, class Sched>
; __device__ __forceinline__ void gemm_phase(LAS unsigned char* lds, const Gemm g, const Sched& S, const Epi& E) {
;     ...
;             const bool last = (t == nt - 2);
;             const char* a1 = cA + (size_t)(t + 1) * kstep;
;             const char* a2 = last ? nA : cA + (size_t)(t + 2) * kstep; const char* b2 = last ? nB : cB + (size_t)(t + 2) * kstep;
;             const char* a3 = a2 + kstep; const char* b3 = b2 + kstep;
;             PG8_LDB(B0, 0, 0); PG8_LDB(B1, 0, 1); PG8_SCHED; PG8_LDA(At, 0, 0); PG8_STAGE(PG8_SA(1, 1), a1 + hstepA, voffA);
;             PG8_WAIT_V(8); PG8_WAIT_L(0); PG8_BAR; PG8_MMA(0, 0, At, B0); PG8_MMA(0, 1, At, B1); PG8_BAR; PG8_SCHED;
;             PG8_LDA(At, 0, 1); PG8_STAGE(PG8_SB(0, 0), b2, voffB); PG8_STAGE(PG8_SB(0, 1), b2 + hstepB, voffB); PG8_STAGE(PG8_SA(0, 0), a2, voffA);
.Ledge_p8:
.LBB0_917:
	ds_read_b128 v[128:131], v208
	ds_read_b128 v[132:135], v208 offset:1024
	ds_read_b128 v[136:139], v208 offset:2048
	ds_read_b128 v[140:143], v208 offset:3072
	ds_read_b128 v[144:147], v209
	ds_read_b128 v[148:151], v209 offset:1024
	ds_read_b128 v[172:175], v209 offset:2048
	ds_read_b128 v[176:179], v209 offset:3072
	s_add_i32 s55, s47, 2
	s_add_u32 s57, s8, 0xffe00800
	s_addc_u32 s59, s9, -1
	s_cmp_eq_u32 s35, s47
	s_cselect_b32 s71, s2, s59
	s_cselect_b32 s70, s5, s57
	s_cselect_b32 s67, s19, s46
	s_cselect_b32 s66, s34, s41
	v_lshl_add_u64 v[216:217], s[8:9], 0, v[168:169]
	s_add_i32 m0, s17, 0xc000
	ds_read_b128 v[180:183], v210
	ds_read_b128 v[184:187], v210 offset:1024
	ds_read_b128 v[188:191], v210 offset:2048
	ds_read_b128 v[192:195], v210 offset:3072
	ds_read_b128 v[196:199], v210 offset:4096
	ds_read_b128 v[200:203], v210 offset:5120
	ds_read_b128 v[204:207], v210 offset:6144
	ds_read_b128 v[212:215], v210 offset:7168
	global_load_lds_dwordx4 v[216:217], off
	v_lshl_add_u64 v[216:217], s[8:9], 0, v[170:171]
	s_add_i32 m0, s17, 0xe000
	s_nop 0
	global_load_lds_dwordx4 v[216:217], off
	s_waitcnt vmcnt(8)
	s_waitcnt lgkmcnt(0)
	s_barrier
	s_setprio 1
	s_waitcnt lgkmcnt(0)
	v_mfma_f32_16x16x32_bf16 v[124:127], v[128:131], v[180:183], v[124:127]
	v_mfma_f32_16x16x32_bf16 v[120:123], v[136:139], v[180:183], v[120:123]
	v_mfma_f32_16x16x32_bf16 v[116:119], v[128:131], v[188:191], v[116:119]
	v_mfma_f32_16x16x32_bf16 v[112:115], v[136:139], v[188:191], v[112:115]
	v_mfma_f32_16x16x32_bf16 v[104:107], v[128:131], v[196:199], v[104:107]
	v_mfma_f32_16x16x32_bf16 v[96:99], v[136:139], v[196:199], v[96:99]
	v_mfma_f32_16x16x32_bf16 v[88:91], v[128:131], v[204:207], v[88:91]
	v_mfma_f32_16x16x32_bf16 v[80:83], v[136:139], v[204:207], v[80:83]
	v_mfma_f32_16x16x32_bf16 v[124:127], v[132:135], v[184:187], v[124:127]
	v_mfma_f32_16x16x32_bf16 v[120:123], v[140:143], v[184:187], v[120:123]
	v_mfma_f32_16x16x32_bf16 v[116:119], v[132:135], v[192:195], v[116:119]
	v_mfma_f32_16x16x32_bf16 v[112:115], v[140:143], v[192:195], v[112:115]
	v_mfma_f32_16x16x32_bf16 v[104:107], v[132:135], v[200:203], v[104:107]
	v_mfma_f32_16x16x32_bf16 v[96:99], v[140:143], v[200:203], v[96:99]
	v_mfma_f32_16x16x32_bf16 v[88:91], v[132:135], v[212:215], v[88:91]
	v_mfma_f32_16x16x32_bf16 v[80:83], v[140:143], v[212:215], v[80:83]
	v_mfma_f32_16x16x32_bf16 v[108:111], v[144:147], v[180:183], v[108:111]
	v_mfma_f32_16x16x32_bf16 v[100:103], v[172:175], v[180:183], v[100:103]
	v_mfma_f32_16x16x32_bf16 v[92:95], v[144:147], v[188:191], v[92:95]
	v_mfma_f32_16x16x32_bf16 v[84:87], v[172:175], v[188:191], v[84:87]
	v_mfma_f32_16x16x32_bf16 v[76:79], v[144:147], v[196:199], v[76:79]
	v_mfma_f32_16x16x32_bf16 v[72:75], v[172:175], v[196:199], v[72:75]
	v_mfma_f32_16x16x32_bf16 v[68:71], v[144:147], v[204:207], v[68:71]
	v_mfma_f32_16x16x32_bf16 v[64:67], v[172:175], v[204:207], v[64:67]
	v_mfma_f32_16x16x32_bf16 v[108:111], v[148:151], v[184:187], v[108:111]
	v_mfma_f32_16x16x32_bf16 v[100:103], v[176:179], v[184:187], v[100:103]
	v_mfma_f32_16x16x32_bf16 v[92:95], v[148:151], v[192:195], v[92:95]
	v_mfma_f32_16x16x32_bf16 v[84:87], v[176:179], v[192:195], v[84:87]
	v_mfma_f32_16x16x32_bf16 v[76:79], v[148:151], v[200:203], v[76:79]
	v_mfma_f32_16x16x32_bf16 v[72:75], v[176:179], v[200:203], v[72:75]
	v_mfma_f32_16x16x32_bf16 v[68:71], v[148:151], v[212:215], v[68:71]
	v_mfma_f32_16x16x32_bf16 v[64:67], v[176:179], v[212:215], v[64:67]
	s_setprio 0
	s_barrier
	s_add_i32 s47, s81, s39
	v_lshl_add_u64 v[216:217], s[66:67], 0, v[156:157]
	s_mov_b32 m0, s47
	ds_read_b128 v[180:183], v210 offset:16384
	ds_read_b128 v[184:187], v210 offset:17408
	ds_read_b128 v[188:191], v210 offset:18432
	ds_read_b128 v[192:195], v210 offset:19456
	ds_read_b128 v[196:199], v210 offset:20480
	ds_read_b128 v[200:203], v210 offset:21504
	ds_read_b128 v[204:207], v210 offset:22528
	ds_read_b128 v[212:215], v210 offset:23552
	global_load_lds_dwordx4 v[216:217], off
	s_add_i32 m0, s47, 0x2000
	s_add_u32 s90, s66, 0x200000
	v_lshl_add_u64 v[218:219], s[66:67], 0, v[160:161]
	s_addc_u32 s91, s67, 0
	s_add_i32 s47, s82, s39
	global_load_lds_dwordx4 v[218:219], off
	v_lshl_add_u64 v[220:221], s[90:91], 0, v[156:157]
	s_mov_b32 m0, s47
	v_lshl_add_u64 v[222:223], s[70:71], 0, v[158:159]
	global_load_lds_dwordx4 v[220:221], off
	v_lshl_add_u64 v[220:221], s[90:91], 0, v[160:161]
	s_add_i32 m0, s47, 0x2000
	s_nop 0
	global_load_lds_dwordx4 v[220:221], off
	v_lshl_add_u64 v[220:221], s[70:71], 0, v[154:155]
	s_mov_b32 m0, s17
	s_nop 0
	global_load_lds_dwordx4 v[220:221], off
	s_mov_b32 m0, s72
	s_nop 0
	global_load_lds_dwordx4 v[222:223], off
	s_waitcnt vmcnt(8)
	s_waitcnt lgkmcnt(0)
	s_barrier
; #define PG8_STAGE(bufoff, gbase, voff) do { _Pragma("unroll") for (int _i = 0; _i < 2; ++_i) \
;         __builtin_amdgcn_global_load_lds((const unsigned*)((const char*)(gbase) + (voff)[_i]), (LAS unsigned*)(lds + (bufoff) + ldsw + _i * 8192), 16, 0, 0); } while (0)
; #define PG8_LDA(dst, b, h) do { _Pragma("unroll") for (int m = 0; m < 4; ++m) _Pragma("unroll") for (int k = 0; k < 2; ++k) dst[m][k] = *(const LAS bf16x8*)(lds + PG8_SA(b, h) + aoff + m * 2048 + k * 1024); } while (0)
; #define PG8_LDB(dst, b, h) do { _Pragma("unroll") for (int n = 0; n < 2; ++n) _Pragma("unroll") for (int k = 0; k < 2; ++k) dst[n][k] = *(const LAS bf16x8*)(lds + PG8_SB(b, h) + boff + n * 2048 + k * 1024); } while (0)
; #define PG8_MMA(ai, bj, At, Bt) do { __builtin_amdgcn_s_setprio(1); _Pragma("unroll") for (int m = 0; m < 4; ++m) _Pragma("unroll") for (int n = 0; n < 2; ++n) _Pragma("unroll") for (int k = 0; k < 2; ++k) \
;         acc[ai][bj][m][n] = __builtin_amdgcn_mfma_f32_16x16x32_bf16(Bt[n][k], At[m][k], acc[ai][bj][m][n], 0, 0, 0); __builtin_amdgcn_s_setprio(0); } while (0)
; #define PG8_WAIT_V(n) asm volatile("s_waitcnt vmcnt(" #n ")" ::: "memory")
; #define PG8_WAIT_L(n) asm volatile("s_waitcnt lgkmcnt(" #n ")" ::: "memory")
; #define PG8_BAR __builtin_amdgcn_s_barrier()
; #define PG8_SCHED __builtin_amdgcn_sched_barrier(0)
; template <class Epi, class Sched>
; __device__ __forceinline__ void gemm_phase(LAS unsigned char* lds, const Gemm g, const Sched& S, const Epi& E) {
;     ...
;             PG8_WAIT_V(8); PG8_WAIT_L(0); PG8_BAR; PG8_MMA(1, 0, At, B0); PG8_MMA(1, 1, At, B1); PG8_BAR; PG8_SCHED;
;             PG8_LDB(B0, 1, 0); PG8_LDB(B1, 1, 1); PG8_SCHED; PG8_LDA(At, 1, 0); PG8_STAGE(PG8_SA(0, 1), a2 + hstepA, voffA);
;             PG8_WAIT_V(8); PG8_WAIT_L(0); PG8_BAR; PG8_MMA(0, 0, At, B0); PG8_MMA(0, 1, At, B1); PG8_BAR; PG8_SCHED;
	s_setprio 1
	s_waitcnt lgkmcnt(0)
	v_mfma_f32_16x16x32_bf16 v[60:63], v[128:131], v[180:183], v[60:63]
	v_mfma_f32_16x16x32_bf16 v[56:59], v[136:139], v[180:183], v[56:59]
	v_mfma_f32_16x16x32_bf16 v[52:55], v[128:131], v[188:191], v[52:55]
	v_mfma_f32_16x16x32_bf16 v[48:51], v[136:139], v[188:191], v[48:51]
	v_mfma_f32_16x16x32_bf16 v[40:43], v[128:131], v[196:199], v[40:43]
	v_mfma_f32_16x16x32_bf16 v[32:35], v[136:139], v[196:199], v[32:35]
	v_mfma_f32_16x16x32_bf16 v[24:27], v[128:131], v[204:207], v[24:27]
	v_mfma_f32_16x16x32_bf16 v[16:19], v[136:139], v[204:207], v[16:19]
	v_mfma_f32_16x16x32_bf16 v[60:63], v[132:135], v[184:187], v[60:63]
	v_mfma_f32_16x16x32_bf16 v[56:59], v[140:143], v[184:187], v[56:59]
	v_mfma_f32_16x16x32_bf16 v[52:55], v[132:135], v[192:195], v[52:55]
	v_mfma_f32_16x16x32_bf16 v[48:51], v[140:143], v[192:195], v[48:51]
	v_mfma_f32_16x16x32_bf16 v[40:43], v[132:135], v[200:203], v[40:43]
	v_mfma_f32_16x16x32_bf16 v[32:35], v[140:143], v[200:203], v[32:35]
	v_mfma_f32_16x16x32_bf16 v[24:27], v[132:135], v[212:215], v[24:27]
	v_mfma_f32_16x16x32_bf16 v[16:19], v[140:143], v[212:215], v[16:19]
	v_mfma_f32_16x16x32_bf16 v[44:47], v[144:147], v[180:183], v[44:47]
	v_mfma_f32_16x16x32_bf16 v[36:39], v[172:175], v[180:183], v[36:39]
	v_mfma_f32_16x16x32_bf16 v[28:31], v[144:147], v[188:191], v[28:31]
	v_mfma_f32_16x16x32_bf16 v[20:23], v[172:175], v[188:191], v[20:23]
	v_mfma_f32_16x16x32_bf16 v[12:15], v[144:147], v[196:199], v[12:15]
	v_mfma_f32_16x16x32_bf16 v[8:11], v[172:175], v[196:199], v[8:11]
	v_mfma_f32_16x16x32_bf16 v[4:7], v[144:147], v[204:207], v[4:7]
	v_mfma_f32_16x16x32_bf16 v[0:3], v[172:175], v[204:207], v[0:3]
	v_mfma_f32_16x16x32_bf16 v[44:47], v[148:151], v[184:187], v[44:47]
	v_mfma_f32_16x16x32_bf16 v[36:39], v[176:179], v[184:187], v[36:39]
	v_mfma_f32_16x16x32_bf16 v[28:31], v[148:151], v[192:195], v[28:31]
	v_mfma_f32_16x16x32_bf16 v[20:23], v[176:179], v[192:195], v[20:23]
	v_mfma_f32_16x16x32_bf16 v[12:15], v[148:151], v[200:203], v[12:15]
	v_mfma_f32_16x16x32_bf16 v[8:11], v[176:179], v[200:203], v[8:11]
	v_mfma_f32_16x16x32_bf16 v[4:7], v[148:151], v[212:215], v[4:7]
	v_mfma_f32_16x16x32_bf16 v[0:3], v[176:179], v[212:215], v[0:3]
	s_setprio 0
	s_barrier
	s_add_i32 s47, 0, 0x18000
	s_add_i32 s57, 0, 0x1c000
	v_add_u32_e32 v140, s47, v153
	v_add_u32_e32 v176, s57, v153
	ds_read_b128 v[128:131], v140
	ds_read_b128 v[132:135], v140 offset:1024
	ds_read_b128 v[136:139], v140 offset:2048
	ds_read_b128 v[140:143], v140 offset:3072
	ds_read_b128 v[144:147], v176
	ds_read_b128 v[148:151], v176 offset:1024
	ds_read_b128 v[172:175], v176 offset:2048
	ds_read_b128 v[176:179], v176 offset:3072
	s_add_u32 s70, s70, 0x200000
	s_addc_u32 s71, s71, 0
	s_mov_b32 m0, s73
	v_lshl_add_u64 v[224:225], s[70:71], 0, v[154:155]
	ds_read_b128 v[180:183], v210 offset:32768
	ds_read_b128 v[184:187], v210 offset:33792
	ds_read_b128 v[188:191], v210 offset:34816
	ds_read_b128 v[192:195], v210 offset:35840
	ds_read_b128 v[196:199], v210 offset:36864
	ds_read_b128 v[200:203], v210 offset:37888
	ds_read_b128 v[204:207], v210 offset:38912
	ds_read_b128 v[212:215], v210 offset:39936
	global_load_lds_dwordx4 v[224:225], off
	v_lshl_add_u64 v[224:225], s[70:71], 0, v[158:159]
	s_mov_b32 m0, s76
	s_nop 0
	global_load_lds_dwordx4 v[224:225], off
	s_waitcnt vmcnt(8)
	s_waitcnt lgkmcnt(0)
	s_barrier
	s_setprio 1
	s_waitcnt lgkmcnt(0)
	v_mfma_f32_16x16x32_bf16 v[124:127], v[128:131], v[180:183], v[124:127]
	v_mfma_f32_16x16x32_bf16 v[120:123], v[136:139], v[180:183], v[120:123]
	v_mfma_f32_16x16x32_bf16 v[116:119], v[128:131], v[188:191], v[116:119]
	v_mfma_f32_16x16x32_bf16 v[112:115], v[136:139], v[188:191], v[112:115]
	v_mfma_f32_16x16x32_bf16 v[104:107], v[128:131], v[196:199], v[104:107]
	v_mfma_f32_16x16x32_bf16 v[96:99], v[136:139], v[196:199], v[96:99]
	v_mfma_f32_16x16x32_bf16 v[88:91], v[128:131], v[204:207], v[88:91]
	v_mfma_f32_16x16x32_bf16 v[80:83], v[136:139], v[204:207], v[80:83]
	v_mfma_f32_16x16x32_bf16 v[124:127], v[132:135], v[184:187], v[124:127]
	v_mfma_f32_16x16x32_bf16 v[120:123], v[140:143], v[184:187], v[120:123]
	v_mfma_f32_16x16x32_bf16 v[116:119], v[132:135], v[192:195], v[116:119]
	v_mfma_f32_16x16x32_bf16 v[112:115], v[140:143], v[192:195], v[112:115]
	v_mfma_f32_16x16x32_bf16 v[104:107], v[132:135], v[200:203], v[104:107]
	v_mfma_f32_16x16x32_bf16 v[96:99], v[140:143], v[200:203], v[96:99]
	v_mfma_f32_16x16x32_bf16 v[88:91], v[132:135], v[212:215], v[88:91]
	v_mfma_f32_16x16x32_bf16 v[80:83], v[140:143], v[212:215], v[80:83]
	v_mfma_f32_16x16x32_bf16 v[108:111], v[144:147], v[180:183], v[108:111]
	v_mfma_f32_16x16x32_bf16 v[100:103], v[172:175], v[180:183], v[100:103]
	v_mfma_f32_16x16x32_bf16 v[92:95], v[144:147], v[188:191], v[92:95]
	v_mfma_f32_16x16x32_bf16 v[84:87], v[172:175], v[188:191], v[84:87]
	v_mfma_f32_16x16x32_bf16 v[76:79], v[144:147], v[196:199], v[76:79]
	v_mfma_f32_16x16x32_bf16 v[72:75], v[172:175], v[196:199], v[72:75]
	v_mfma_f32_16x16x32_bf16 v[68:71], v[144:147], v[204:207], v[68:71]
	v_mfma_f32_16x16x32_bf16 v[64:67], v[172:175], v[204:207], v[64:67]
	v_mfma_f32_16x16x32_bf16 v[108:111], v[148:151], v[184:187], v[108:111]
	v_mfma_f32_16x16x32_bf16 v[100:103], v[176:179], v[184:187], v[100:103]
	v_mfma_f32_16x16x32_bf16 v[92:95], v[148:151], v[192:195], v[92:95]
	v_mfma_f32_16x16x32_bf16 v[84:87], v[176:179], v[192:195], v[84:87]
	v_mfma_f32_16x16x32_bf16 v[76:79], v[148:151], v[200:203], v[76:79]
	v_mfma_f32_16x16x32_bf16 v[72:75], v[176:179], v[200:203], v[72:75]
	v_mfma_f32_16x16x32_bf16 v[68:71], v[148:151], v[212:215], v[68:71]
	v_mfma_f32_16x16x32_bf16 v[64:67], v[176:179], v[212:215], v[64:67]
	s_setprio 0
	s_barrier
; #define PG8_STAGE(bufoff, gbase, voff) do { _Pragma("unroll") for (int _i = 0; _i < 2; ++_i) \
;         __builtin_amdgcn_global_load_lds((const unsigned*)((const char*)(gbase) + (voff)[_i]), (LAS unsigned*)(lds + (bufoff) + ldsw + _i * 8192), 16, 0, 0); } while (0)
; #define PG8_LDA(dst, b, h) do { _Pragma("unroll") for (int m = 0; m < 4; ++m) _Pragma("unroll") for (int k = 0; k < 2; ++k) dst[m][k] = *(const LAS bf16x8*)(lds + PG8_SA(b, h) + aoff + m * 2048 + k * 1024); } while (0)
; #define PG8_MMA(ai, bj, At, Bt) do { __builtin_amdgcn_s_setprio(1); _Pragma("unroll") for (int m = 0; m < 4; ++m) _Pragma("unroll") for (int n = 0; n < 2; ++n) _Pragma("unroll") for (int k = 0; k < 2; ++k) \
;         acc[ai][bj][m][n] = __builtin_amdgcn_mfma_f32_16x16x32_bf16(Bt[n][k], At[m][k], acc[ai][bj][m][n], 0, 0, 0); __builtin_amdgcn_s_setprio(0); } while (0)
; #define PG8_WAIT_V(n) asm volatile("s_waitcnt vmcnt(" #n ")" ::: "memory")
; #define PG8_WAIT_L(n) asm volatile("s_waitcnt lgkmcnt(" #n ")" ::: "memory")
; #define PG8_BAR __builtin_amdgcn_s_barrier()
; #define PG8_SCHED __builtin_amdgcn_sched_barrier(0)
; template <class Epi, class Sched>
; __device__ __forceinline__ void gemm_phase(LAS unsigned char* lds, const Gemm g, const Sched& S, const Epi& E) {
;     ...
;             PG8_LDA(At, 1, 1); PG8_STAGE(PG8_SB(1, 0), b3, voffB); PG8_STAGE(PG8_SB(1, 1), b3 + hstepB, voffB); PG8_STAGE(PG8_SA(1, 0), a3, voffA);
;             PG8_WAIT_V(8); PG8_WAIT_L(0); PG8_BAR; PG8_MMA(1, 0, At, B0); PG8_MMA(1, 1, At, B1); PG8_BAR; PG8_SCHED;
;         }
;         if (wr == 0) PG8_BAR;
	s_add_i32 s47, s47, s39
	v_lshl_add_u64 v[216:217], v[216:217], 0, s[24:25]
	s_mov_b32 m0, s47
	ds_read_b128 v[180:183], v210 offset:49152
	ds_read_b128 v[184:187], v210 offset:50176
	ds_read_b128 v[188:191], v210 offset:51200
	ds_read_b128 v[192:195], v210 offset:52224
	ds_read_b128 v[196:199], v210 offset:53248
	ds_read_b128 v[200:203], v210 offset:54272
	ds_read_b128 v[204:207], v210 offset:55296
	ds_read_b128 v[212:215], v210 offset:56320
	global_load_lds_dwordx4 v[216:217], off
	s_add_i32 m0, s47, 0x2000
	s_add_u32 s66, s66, 0x200080
	v_lshl_add_u64 v[216:217], v[218:219], 0, s[24:25]
	s_addc_u32 s67, s67, 0
	s_add_i32 s47, s57, s39
	global_load_lds_dwordx4 v[216:217], off
	v_lshl_add_u64 v[216:217], s[66:67], 0, v[156:157]
	s_mov_b32 m0, s47
	s_nop 0
	global_load_lds_dwordx4 v[216:217], off
	v_lshl_add_u64 v[216:217], s[66:67], 0, v[160:161]
	s_add_i32 m0, s47, 0x2000
	s_nop 0
	global_load_lds_dwordx4 v[216:217], off
	v_lshl_add_u64 v[216:217], v[220:221], 0, s[98:99]
	s_mov_b32 m0, s79
	s_nop 0
	global_load_lds_dwordx4 v[216:217], off
	v_lshl_add_u64 v[216:217], v[222:223], 0, s[98:99]
	s_mov_b32 m0, s80
	s_nop 0
	global_load_lds_dwordx4 v[216:217], off
	s_waitcnt vmcnt(8)
	s_waitcnt lgkmcnt(0)
	s_barrier
	s_setprio 1
	s_waitcnt lgkmcnt(0)
	v_mfma_f32_16x16x32_bf16 v[60:63], v[128:131], v[180:183], v[60:63]
	v_mfma_f32_16x16x32_bf16 v[56:59], v[136:139], v[180:183], v[56:59]
	v_mfma_f32_16x16x32_bf16 v[52:55], v[128:131], v[188:191], v[52:55]
	v_mfma_f32_16x16x32_bf16 v[48:51], v[136:139], v[188:191], v[48:51]
	v_mfma_f32_16x16x32_bf16 v[40:43], v[128:131], v[196:199], v[40:43]
	v_mfma_f32_16x16x32_bf16 v[32:35], v[136:139], v[196:199], v[32:35]
	v_mfma_f32_16x16x32_bf16 v[24:27], v[128:131], v[204:207], v[24:27]
	v_mfma_f32_16x16x32_bf16 v[16:19], v[136:139], v[204:207], v[16:19]
	v_mfma_f32_16x16x32_bf16 v[60:63], v[132:135], v[184:187], v[60:63]
	v_mfma_f32_16x16x32_bf16 v[56:59], v[140:143], v[184:187], v[56:59]
	v_mfma_f32_16x16x32_bf16 v[52:55], v[132:135], v[192:195], v[52:55]
	v_mfma_f32_16x16x32_bf16 v[48:51], v[140:143], v[192:195], v[48:51]
	v_mfma_f32_16x16x32_bf16 v[40:43], v[132:135], v[200:203], v[40:43]
	v_mfma_f32_16x16x32_bf16 v[32:35], v[140:143], v[200:203], v[32:35]
	v_mfma_f32_16x16x32_bf16 v[24:27], v[132:135], v[212:215], v[24:27]
	v_mfma_f32_16x16x32_bf16 v[16:19], v[140:143], v[212:215], v[16:19]
	v_mfma_f32_16x16x32_bf16 v[44:47], v[144:147], v[180:183], v[44:47]
	v_mfma_f32_16x16x32_bf16 v[36:39], v[172:175], v[180:183], v[36:39]
	v_mfma_f32_16x16x32_bf16 v[28:31], v[144:147], v[188:191], v[28:31]
	v_mfma_f32_16x16x32_bf16 v[20:23], v[172:175], v[188:191], v[20:23]
	v_mfma_f32_16x16x32_bf16 v[12:15], v[144:147], v[196:199], v[12:15]
	v_mfma_f32_16x16x32_bf16 v[8:11], v[172:175], v[196:199], v[8:11]
	v_mfma_f32_16x16x32_bf16 v[4:7], v[144:147], v[204:207], v[4:7]
	v_mfma_f32_16x16x32_bf16 v[0:3], v[172:175], v[204:207], v[0:3]
	v_mfma_f32_16x16x32_bf16 v[44:47], v[148:151], v[184:187], v[44:47]
	v_mfma_f32_16x16x32_bf16 v[36:39], v[176:179], v[184:187], v[36:39]
	v_mfma_f32_16x16x32_bf16 v[28:31], v[148:151], v[192:195], v[28:31]
	v_mfma_f32_16x16x32_bf16 v[20:23], v[176:179], v[192:195], v[20:23]
	v_mfma_f32_16x16x32_bf16 v[12:15], v[148:151], v[200:203], v[12:15]
	v_mfma_f32_16x16x32_bf16 v[8:11], v[176:179], v[200:203], v[8:11]
	v_mfma_f32_16x16x32_bf16 v[4:7], v[148:151], v[212:215], v[4:7]
	v_mfma_f32_16x16x32_bf16 v[0:3], v[176:179], v[212:215], v[0:3]
	s_setprio 0
	s_barrier
	s_add_u32 s8, s8, 0x1000
	s_addc_u32 s9, s9, 0
	s_add_u32 s41, s41, 0x100
	s_addc_u32 s46, s46, 0
	s_cmp_ge_i32 s55, s4
	s_mov_b32 s47, s55
	s_cbranch_scc0 .LBB0_917
	s_and_b64 vcc, exec, s[36:37]
	s_cbranch_vccz .LBB0_922
	s_barrier
	s_cmp_lt_i32 s12, 0
	s_mov_b64 s[8:9], -1
	s_cbranch_scc1 .LBB0_923
